# nt policy: P3 stores, X f32 stores and R loads of P2/P6/P8, P9 final loads+stores, PLE stores, P5 gate/merged loads
# speedup vs baseline: 1.0025x; 1.0025x over previous
; __device__ __forceinline__ unsigned cvtpk(float lo, float hi) { f32x2_t v = {lo, hi}; bf16x2_t b = __builtin_convertvector(v, bf16x2_t); return __builtin_bit_cast(unsigned, b); }
;     __device__ __forceinline__ void operator()(const pg8::f32x4 (&acc)[2][2][4][2], const pg8::Unit& u, int wr, int wc, int fr, int fq) const {
;         const int row0 = u.pm * 256 + wr * 64 + fr, colb = u.pn * 256 + wc * 32 + 8 * fq;
; #pragma unroll
;         for (int ai = 0; ai < 2; ++ai) {
;             pg8::f32x4 rv[4][2][2];
; #pragma unroll
;             for (int m = 0; m < 4; ++m)
; #pragma unroll
;                 for (int bj = 0; bj < 2; ++bj) { const size_t off = (size_t)(row0 + ai * 128 + m * 16) * DM + colb + bj * 128;
;                     rv[m][bj][0] = *(const pg8::f32x4*)(R + off); rv[m][bj][1] = *(const pg8::f32x4*)(R + off + 4); }
; #pragma unroll
;             for (int m = 0; m < 4; ++m) {
;                 const int row = row0 + ai * 128 + m * 16;
;                 float sq = 0.f;
; #pragma unroll
;                 for (int bj = 0; bj < 2; ++bj) {
;                     const size_t off = (size_t)row * DM + colb + bj * 128;
;                     const pg8::f32x4 v0 = rv[m][bj][0] + acc[ai][bj][m][0] * alpha, v1 = rv[m][bj][1] + acc[ai][bj][m][1] * alpha;
;                     *(pg8::f32x4*)(X + off) = v0; *(pg8::f32x4*)(X + off + 4) = v1;
;                     u32x4 w; w[0] = cvtpk(v0[0], v0[1]); w[1] = cvtpk(v0[2], v0[3]); w[2] = cvtpk(v1[0], v1[1]); w[3] = cvtpk(v1[2], v1[3]);
;                     *(u32x4*)(XB + off) = w;
;                     sq += (v0[0] * v0[0] + v0[1] * v0[1]) + (v0[2] * v0[2] + v0[3] * v0[3]) + (v1[0] * v1[0] + v1[1] * v1[1]) + (v1[2] * v1[2] + v1[3] * v1[3]);
;                 }
;                 sq += __shfl_xor(sq, 16); sq += __shfl_xor(sq, 32);
;                 if (fq == 0) atomicAdd(ssout + row, sq);
.LBB0_288:
	v_lshl_add_u32 v194, s44, 8, v205
	v_lshl_or_b32 v192, s45, 8, v207
	v_ashrrev_i32_e32 v193, 31, v192
	v_ashrrev_i32_e32 v195, 31, v194
	v_lshl_add_u64 v[196:197], v[192:193], 2, s[36:37]
	v_lshlrev_b64 v[128:129], 13, v[194:195]
	v_lshl_add_u64 v[128:129], v[196:197], 0, v[128:129]
	global_load_dwordx4 v[214:217], v[128:129], off nt
	global_load_dwordx4 v[222:225], v[128:129], off offset:16 nt
	global_load_dwordx4 v[226:229], v[128:129], off offset:512 nt
	global_load_dwordx4 v[230:233], v[128:129], off offset:528 nt
	v_or_b32_e32 v202, 16, v194
	v_or_b32_e32 v200, 32, v194
	v_or_b32_e32 v198, 48, v194
	v_ashrrev_i32_e32 v203, 31, v202
	v_ashrrev_i32_e32 v201, 31, v200
	v_ashrrev_i32_e32 v199, 31, v198
	v_lshlrev_b64 v[128:129], 13, v[202:203]
	v_lshlrev_b64 v[130:131], 13, v[200:201]
	v_lshlrev_b64 v[132:133], 13, v[198:199]
	v_lshl_add_u64 v[128:129], v[196:197], 0, v[128:129]
	v_lshl_add_u64 v[130:131], v[196:197], 0, v[130:131]
	v_lshl_add_u64 v[132:133], v[196:197], 0, v[132:133]
	global_load_dwordx4 v[168:171], v[128:129], off offset:16 nt
	global_load_dwordx4 v[172:175], v[128:129], off nt
	global_load_dwordx4 v[160:163], v[128:129], off offset:528 nt
	global_load_dwordx4 v[164:167], v[128:129], off offset:512 nt
	global_load_dwordx4 v[152:155], v[130:131], off offset:16 nt
	global_load_dwordx4 v[156:159], v[130:131], off nt
	global_load_dwordx4 v[144:147], v[130:131], off offset:528 nt
	global_load_dwordx4 v[148:151], v[130:131], off offset:512 nt
	global_load_dwordx4 v[136:139], v[132:133], off offset:16 nt
	global_load_dwordx4 v[140:143], v[132:133], off nt
	s_nop 0
	global_load_dwordx4 v[128:131], v[132:133], off offset:528 nt
	s_nop 0
	global_load_dwordx4 v[132:135], v[132:133], off offset:512 nt
	v_and_b32_e32 v213, 64, v211
	v_xor_b32_e32 v212, 16, v211
	v_add_u32_e32 v213, 64, v213
	v_xor_b32_e32 v218, 32, v211
	v_cmp_lt_i32_e32 vcc, v212, v213
	s_waitcnt vmcnt(0)
	v_pk_fma_f32 v[126:127], v[126:127], 0.5, v[216:217] op_sel_hi:[1,0,1]
	v_cndmask_b32_e32 v212, v211, v212, vcc
	v_cmp_lt_i32_e32 vcc, v218, v213
	v_pk_fma_f32 v[124:125], v[124:125], 0.5, v[214:215] op_sel_hi:[1,0,1]
	v_pk_fma_f32 v[118:119], v[118:119], 0.5, v[228:229] op_sel_hi:[1,0,1]
	v_cndmask_b32_e32 v221, v211, v218, vcc
	v_lshlrev_b64 v[218:219], 11, v[194:195]
	v_lshl_add_u64 v[218:219], v[218:219], 0, v[192:193]
	v_lshl_add_u64 v[234:235], v[218:219], 2, s[62:63]
	v_pk_fma_f32 v[116:117], v[116:117], 0.5, v[226:227] op_sel_hi:[1,0,1]
	v_lshlrev_b32_e32 v213, 2, v212
	v_lshlrev_b32_e32 v212, 2, v221
	v_pk_fma_f32 v[122:123], v[122:123], 0.5, v[224:225] op_sel_hi:[1,0,1]
	v_pk_fma_f32 v[120:121], v[120:121], 0.5, v[222:223] op_sel_hi:[1,0,1]
	v_pk_fma_f32 v[112:113], v[112:113], 0.5, v[230:231] op_sel_hi:[1,0,1]
	global_store_dwordx4 v[234:235], v[124:127], off nt
	global_store_dwordx4 v[234:235], v[120:123], off offset:16 nt
	v_cvt_pk_bf16_f32 v214, v124, v125
	v_cvt_pk_bf16_f32 v215, v126, v127
	v_mul_f32_e32 v125, v125, v125
	v_mul_f32_e32 v127, v127, v127
	v_mul_f32_e32 v221, v117, v117
	v_mul_f32_e32 v222, v119, v119
	v_pk_fma_f32 v[114:115], v[114:115], 0.5, v[232:233] op_sel_hi:[1,0,1]
	v_cvt_pk_bf16_f32 v216, v120, v121
	v_cvt_pk_bf16_f32 v217, v122, v123
	v_mul_f32_e32 v121, v121, v121
	v_mul_f32_e32 v123, v123, v123
	v_mul_f32_e32 v223, v113, v113
	v_fmac_f32_e32 v125, v124, v124
	v_fmac_f32_e32 v127, v126, v126
	v_fmac_f32_e32 v221, v116, v116
	v_fmac_f32_e32 v222, v118, v118
	v_mul_f32_e32 v224, v115, v115
	v_fmac_f32_e32 v121, v120, v120
	v_fmac_f32_e32 v123, v122, v122
	v_fmac_f32_e32 v223, v112, v112
	v_add_f32_e32 v120, v125, v127
	v_add_f32_e32 v122, v221, v222
	v_fmac_f32_e32 v224, v114, v114
	v_add_f32_e32 v120, v121, v120
	v_add_f32_e32 v121, v223, v122
	v_add_f32_e32 v120, v123, v120
	v_add_f32_e32 v121, v224, v121
	v_add_f32_e32 v120, v120, v121
	ds_bpermute_b32 v121, v213, v120
	v_lshlrev_b64 v[218:219], 1, v[218:219]
	v_lshl_add_u64 v[236:237], s[80:81], 0, v[218:219]
	global_store_dwordx4 v[236:237], v[214:217], off
	global_store_dwordx4 v[234:235], v[116:119], off offset:512 nt
	global_store_dwordx4 v[234:235], v[112:115], off offset:528 nt
	v_or_b32_e32 v218, 0x100, v218
	v_cvt_pk_bf16_f32 v116, v116, v117
	v_cvt_pk_bf16_f32 v117, v118, v119
	v_cvt_pk_bf16_f32 v118, v112, v113
	s_waitcnt lgkmcnt(0)
	v_add_f32_e32 v112, v120, v121
	ds_bpermute_b32 v113, v212, v112
	v_cvt_pk_bf16_f32 v119, v114, v115
	v_lshl_add_u64 v[114:115], s[80:81], 0, v[218:219]
	global_store_dwordx4 v[114:115], v[116:119], off
	s_and_saveexec_b64 s[20:21], s[2:3]
	s_cbranch_execz .LBB0_290
	v_lshl_add_u64 v[114:115], v[194:195], 2, s[12:13]
	s_waitcnt lgkmcnt(0)
	v_add_f32_e32 v112, v112, v113
	global_atomic_add_f32 v[114:115], v112, off

; __device__ __forceinline__ unsigned cvtpk(float lo, float hi) { f32x2_t v = {lo, hi}; bf16x2_t b = __builtin_convertvector(v, bf16x2_t); return __builtin_bit_cast(unsigned, b); }
;     __device__ __forceinline__ void operator()(const pg8::f32x4 (&acc)[2][2][4][2], const pg8::Unit& u, int wr, int wc, int fr, int fq) const {
;     ...
;         for (int ai = 0; ai < 2; ++ai) {
;             pg8::f32x4 rv[4][2][2];
; #pragma unroll
;             for (int m = 0; m < 4; ++m)
; #pragma unroll
;                 for (int bj = 0; bj < 2; ++bj) { const size_t off = (size_t)(row0 + ai * 128 + m * 16) * DM + colb + bj * 128;
;                     rv[m][bj][0] = *(const pg8::f32x4*)(R + off); rv[m][bj][1] = *(const pg8::f32x4*)(R + off + 4); }
; #pragma unroll
;             for (int m = 0; m < 4; ++m) {
;                 const int row = row0 + ai * 128 + m * 16;
;                 float sq = 0.f;
; #pragma unroll
;                 for (int bj = 0; bj < 2; ++bj) {
;                     const size_t off = (size_t)row * DM + colb + bj * 128;
;                     const pg8::f32x4 v0 = rv[m][bj][0] + acc[ai][bj][m][0] * alpha, v1 = rv[m][bj][1] + acc[ai][bj][m][1] * alpha;
;                     *(pg8::f32x4*)(X + off) = v0; *(pg8::f32x4*)(X + off + 4) = v1;
;                     u32x4 w; w[0] = cvtpk(v0[0], v0[1]); w[1] = cvtpk(v0[2], v0[3]); w[2] = cvtpk(v1[0], v1[1]); w[3] = cvtpk(v1[2], v1[3]);
;                     *(u32x4*)(XB + off) = w;
;                     sq += (v0[0] * v0[0] + v0[1] * v0[1]) + (v0[2] * v0[2] + v0[3] * v0[3]) + (v1[0] * v1[0] + v1[1] * v1[1]) + (v1[2] * v1[2] + v1[3] * v1[3]);
;                 }
;                 sq += __shfl_xor(sq, 16); sq += __shfl_xor(sq, 32);
;                 if (fq == 0) atomicAdd(ssout + row, sq);
.LBB0_296:
	s_or_b64 exec, exec, s[20:21]
	v_add_u32_e32 v118, 0x80, v194
	v_ashrrev_i32_e32 v119, 31, v118
	s_waitcnt lgkmcnt(0)
	v_lshlrev_b64 v[64:65], 13, v[118:119]
	v_lshl_add_u64 v[64:65], v[196:197], 0, v[64:65]
	global_load_dwordx4 v[120:123], v[64:65], off nt
	global_load_dwordx4 v[124:127], v[64:65], off offset:16 nt
	global_load_dwordx4 v[128:131], v[64:65], off offset:512 nt
	global_load_dwordx4 v[132:135], v[64:65], off offset:528 nt
	v_add_u32_e32 v116, 0x90, v194
	v_add_u32_e32 v114, 0xa0, v194
	v_add_u32_e32 v112, 0xb0, v194
	v_ashrrev_i32_e32 v117, 31, v116
	v_ashrrev_i32_e32 v115, 31, v114
	v_ashrrev_i32_e32 v113, 31, v112
	v_lshlrev_b64 v[64:65], 13, v[116:117]
	v_lshlrev_b64 v[66:67], 13, v[114:115]
	v_lshlrev_b64 v[68:69], 13, v[112:113]
	v_lshl_add_u64 v[64:65], v[196:197], 0, v[64:65]
	v_lshl_add_u64 v[66:67], v[196:197], 0, v[66:67]
	v_lshl_add_u64 v[68:69], v[196:197], 0, v[68:69]
	global_load_dwordx4 v[104:107], v[64:65], off offset:16 nt
	global_load_dwordx4 v[108:111], v[64:65], off nt
	global_load_dwordx4 v[96:99], v[64:65], off offset:528 nt
	global_load_dwordx4 v[100:103], v[64:65], off offset:512 nt
	global_load_dwordx4 v[88:91], v[66:67], off offset:16 nt
	global_load_dwordx4 v[92:95], v[66:67], off nt
	global_load_dwordx4 v[80:83], v[66:67], off offset:528 nt
	global_load_dwordx4 v[84:87], v[66:67], off offset:512 nt
	global_load_dwordx4 v[72:75], v[68:69], off offset:16 nt
	global_load_dwordx4 v[76:79], v[68:69], off nt
	s_nop 0
	global_load_dwordx4 v[64:67], v[68:69], off offset:528 nt
	s_nop 0
	global_load_dwordx4 v[68:71], v[68:69], off offset:512 nt
	v_lshlrev_b64 v[136:137], 11, v[118:119]
	v_lshl_add_u64 v[136:137], v[136:137], 0, v[192:193]
	v_lshl_add_u64 v[138:139], v[136:137], 2, s[62:63]
	v_lshlrev_b64 v[136:137], 1, v[136:137]
	v_lshl_add_u64 v[140:141], s[80:81], 0, v[136:137]
	v_or_b32_e32 v136, 0x100, v136
	s_waitcnt vmcnt(15)
	v_pk_fma_f32 v[62:63], v[62:63], 0.5, v[122:123] op_sel_hi:[1,0,1]
	v_pk_fma_f32 v[60:61], v[60:61], 0.5, v[120:121] op_sel_hi:[1,0,1]
	s_waitcnt vmcnt(13)
	v_pk_fma_f32 v[54:55], v[54:55], 0.5, v[130:131] op_sel_hi:[1,0,1]
	v_pk_fma_f32 v[52:53], v[52:53], 0.5, v[128:129] op_sel_hi:[1,0,1]
	v_pk_fma_f32 v[58:59], v[58:59], 0.5, v[126:127] op_sel_hi:[1,0,1]
	v_pk_fma_f32 v[56:57], v[56:57], 0.5, v[124:125] op_sel_hi:[1,0,1]
	s_waitcnt vmcnt(12)
	v_pk_fma_f32 v[48:49], v[48:49], 0.5, v[132:133] op_sel_hi:[1,0,1]
	global_store_dwordx4 v[138:139], v[60:63], off nt
	global_store_dwordx4 v[138:139], v[56:59], off offset:16 nt
	v_cvt_pk_bf16_f32 v120, v60, v61
	v_cvt_pk_bf16_f32 v121, v62, v63
	v_mul_f32_e32 v61, v61, v61
	v_mul_f32_e32 v63, v63, v63
	v_mul_f32_e32 v124, v53, v53
	v_mul_f32_e32 v125, v55, v55
	v_pk_fma_f32 v[50:51], v[50:51], 0.5, v[134:135] op_sel_hi:[1,0,1]
	v_cvt_pk_bf16_f32 v122, v56, v57
	v_cvt_pk_bf16_f32 v123, v58, v59
	v_mul_f32_e32 v57, v57, v57
	v_mul_f32_e32 v59, v59, v59
	v_mul_f32_e32 v126, v49, v49
	v_fmac_f32_e32 v61, v60, v60
	v_fmac_f32_e32 v63, v62, v62
	v_fmac_f32_e32 v124, v52, v52
	v_fmac_f32_e32 v125, v54, v54
	v_mul_f32_e32 v127, v51, v51
	v_fmac_f32_e32 v57, v56, v56
	v_fmac_f32_e32 v59, v58, v58
	v_fmac_f32_e32 v126, v48, v48
	v_add_f32_e32 v56, v61, v63
	v_add_f32_e32 v58, v124, v125
	v_fmac_f32_e32 v127, v50, v50
	v_add_f32_e32 v56, v57, v56
	v_add_f32_e32 v57, v126, v58
	v_add_f32_e32 v56, v59, v56
	v_add_f32_e32 v57, v127, v57
	v_add_f32_e32 v56, v56, v57
	ds_bpermute_b32 v57, v213, v56
	global_store_dwordx4 v[140:141], v[120:123], off
	global_store_dwordx4 v[138:139], v[52:55], off offset:512 nt
	global_store_dwordx4 v[138:139], v[48:51], off offset:528 nt
	s_nop 0
	v_cvt_pk_bf16_f32 v52, v52, v53
	v_cvt_pk_bf16_f32 v53, v54, v55
	v_cvt_pk_bf16_f32 v54, v48, v49
	s_waitcnt lgkmcnt(0)
	v_add_f32_e32 v48, v56, v57
	ds_bpermute_b32 v49, v212, v48
	v_cvt_pk_bf16_f32 v55, v50, v51
	v_lshl_add_u64 v[50:51], s[80:81], 0, v[136:137]
	global_store_dwordx4 v[50:51], v[52:55], off
	s_and_saveexec_b64 s[20:21], s[2:3]
	s_cbranch_execz .LBB0_298
	v_lshl_add_u64 v[50:51], v[118:119], 2, s[12:13]
	s_waitcnt lgkmcnt(0)
	v_add_f32_e32 v48, v48, v49
	global_atomic_add_f32 v[50:51], v48, off

; __device__ __forceinline__ unsigned cvtpk(float lo, float hi) { f32x2_t v = {lo, hi}; bf16x2_t b = __builtin_convertvector(v, bf16x2_t); return __builtin_bit_cast(unsigned, b); }
; __device__ __forceinline__ float bflo(unsigned w) { return __uint_as_float(w << 16); }
; __device__ __forceinline__ float bfhi(unsigned w) { return __uint_as_float(w & 0xffff0000u); }
;     __device__ __forceinline__ void operator()(const pg8::f32x4 (&acc)[2][2][4][2], const pg8::Unit& u, int wr, int wc, int fr, int fq) const {
;         const bool second = u.pm >= TOK / 256;
;         const int pm = second ? u.pm - TOK / 256 : u.pm, pn = second ? u.pn - DM / 256 : u.pn;
;         const bf16* G = second ? GB_ : GA_;
;         const int row0 = pm * 256 + wr * 64 + fr, colb = pn * 256 + wc * 32 + 8 * fq;
; #pragma unroll
;         for (int ai = 0; ai < 2; ++ai) {
;             u32x4 gv[4][2], pv[4][2];
; #pragma unroll
;             for (int m = 0; m < 4; ++m)
; #pragma unroll
;                 for (int bj = 0; bj < 2; ++bj) { const size_t off = (size_t)(row0 + ai * 128 + m * 16) * DM + colb + bj * 128;
;                     gv[m][bj] = *(const u32x4*)(G + off); pv[m][bj] = (u32x4){0u, 0u, 0u, 0u}; if (second) pv[m][bj] = *(const u32x4*)(Mg + off); }
; #pragma unroll
;             for (int m = 0; m < 4; ++m)
; #pragma unroll
;                 for (int bj = 0; bj < 2; ++bj) {
;                     const size_t off = (size_t)(row0 + ai * 128 + m * 16) * DM + colb + bj * 128;
;                     const u32x4 gw = gv[m][bj], pw = pv[m][bj];
;                     pg8::f32x4 v0 = acc[ai][bj][m][0], v1 = acc[ai][bj][m][1];
;                     v0[0] = v0[0] * bflo(gw[0]) + bflo(pw[0]); v0[1] = v0[1] * bfhi(gw[0]) + bfhi(pw[0]); v0[2] = v0[2] * bflo(gw[1]) + bflo(pw[1]); v0[3] = v0[3] * bfhi(gw[1]) + bfhi(pw[1]);
;                     v1[0] = v1[0] * bflo(gw[2]) + bflo(pw[2]); v1[1] = v1[1] * bfhi(gw[2]) + bfhi(pw[2]); v1[2] = v1[2] * bflo(gw[3]) + bflo(pw[3]); v1[3] = v1[3] * bfhi(gw[3]) + bfhi(pw[3]);
;                     u32x4 w; w[0] = cvtpk(v0[0], v0[1]); w[1] = cvtpk(v0[2], v0[3]); w[2] = cvtpk(v1[0], v1[1]); w[3] = cvtpk(v1[2], v1[3]);
;                     *(u32x4*)(Mg + off) = w;
;                 }
.LBB0_887:
	s_lshl_b32 s13, s20, 8
	s_lshl_b32 s26, s22, 8
	s_add_i32 s15, s13, 0xffffc000
	s_add_i32 s27, s26, 0xfffff800
	s_cmp_gt_i32 s20, 63
	s_cselect_b64 s[24:25], -1, 0
	s_and_b64 s[0:1], s[24:25], exec
	s_cselect_b32 s0, s15, s13
	s_cselect_b32 s1, s27, s26
	v_add_u32_e32 v210, s0, v221
	v_or_b32_e32 v208, s1, v223
	v_ashrrev_i32_e32 v211, 31, v210
	v_ashrrev_i32_e32 v209, 31, v208
	v_lshlrev_b64 v[128:129], 11, v[210:211]
	s_cselect_b32 s22, s35, s76
	s_cselect_b32 s23, s36, s50
	v_lshl_add_u64 v[128:129], v[128:129], 0, v[208:209]
	v_lshl_add_u64 v[130:131], v[128:129], 1, s[22:23]
	global_load_dwordx4 v[188:191], v[130:131], off nt
	s_cmp_lt_i32 s20, 64
	v_mov_b32_e32 v168, 0
	v_lshl_add_u64 v[128:129], v[128:129], 1, s[84:85]
	v_mov_b32_e32 v184, 0
	v_mov_b32_e32 v185, 0
	v_mov_b32_e32 v186, 0
	v_mov_b32_e32 v187, 0
	s_cbranch_scc1 .LBB0_889
	global_load_dwordx4 v[184:187], v[128:129], off nt
.LBB0_889:
	global_load_dwordx4 v[180:183], v[130:131], off offset:256 nt
	v_cndmask_b32_e64 v130, 0, 1, s[24:25]
	v_cmp_ne_u32_e64 s[0:1], 1, v130
	s_andn2_b64 vcc, exec, s[24:25]
	v_mov_b32_e32 v169, 0
	v_mov_b32_e32 v170, 0
	v_mov_b32_e32 v171, 0
	s_cbranch_vccnz .LBB0_891
	global_load_dwordx4 v[168:171], v[128:129], off offset:256 nt
.LBB0_891:
	v_or_b32_e32 v216, 16, v210
	v_ashrrev_i32_e32 v217, 31, v216
	v_lshlrev_b64 v[128:129], 11, v[216:217]
	v_lshl_add_u64 v[128:129], v[128:129], 0, v[208:209]
	v_lshl_add_u64 v[130:131], v[128:129], 1, s[22:23]
	global_load_dwordx4 v[176:179], v[130:131], off nt
	v_mov_b32_e32 v152, 0
	s_and_b64 vcc, exec, s[0:1]
	v_lshl_add_u64 v[128:129], v[128:129], 1, s[84:85]
	v_mov_b32_e32 v172, 0
	v_mov_b32_e32 v173, 0
	v_mov_b32_e32 v174, 0
	v_mov_b32_e32 v175, 0
	s_cbranch_vccnz .LBB0_893
	global_load_dwordx4 v[172:175], v[128:129], off nt
.LBB0_893:
	global_load_dwordx4 v[164:167], v[130:131], off offset:256 nt
	s_and_b64 vcc, exec, s[0:1]
	v_mov_b32_e32 v153, 0
	v_mov_b32_e32 v154, 0
	v_mov_b32_e32 v155, 0
	s_cbranch_vccnz .LBB0_895
	global_load_dwordx4 v[152:155], v[128:129], off offset:256 nt
.LBB0_895:
	v_or_b32_e32 v214, 32, v210
	v_ashrrev_i32_e32 v215, 31, v214
	v_lshlrev_b64 v[128:129], 11, v[214:215]
	v_lshl_add_u64 v[128:129], v[128:129], 0, v[208:209]
	v_lshl_add_u64 v[130:131], v[128:129], 1, s[22:23]
	global_load_dwordx4 v[160:163], v[130:131], off nt
	v_mov_b32_e32 v136, 0
	s_and_b64 vcc, exec, s[0:1]
	v_lshl_add_u64 v[128:129], v[128:129], 1, s[84:85]
	v_mov_b32_e32 v156, 0
	v_mov_b32_e32 v157, 0
	v_mov_b32_e32 v158, 0
	v_mov_b32_e32 v159, 0
	s_cbranch_vccnz .LBB0_897
	global_load_dwordx4 v[156:159], v[128:129], off nt
.LBB0_897:
	global_load_dwordx4 v[148:151], v[130:131], off offset:256 nt
	s_and_b64 vcc, exec, s[0:1]
	v_mov_b32_e32 v137, 0
	v_mov_b32_e32 v138, 0
	v_mov_b32_e32 v139, 0
	s_cbranch_vccnz .LBB0_899
	global_load_dwordx4 v[136:139], v[128:129], off offset:256 nt
.LBB0_899:
	v_or_b32_e32 v212, 48, v210
	v_ashrrev_i32_e32 v213, 31, v212
	v_lshlrev_b64 v[128:129], 11, v[212:213]
	v_lshl_add_u64 v[132:133], v[128:129], 0, v[208:209]
	v_lshl_add_u64 v[130:131], v[132:133], 1, s[22:23]
	global_load_dwordx4 v[144:147], v[130:131], off nt
	v_mov_b32_e32 v128, 0
	s_and_b64 vcc, exec, s[0:1]
	v_lshl_add_u64 v[218:219], v[132:133], 1, s[84:85]
	v_mov_b32_e32 v140, 0
	v_mov_b32_e32 v141, 0
	v_mov_b32_e32 v142, 0
	v_mov_b32_e32 v143, 0
	s_cbranch_vccnz .LBB0_901
	global_load_dwordx4 v[140:143], v[218:219], off nt
.LBB0_901:
	global_load_dwordx4 v[132:135], v[130:131], off offset:256 nt
	s_and_b64 vcc, exec, s[0:1]
	v_mov_b32_e32 v129, 0
	v_mov_b32_e32 v130, 0
	v_mov_b32_e32 v131, 0
	s_cbranch_vccnz .LBB0_903
	global_load_dwordx4 v[128:131], v[218:219], off offset:256 nt
.LBB0_903:
	s_waitcnt vmcnt(0)
	v_lshlrev_b32_e32 v228, 16, v188
	v_and_b32_e32 v229, 0xffff0000, v188
	v_lshlrev_b32_e32 v230, 16, v184
	v_and_b32_e32 v231, 0xffff0000, v184
	v_lshlrev_b32_e32 v188, 16, v189
	v_and_b32_e32 v189, 0xffff0000, v189
	v_lshlrev_b32_e32 v184, 16, v185
	v_and_b32_e32 v185, 0xffff0000, v185
	v_pk_fma_f32 v[126:127], v[126:127], v[188:189], v[184:185]
	v_lshlrev_b32_e32 v184, 16, v190
	v_and_b32_e32 v185, 0xffff0000, v190
	v_lshlrev_b32_e32 v188, 16, v186
	v_and_b32_e32 v189, 0xffff0000, v186
	v_lshlrev_b64 v[218:219], 12, v[210:211]
	v_pk_fma_f32 v[124:125], v[124:125], v[228:229], v[230:231]
	v_pk_fma_f32 v[184:185], v[120:121], v[184:185], v[188:189]
	v_lshlrev_b32_e32 v120, 16, v191
	v_and_b32_e32 v121, 0xffff0000, v191
	v_lshlrev_b32_e32 v186, 16, v187
	v_and_b32_e32 v187, 0xffff0000, v187
	v_pk_fma_f32 v[186:187], v[122:123], v[120:121], v[186:187]
	v_cvt_pk_bf16_f32 v120, v124, v125
	v_cvt_pk_bf16_f32 v122, v184, v185
	v_lshl_add_u64 v[124:125], s[84:85], 0, v[218:219]
	v_lshlrev_b64 v[184:185], 1, v[208:209]
	v_cvt_pk_bf16_f32 v121, v126, v127
	v_cvt_pk_bf16_f32 v123, v186, v187
	v_lshl_add_u64 v[124:125], v[124:125], 0, v[184:185]
	global_store_dwordx4 v[124:125], v[120:123], off
	s_and_b64 vcc, exec, s[0:1]
	s_nop 0
	v_lshlrev_b32_e32 v120, 16, v180
	v_and_b32_e32 v121, 0xffff0000, v180
	v_lshlrev_b32_e32 v122, 16, v168
	v_and_b32_e32 v123, 0xffff0000, v168
	v_pk_fma_f32 v[116:117], v[116:117], v[120:121], v[122:123]
	v_lshlrev_b32_e32 v120, 16, v181
	v_and_b32_e32 v121, 0xffff0000, v181
	v_lshlrev_b32_e32 v122, 16, v169
	v_and_b32_e32 v123, 0xffff0000, v169
	v_pk_fma_f32 v[118:119], v[118:119], v[120:121], v[122:123]
	v_lshlrev_b32_e32 v120, 16, v182
	v_and_b32_e32 v121, 0xffff0000, v182
	v_lshlrev_b32_e32 v122, 16, v170
	v_and_b32_e32 v123, 0xffff0000, v170
	v_pk_fma_f32 v[120:121], v[112:113], v[120:121], v[122:123]
	v_lshlrev_b32_e32 v112, 16, v183
	v_and_b32_e32 v113, 0xffff0000, v183
; __device__ __forceinline__ unsigned cvtpk(float lo, float hi) { f32x2_t v = {lo, hi}; bf16x2_t b = __builtin_convertvector(v, bf16x2_t); return __builtin_bit_cast(unsigned, b); }
; __device__ __forceinline__ float bflo(unsigned w) { return __uint_as_float(w << 16); }
; __device__ __forceinline__ float bfhi(unsigned w) { return __uint_as_float(w & 0xffff0000u); }
;     __device__ __forceinline__ void operator()(const pg8::f32x4 (&acc)[2][2][4][2], const pg8::Unit& u, int wr, int wc, int fr, int fq) const {
;     ...
;             for (int m = 0; m < 4; ++m)
; #pragma unroll
;                 for (int bj = 0; bj < 2; ++bj) {
;                     const size_t off = (size_t)(row0 + ai * 128 + m * 16) * DM + colb + bj * 128;
;                     const u32x4 gw = gv[m][bj], pw = pv[m][bj];
;                     pg8::f32x4 v0 = acc[ai][bj][m][0], v1 = acc[ai][bj][m][1];
;                     v0[0] = v0[0] * bflo(gw[0]) + bflo(pw[0]); v0[1] = v0[1] * bfhi(gw[0]) + bfhi(pw[0]); v0[2] = v0[2] * bflo(gw[1]) + bflo(pw[1]); v0[3] = v0[3] * bfhi(gw[1]) + bfhi(pw[1]);
;                     v1[0] = v1[0] * bflo(gw[2]) + bflo(pw[2]); v1[1] = v1[1] * bfhi(gw[2]) + bfhi(pw[2]); v1[2] = v1[2] * bflo(gw[3]) + bflo(pw[3]); v1[3] = v1[3] * bfhi(gw[3]) + bfhi(pw[3]);
;                     u32x4 w; w[0] = cvtpk(v0[0], v0[1]); w[1] = cvtpk(v0[2], v0[3]); w[2] = cvtpk(v1[0], v1[1]); w[3] = cvtpk(v1[2], v1[3]);
;                     *(u32x4*)(Mg + off) = w;
;                 }
	v_lshlrev_b32_e32 v122, 16, v171
	v_and_b32_e32 v123, 0xffff0000, v171
	v_pk_fma_f32 v[122:123], v[114:115], v[112:113], v[122:123]
	v_cvt_pk_bf16_f32 v112, v116, v117
	v_cvt_pk_bf16_f32 v113, v118, v119
	v_cvt_pk_bf16_f32 v114, v120, v121
	v_cvt_pk_bf16_f32 v115, v122, v123
	global_store_dwordx4 v[124:125], v[112:115], off offset:256
	v_lshlrev_b32_e32 v116, 16, v172
	v_and_b32_e32 v117, 0xffff0000, v172
	v_lshlrev_b32_e32 v114, 16, v176
	v_and_b32_e32 v115, 0xffff0000, v176
	v_pk_fma_f32 v[108:109], v[108:109], v[114:115], v[116:117]
	v_lshlrev_b32_e32 v114, 16, v177
	v_and_b32_e32 v115, 0xffff0000, v177
	v_lshlrev_b32_e32 v116, 16, v173
	v_and_b32_e32 v117, 0xffff0000, v173
	v_pk_fma_f32 v[110:111], v[110:111], v[114:115], v[116:117]
	v_lshlrev_b32_e32 v114, 16, v178
	v_and_b32_e32 v115, 0xffff0000, v178
	v_lshlrev_b32_e32 v116, 16, v174
	v_and_b32_e32 v117, 0xffff0000, v174
	v_lshlrev_b64 v[112:113], 12, v[216:217]
	v_pk_fma_f32 v[114:115], v[104:105], v[114:115], v[116:117]
	v_lshlrev_b32_e32 v104, 16, v179
	v_and_b32_e32 v105, 0xffff0000, v179
	v_lshlrev_b32_e32 v116, 16, v175
	v_and_b32_e32 v117, 0xffff0000, v175
	v_pk_fma_f32 v[116:117], v[106:107], v[104:105], v[116:117]
	v_cvt_pk_bf16_f32 v104, v108, v109
	v_lshl_add_u64 v[108:109], s[84:85], 0, v[112:113]
	v_cvt_pk_bf16_f32 v105, v110, v111
	v_cvt_pk_bf16_f32 v106, v114, v115
	v_cvt_pk_bf16_f32 v107, v116, v117
	v_lshl_add_u64 v[108:109], v[108:109], 0, v[184:185]
	global_store_dwordx4 v[108:109], v[104:107], off
	v_mov_b32_e32 v120, 0
	v_mov_b32_e32 v121, 0
	v_lshlrev_b32_e32 v104, 16, v164
	v_and_b32_e32 v105, 0xffff0000, v164
	v_lshlrev_b32_e32 v106, 16, v152
	v_and_b32_e32 v107, 0xffff0000, v152
	v_pk_fma_f32 v[100:101], v[100:101], v[104:105], v[106:107]
	v_lshlrev_b32_e32 v104, 16, v165
	v_and_b32_e32 v105, 0xffff0000, v165
	v_lshlrev_b32_e32 v106, 16, v153
	v_and_b32_e32 v107, 0xffff0000, v153
	v_pk_fma_f32 v[102:103], v[102:103], v[104:105], v[106:107]
	v_lshlrev_b32_e32 v104, 16, v166
	v_and_b32_e32 v105, 0xffff0000, v166
	v_lshlrev_b32_e32 v106, 16, v154
	v_and_b32_e32 v107, 0xffff0000, v154
	v_pk_fma_f32 v[104:105], v[96:97], v[104:105], v[106:107]
	v_lshlrev_b32_e32 v96, 16, v167
	v_and_b32_e32 v97, 0xffff0000, v167
	v_lshlrev_b32_e32 v106, 16, v155
	v_and_b32_e32 v107, 0xffff0000, v155
	v_pk_fma_f32 v[106:107], v[98:99], v[96:97], v[106:107]
	v_cvt_pk_bf16_f32 v96, v100, v101
	v_cvt_pk_bf16_f32 v97, v102, v103
	v_cvt_pk_bf16_f32 v98, v104, v105
	v_cvt_pk_bf16_f32 v99, v106, v107
	global_store_dwordx4 v[108:109], v[96:99], off offset:256
	v_lshlrev_b32_e32 v100, 16, v156
	v_and_b32_e32 v101, 0xffff0000, v156
	v_lshlrev_b32_e32 v98, 16, v160
	v_and_b32_e32 v99, 0xffff0000, v160
	v_pk_fma_f32 v[92:93], v[92:93], v[98:99], v[100:101]
	v_lshlrev_b32_e32 v98, 16, v161
	v_and_b32_e32 v99, 0xffff0000, v161
	v_lshlrev_b32_e32 v100, 16, v157
	v_and_b32_e32 v101, 0xffff0000, v157
	v_pk_fma_f32 v[94:95], v[94:95], v[98:99], v[100:101]
	v_lshlrev_b32_e32 v98, 16, v162
	v_and_b32_e32 v99, 0xffff0000, v162
	v_lshlrev_b32_e32 v100, 16, v158
	v_and_b32_e32 v101, 0xffff0000, v158
	v_lshlrev_b64 v[96:97], 12, v[214:215]
	v_pk_fma_f32 v[98:99], v[88:89], v[98:99], v[100:101]
	v_lshlrev_b32_e32 v88, 16, v163
	v_and_b32_e32 v89, 0xffff0000, v163
	v_lshlrev_b32_e32 v100, 16, v159
	v_and_b32_e32 v101, 0xffff0000, v159
	v_pk_fma_f32 v[100:101], v[90:91], v[88:89], v[100:101]
	v_cvt_pk_bf16_f32 v88, v92, v93
	v_lshl_add_u64 v[92:93], s[84:85], 0, v[96:97]
	v_cvt_pk_bf16_f32 v89, v94, v95
	v_cvt_pk_bf16_f32 v90, v98, v99
	v_cvt_pk_bf16_f32 v91, v100, v101
	v_lshl_add_u64 v[92:93], v[92:93], 0, v[184:185]
	global_store_dwordx4 v[92:93], v[88:91], off
	v_mov_b32_e32 v104, 0
	v_mov_b32_e32 v122, 0
	v_lshlrev_b32_e32 v88, 16, v148
	v_and_b32_e32 v89, 0xffff0000, v148
	v_lshlrev_b32_e32 v90, 16, v136
	v_and_b32_e32 v91, 0xffff0000, v136
	v_pk_fma_f32 v[84:85], v[84:85], v[88:89], v[90:91]
	v_lshlrev_b32_e32 v88, 16, v149
	v_and_b32_e32 v89, 0xffff0000, v149
	v_lshlrev_b32_e32 v90, 16, v137
	v_and_b32_e32 v91, 0xffff0000, v137
	v_pk_fma_f32 v[86:87], v[86:87], v[88:89], v[90:91]
	v_lshlrev_b32_e32 v88, 16, v150
	v_and_b32_e32 v89, 0xffff0000, v150
	v_lshlrev_b32_e32 v90, 16, v138
	v_and_b32_e32 v91, 0xffff0000, v138
	v_pk_fma_f32 v[88:89], v[80:81], v[88:89], v[90:91]
	v_lshlrev_b32_e32 v80, 16, v151
	v_and_b32_e32 v81, 0xffff0000, v151
	v_lshlrev_b32_e32 v90, 16, v139
	v_and_b32_e32 v91, 0xffff0000, v139
	v_pk_fma_f32 v[90:91], v[82:83], v[80:81], v[90:91]
	v_cvt_pk_bf16_f32 v80, v84, v85
	v_cvt_pk_bf16_f32 v81, v86, v87
	v_cvt_pk_bf16_f32 v82, v88, v89
	v_cvt_pk_bf16_f32 v83, v90, v91
	global_store_dwordx4 v[92:93], v[80:83], off offset:256
	v_lshlrev_b32_e32 v84, 16, v140
	v_and_b32_e32 v85, 0xffff0000, v140
	v_lshlrev_b32_e32 v82, 16, v144
	v_and_b32_e32 v83, 0xffff0000, v144
	v_pk_fma_f32 v[76:77], v[76:77], v[82:83], v[84:85]
; __device__ __forceinline__ unsigned cvtpk(float lo, float hi) { f32x2_t v = {lo, hi}; bf16x2_t b = __builtin_convertvector(v, bf16x2_t); return __builtin_bit_cast(unsigned, b); }
; __device__ __forceinline__ float bflo(unsigned w) { return __uint_as_float(w << 16); }
; __device__ __forceinline__ float bfhi(unsigned w) { return __uint_as_float(w & 0xffff0000u); }
;     __device__ __forceinline__ void operator()(const pg8::f32x4 (&acc)[2][2][4][2], const pg8::Unit& u, int wr, int wc, int fr, int fq) const {
;     ...
;             u32x4 gv[4][2], pv[4][2];
; #pragma unroll
;             for (int m = 0; m < 4; ++m)
; #pragma unroll
;                 for (int bj = 0; bj < 2; ++bj) { const size_t off = (size_t)(row0 + ai * 128 + m * 16) * DM + colb + bj * 128;
;                     gv[m][bj] = *(const u32x4*)(G + off); pv[m][bj] = (u32x4){0u, 0u, 0u, 0u}; if (second) pv[m][bj] = *(const u32x4*)(Mg + off); }
; #pragma unroll
;             for (int m = 0; m < 4; ++m)
; #pragma unroll
;                 for (int bj = 0; bj < 2; ++bj) {
;                     const size_t off = (size_t)(row0 + ai * 128 + m * 16) * DM + colb + bj * 128;
;                     const u32x4 gw = gv[m][bj], pw = pv[m][bj];
;                     pg8::f32x4 v0 = acc[ai][bj][m][0], v1 = acc[ai][bj][m][1];
;                     v0[0] = v0[0] * bflo(gw[0]) + bflo(pw[0]); v0[1] = v0[1] * bfhi(gw[0]) + bfhi(pw[0]); v0[2] = v0[2] * bflo(gw[1]) + bflo(pw[1]); v0[3] = v0[3] * bfhi(gw[1]) + bfhi(pw[1]);
;                     v1[0] = v1[0] * bflo(gw[2]) + bflo(pw[2]); v1[1] = v1[1] * bfhi(gw[2]) + bfhi(pw[2]); v1[2] = v1[2] * bflo(gw[3]) + bflo(pw[3]); v1[3] = v1[3] * bfhi(gw[3]) + bfhi(pw[3]);
;                     u32x4 w; w[0] = cvtpk(v0[0], v0[1]); w[1] = cvtpk(v0[2], v0[3]); w[2] = cvtpk(v1[0], v1[1]); w[3] = cvtpk(v1[2], v1[3]);
;                     *(u32x4*)(Mg + off) = w;
	v_lshlrev_b32_e32 v82, 16, v145
	v_and_b32_e32 v83, 0xffff0000, v145
	v_lshlrev_b32_e32 v84, 16, v141
	v_and_b32_e32 v85, 0xffff0000, v141
	v_pk_fma_f32 v[78:79], v[78:79], v[82:83], v[84:85]
	v_lshlrev_b32_e32 v82, 16, v146
	v_and_b32_e32 v83, 0xffff0000, v146
	v_lshlrev_b32_e32 v84, 16, v142
	v_and_b32_e32 v85, 0xffff0000, v142
	v_lshlrev_b64 v[80:81], 12, v[212:213]
	v_pk_fma_f32 v[82:83], v[72:73], v[82:83], v[84:85]
	v_lshlrev_b32_e32 v72, 16, v147
	v_and_b32_e32 v73, 0xffff0000, v147
	v_lshlrev_b32_e32 v84, 16, v143
	v_and_b32_e32 v85, 0xffff0000, v143
	v_pk_fma_f32 v[84:85], v[74:75], v[72:73], v[84:85]
	v_cvt_pk_bf16_f32 v72, v76, v77
	v_lshl_add_u64 v[76:77], s[84:85], 0, v[80:81]
	v_cvt_pk_bf16_f32 v73, v78, v79
	v_cvt_pk_bf16_f32 v74, v82, v83
	v_cvt_pk_bf16_f32 v75, v84, v85
	v_lshl_add_u64 v[76:77], v[76:77], 0, v[184:185]
	global_store_dwordx4 v[76:77], v[72:75], off
	v_mov_b32_e32 v123, 0
	s_nop 0
	v_lshlrev_b32_e32 v72, 16, v132
	v_and_b32_e32 v73, 0xffff0000, v132
	v_lshlrev_b32_e32 v74, 16, v128
	v_and_b32_e32 v75, 0xffff0000, v128
	v_pk_fma_f32 v[68:69], v[68:69], v[72:73], v[74:75]
	v_lshlrev_b32_e32 v72, 16, v133
	v_and_b32_e32 v73, 0xffff0000, v133
	v_lshlrev_b32_e32 v74, 16, v129
	v_and_b32_e32 v75, 0xffff0000, v129
	v_pk_fma_f32 v[70:71], v[70:71], v[72:73], v[74:75]
	v_lshlrev_b32_e32 v72, 16, v134
	v_and_b32_e32 v73, 0xffff0000, v134
	v_lshlrev_b32_e32 v74, 16, v130
	v_and_b32_e32 v75, 0xffff0000, v130
	v_pk_fma_f32 v[72:73], v[64:65], v[72:73], v[74:75]
	v_lshlrev_b32_e32 v64, 16, v135
	v_and_b32_e32 v65, 0xffff0000, v135
	v_lshlrev_b32_e32 v74, 16, v131
	v_and_b32_e32 v75, 0xffff0000, v131
	v_pk_fma_f32 v[74:75], v[66:67], v[64:65], v[74:75]
	v_add_u32_e32 v134, 0x80, v210
	v_cvt_pk_bf16_f32 v64, v68, v69
	v_cvt_pk_bf16_f32 v65, v70, v71
	v_cvt_pk_bf16_f32 v66, v72, v73
	v_cvt_pk_bf16_f32 v67, v74, v75
	v_ashrrev_i32_e32 v135, 31, v134
	global_store_dwordx4 v[76:77], v[64:67], off offset:256
	s_nop 1
	v_lshlrev_b64 v[64:65], 11, v[134:135]
	v_lshl_add_u64 v[64:65], v[64:65], 0, v[208:209]
	v_lshl_add_u64 v[66:67], v[64:65], 1, s[22:23]
	global_load_dwordx4 v[124:127], v[66:67], off nt
	v_lshl_add_u64 v[64:65], v[64:65], 1, s[84:85]
	s_cbranch_vccnz .LBB0_905
	global_load_dwordx4 v[120:123], v[64:65], off nt
.LBB0_905:
	global_load_dwordx4 v[116:119], v[66:67], off offset:256 nt
	s_and_b64 vcc, exec, s[0:1]
	v_mov_b32_e32 v105, 0
	v_mov_b32_e32 v106, 0
	v_mov_b32_e32 v107, 0
	s_cbranch_vccnz .LBB0_907
	global_load_dwordx4 v[104:107], v[64:65], off offset:256 nt
.LBB0_907:
	v_add_u32_e32 v132, 0x90, v210
	v_ashrrev_i32_e32 v133, 31, v132
	v_lshlrev_b64 v[64:65], 11, v[132:133]
	v_lshl_add_u64 v[64:65], v[64:65], 0, v[208:209]
	v_lshl_add_u64 v[66:67], v[64:65], 1, s[22:23]
	global_load_dwordx4 v[112:115], v[66:67], off nt
	v_mov_b32_e32 v88, 0
	s_and_b64 vcc, exec, s[0:1]
	v_lshl_add_u64 v[64:65], v[64:65], 1, s[84:85]
	v_mov_b32_e32 v108, 0
	v_mov_b32_e32 v109, 0
	v_mov_b32_e32 v110, 0
	v_mov_b32_e32 v111, 0
	s_cbranch_vccnz .LBB0_909
	global_load_dwordx4 v[108:111], v[64:65], off nt
.LBB0_909:
	global_load_dwordx4 v[100:103], v[66:67], off offset:256 nt
	s_and_b64 vcc, exec, s[0:1]
	v_mov_b32_e32 v89, 0
	v_mov_b32_e32 v90, 0
	v_mov_b32_e32 v91, 0
	s_cbranch_vccnz .LBB0_911
	global_load_dwordx4 v[88:91], v[64:65], off offset:256 nt
.LBB0_911:
	v_add_u32_e32 v130, 0xa0, v210
	v_ashrrev_i32_e32 v131, 31, v130
	v_lshlrev_b64 v[64:65], 11, v[130:131]
	v_lshl_add_u64 v[64:65], v[64:65], 0, v[208:209]
	v_lshl_add_u64 v[66:67], v[64:65], 1, s[22:23]
	global_load_dwordx4 v[96:99], v[66:67], off nt
	v_mov_b32_e32 v72, 0
	s_and_b64 vcc, exec, s[0:1]
	v_lshl_add_u64 v[64:65], v[64:65], 1, s[84:85]
	v_mov_b32_e32 v92, 0
	v_mov_b32_e32 v93, 0
	v_mov_b32_e32 v94, 0
	v_mov_b32_e32 v95, 0
	s_cbranch_vccnz .LBB0_913
	global_load_dwordx4 v[92:95], v[64:65], off nt
.LBB0_913:
	global_load_dwordx4 v[84:87], v[66:67], off offset:256 nt
	s_and_b64 vcc, exec, s[0:1]
	v_mov_b32_e32 v73, 0
	v_mov_b32_e32 v74, 0
	v_mov_b32_e32 v75, 0
	s_cbranch_vccnz .LBB0_915
	global_load_dwordx4 v[72:75], v[64:65], off offset:256 nt
.LBB0_915:
	v_add_u32_e32 v128, 0xb0, v210
	v_ashrrev_i32_e32 v129, 31, v128
	v_lshlrev_b64 v[64:65], 11, v[128:129]
	v_lshl_add_u64 v[68:69], v[64:65], 0, v[208:209]
	v_lshl_add_u64 v[66:67], v[68:69], 1, s[22:23]
	global_load_dwordx4 v[80:83], v[66:67], off nt
	v_mov_b32_e32 v64, 0
	s_and_b64 vcc, exec, s[0:1]
	v_lshl_add_u64 v[136:137], v[68:69], 1, s[84:85]
	v_mov_b32_e32 v76, 0
	v_mov_b32_e32 v77, 0
	v_mov_b32_e32 v78, 0
	v_mov_b32_e32 v79, 0
	s_cbranch_vccnz .LBB0_917
	global_load_dwordx4 v[76:79], v[136:137], off nt
.LBB0_917:
	global_load_dwordx4 v[68:71], v[66:67], off offset:256 nt
	s_and_b64 vcc, exec, s[0:1]
	v_mov_b32_e32 v65, 0
	v_mov_b32_e32 v66, 0
	v_mov_b32_e32 v67, 0
	s_cbranch_vccnz .LBB0_919
	global_load_dwordx4 v[64:67], v[136:137], off offset:256 nt

; __device__ __forceinline__ unsigned cvtpk(float lo, float hi) { f32x2_t v = {lo, hi}; bf16x2_t b = __builtin_convertvector(v, bf16x2_t); return __builtin_bit_cast(unsigned, b); }
;     __device__ __forceinline__ void operator()(const pg8::f32x4 (&acc)[2][2][4][2], const pg8::Unit& u, int wr, int wc, int fr, int fq) const {
;         const int row0 = u.pm * 256 + wr * 64 + fr, colb = u.pn * 256 + wc * 32 + 8 * fq;
; #pragma unroll
;         for (int ai = 0; ai < 2; ++ai) {
;             pg8::f32x4 rv[4][2][2];
; #pragma unroll
;             for (int m = 0; m < 4; ++m)
; #pragma unroll
;                 for (int bj = 0; bj < 2; ++bj) { const size_t off = (size_t)(row0 + ai * 128 + m * 16) * DM + colb + bj * 128;
;                     rv[m][bj][0] = *(const pg8::f32x4*)(R + off); rv[m][bj][1] = *(const pg8::f32x4*)(R + off + 4); }
; #pragma unroll
;             for (int m = 0; m < 4; ++m) {
;                 const int row = row0 + ai * 128 + m * 16;
;                 float sq = 0.f;
; #pragma unroll
;                 for (int bj = 0; bj < 2; ++bj) {
;                     const size_t off = (size_t)row * DM + colb + bj * 128;
;                     const pg8::f32x4 v0 = rv[m][bj][0] + acc[ai][bj][m][0] * alpha, v1 = rv[m][bj][1] + acc[ai][bj][m][1] * alpha;
;                     *(pg8::f32x4*)(X + off) = v0; *(pg8::f32x4*)(X + off + 4) = v1;
;                     u32x4 w; w[0] = cvtpk(v0[0], v0[1]); w[1] = cvtpk(v0[2], v0[3]); w[2] = cvtpk(v1[0], v1[1]); w[3] = cvtpk(v1[2], v1[3]);
;                     *(u32x4*)(XB + off) = w;
;                     sq += (v0[0] * v0[0] + v0[1] * v0[1]) + (v0[2] * v0[2] + v0[3] * v0[3]) + (v1[0] * v1[0] + v1[1] * v1[1]) + (v1[2] * v1[2] + v1[3] * v1[3]);
;                 }
;                 sq += __shfl_xor(sq, 16); sq += __shfl_xor(sq, 32);
;                 if (fq == 0) atomicAdd(ssout + row, sq);
.LBB0_996:
	v_lshl_add_u32 v194, s22, 8, v210
	v_lshl_or_b32 v192, s24, 8, v212
	v_ashrrev_i32_e32 v193, 31, v192
	v_ashrrev_i32_e32 v195, 31, v194
	v_lshl_add_u64 v[196:197], v[192:193], 2, s[62:63]
	v_lshlrev_b64 v[128:129], 13, v[194:195]
	v_lshl_add_u64 v[238:239], v[196:197], 0, v[128:129]
	global_load_dwordx4 v[222:225], v[238:239], off nt
	global_load_dwordx4 v[226:229], v[238:239], off offset:16 nt
	global_load_dwordx4 v[230:233], v[238:239], off offset:512 nt
	global_load_dwordx4 v[234:237], v[238:239], off offset:528 nt
	v_or_b32_e32 v206, 16, v194
	v_or_b32_e32 v202, 32, v194
	v_or_b32_e32 v198, 48, v194
	v_ashrrev_i32_e32 v207, 31, v206
	v_ashrrev_i32_e32 v203, 31, v202
	v_ashrrev_i32_e32 v199, 31, v198
	v_lshlrev_b64 v[128:129], 13, v[206:207]
	v_lshlrev_b64 v[130:131], 13, v[202:203]
	v_lshlrev_b64 v[132:133], 13, v[198:199]
	v_lshl_add_u64 v[208:209], v[196:197], 0, v[128:129]
	v_lshl_add_u64 v[204:205], v[196:197], 0, v[130:131]
	v_lshl_add_u64 v[200:201], v[196:197], 0, v[132:133]
	global_load_dwordx4 v[168:171], v[208:209], off offset:16 nt
	global_load_dwordx4 v[172:175], v[208:209], off nt
	global_load_dwordx4 v[160:163], v[208:209], off offset:528 nt
	global_load_dwordx4 v[164:167], v[208:209], off offset:512 nt
	global_load_dwordx4 v[152:155], v[204:205], off offset:16 nt
	global_load_dwordx4 v[156:159], v[204:205], off nt
	global_load_dwordx4 v[144:147], v[204:205], off offset:528 nt
	global_load_dwordx4 v[148:151], v[204:205], off offset:512 nt
	global_load_dwordx4 v[136:139], v[200:201], off offset:16 nt
	global_load_dwordx4 v[140:143], v[200:201], off nt
	global_load_dwordx4 v[128:131], v[200:201], off offset:528 nt
	global_load_dwordx4 v[132:135], v[200:201], off offset:512 nt
	v_and_b32_e32 v218, 64, v216
	v_xor_b32_e32 v217, 16, v216
	v_add_u32_e32 v218, 64, v218
	v_xor_b32_e32 v219, 32, v216
	v_cmp_lt_i32_e32 vcc, v217, v218
	v_lshlrev_b64 v[240:241], 11, v[194:195]
	v_lshl_add_u64 v[240:241], v[240:241], 0, v[192:193]
	v_cndmask_b32_e32 v217, v216, v217, vcc
	v_cmp_lt_i32_e32 vcc, v219, v218
	v_lshlrev_b32_e32 v218, 2, v217
	v_lshlrev_b64 v[240:241], 1, v[240:241]
	v_cndmask_b32_e32 v219, v216, v219, vcc
	v_lshlrev_b32_e32 v217, 2, v219
	v_lshl_add_u64 v[242:243], s[80:81], 0, v[240:241]
	v_or_b32_e32 v240, 0x100, v240
	s_waitcnt vmcnt(0)
	v_pk_add_f32 v[126:127], v[126:127], v[224:225]
	v_pk_add_f32 v[124:125], v[124:125], v[222:223]
	v_pk_add_f32 v[118:119], v[118:119], v[232:233]
	v_pk_add_f32 v[116:117], v[116:117], v[230:231]
	v_pk_add_f32 v[122:123], v[122:123], v[228:229]
	v_pk_add_f32 v[120:121], v[120:121], v[226:227]
	v_pk_add_f32 v[112:113], v[112:113], v[234:235]
	global_store_dwordx4 v[238:239], v[124:127], off nt
	global_store_dwordx4 v[238:239], v[120:123], off offset:16 nt
	v_cvt_pk_bf16_f32 v222, v124, v125
	v_cvt_pk_bf16_f32 v223, v126, v127
	v_mul_f32_e32 v125, v125, v125
	v_mul_f32_e32 v127, v127, v127
	v_mul_f32_e32 v219, v117, v117
	v_mul_f32_e32 v221, v119, v119
	v_pk_add_f32 v[114:115], v[114:115], v[236:237]
	v_cvt_pk_bf16_f32 v224, v120, v121
	v_cvt_pk_bf16_f32 v225, v122, v123
	v_mul_f32_e32 v121, v121, v121
	v_mul_f32_e32 v123, v123, v123
	v_mul_f32_e32 v226, v113, v113
	v_fmac_f32_e32 v125, v124, v124
	v_fmac_f32_e32 v127, v126, v126
	v_fmac_f32_e32 v219, v116, v116
	v_fmac_f32_e32 v221, v118, v118
	v_mul_f32_e32 v227, v115, v115
	v_fmac_f32_e32 v121, v120, v120
	v_fmac_f32_e32 v123, v122, v122
	v_fmac_f32_e32 v226, v112, v112
	v_add_f32_e32 v120, v125, v127
	v_add_f32_e32 v122, v219, v221
	v_fmac_f32_e32 v227, v114, v114
	v_add_f32_e32 v120, v121, v120
	v_add_f32_e32 v121, v226, v122
	v_add_f32_e32 v120, v123, v120
	v_add_f32_e32 v121, v227, v121
	v_add_f32_e32 v120, v120, v121
	ds_bpermute_b32 v121, v218, v120
	global_store_dwordx4 v[242:243], v[222:225], off
	global_store_dwordx4 v[238:239], v[116:119], off offset:512 nt
	global_store_dwordx4 v[238:239], v[112:115], off offset:528 nt
	s_nop 0
	v_cvt_pk_bf16_f32 v116, v116, v117
	v_cvt_pk_bf16_f32 v117, v118, v119
	v_cvt_pk_bf16_f32 v118, v112, v113
	s_waitcnt lgkmcnt(0)
	v_add_f32_e32 v112, v120, v121
	ds_bpermute_b32 v113, v217, v112
	v_cvt_pk_bf16_f32 v119, v114, v115
	v_lshl_add_u64 v[114:115], s[80:81], 0, v[240:241]
	global_store_dwordx4 v[114:115], v[116:119], off
	s_and_saveexec_b64 s[22:23], s[0:1]
	s_cbranch_execz .LBB0_998
	v_lshl_add_u64 v[114:115], v[194:195], 2, s[8:9]
	s_waitcnt lgkmcnt(0)
	v_add_f32_e32 v112, v112, v113
	global_atomic_add_f32 v[114:115], v112, off

; __device__ __forceinline__ unsigned cvtpk(float lo, float hi) { f32x2_t v = {lo, hi}; bf16x2_t b = __builtin_convertvector(v, bf16x2_t); return __builtin_bit_cast(unsigned, b); }
;     __device__ __forceinline__ void operator()(const pg8::f32x4 (&acc)[2][2][4][2], const pg8::Unit& u, int wr, int wc, int fr, int fq) const {
;     ...
;         for (int ai = 0; ai < 2; ++ai) {
;             pg8::f32x4 rv[4][2][2];
; #pragma unroll
;             for (int m = 0; m < 4; ++m)
; #pragma unroll
;                 for (int bj = 0; bj < 2; ++bj) { const size_t off = (size_t)(row0 + ai * 128 + m * 16) * DM + colb + bj * 128;
;                     rv[m][bj][0] = *(const pg8::f32x4*)(R + off); rv[m][bj][1] = *(const pg8::f32x4*)(R + off + 4); }
; #pragma unroll
;             for (int m = 0; m < 4; ++m) {
;                 const int row = row0 + ai * 128 + m * 16;
;                 float sq = 0.f;
; #pragma unroll
;                 for (int bj = 0; bj < 2; ++bj) {
;                     const size_t off = (size_t)row * DM + colb + bj * 128;
;                     const pg8::f32x4 v0 = rv[m][bj][0] + acc[ai][bj][m][0] * alpha, v1 = rv[m][bj][1] + acc[ai][bj][m][1] * alpha;
;                     *(pg8::f32x4*)(X + off) = v0; *(pg8::f32x4*)(X + off + 4) = v1;
;                     u32x4 w; w[0] = cvtpk(v0[0], v0[1]); w[1] = cvtpk(v0[2], v0[3]); w[2] = cvtpk(v1[0], v1[1]); w[3] = cvtpk(v1[2], v1[3]);
;                     *(u32x4*)(XB + off) = w;
;                     sq += (v0[0] * v0[0] + v0[1] * v0[1]) + (v0[2] * v0[2] + v0[3] * v0[3]) + (v1[0] * v1[0] + v1[1] * v1[1]) + (v1[2] * v1[2] + v1[3] * v1[3]);
;                 }
;                 sq += __shfl_xor(sq, 16); sq += __shfl_xor(sq, 32);
;                 if (fq == 0) atomicAdd(ssout + row, sq);
.LBB0_1004:
	s_or_b64 exec, exec, s[22:23]
	v_add_u32_e32 v124, 0x80, v194
	v_ashrrev_i32_e32 v125, 31, v124
	s_waitcnt lgkmcnt(0)
	v_lshlrev_b64 v[64:65], 13, v[124:125]
	v_lshl_add_u64 v[142:143], v[196:197], 0, v[64:65]
	global_load_dwordx4 v[126:129], v[142:143], off nt
	global_load_dwordx4 v[130:133], v[142:143], off offset:16 nt
	global_load_dwordx4 v[134:137], v[142:143], off offset:512 nt
	global_load_dwordx4 v[138:141], v[142:143], off offset:528 nt
	v_add_u32_e32 v120, 0x90, v194
	v_add_u32_e32 v116, 0xa0, v194
	v_add_u32_e32 v112, 0xb0, v194
	v_ashrrev_i32_e32 v121, 31, v120
	v_ashrrev_i32_e32 v117, 31, v116
	v_ashrrev_i32_e32 v113, 31, v112
	v_lshlrev_b64 v[64:65], 13, v[120:121]
	v_lshlrev_b64 v[66:67], 13, v[116:117]
	v_lshlrev_b64 v[68:69], 13, v[112:113]
	v_lshl_add_u64 v[122:123], v[196:197], 0, v[64:65]
	v_lshl_add_u64 v[118:119], v[196:197], 0, v[66:67]
	v_lshl_add_u64 v[114:115], v[196:197], 0, v[68:69]
	global_load_dwordx4 v[104:107], v[122:123], off offset:16 nt
	global_load_dwordx4 v[108:111], v[122:123], off nt
	global_load_dwordx4 v[96:99], v[122:123], off offset:528 nt
	global_load_dwordx4 v[100:103], v[122:123], off offset:512 nt
	global_load_dwordx4 v[88:91], v[118:119], off offset:16 nt
	global_load_dwordx4 v[92:95], v[118:119], off nt
	global_load_dwordx4 v[80:83], v[118:119], off offset:528 nt
	global_load_dwordx4 v[84:87], v[118:119], off offset:512 nt
	global_load_dwordx4 v[72:75], v[114:115], off offset:16 nt
	global_load_dwordx4 v[76:79], v[114:115], off nt
	global_load_dwordx4 v[64:67], v[114:115], off offset:528 nt
	global_load_dwordx4 v[68:71], v[114:115], off offset:512 nt
	v_lshlrev_b64 v[144:145], 11, v[124:125]
	v_lshl_add_u64 v[144:145], v[144:145], 0, v[192:193]
	v_lshlrev_b64 v[144:145], 1, v[144:145]
	v_lshl_add_u64 v[146:147], s[80:81], 0, v[144:145]
	v_or_b32_e32 v144, 0x100, v144
	s_waitcnt vmcnt(15)
	v_pk_add_f32 v[62:63], v[62:63], v[128:129]
	v_pk_add_f32 v[60:61], v[60:61], v[126:127]
	s_waitcnt vmcnt(13)
	v_pk_add_f32 v[54:55], v[54:55], v[136:137]
	v_pk_add_f32 v[52:53], v[52:53], v[134:135]
	v_pk_add_f32 v[58:59], v[58:59], v[132:133]
	v_pk_add_f32 v[56:57], v[56:57], v[130:131]
	s_waitcnt vmcnt(12)
	v_pk_add_f32 v[48:49], v[48:49], v[138:139]
	global_store_dwordx4 v[142:143], v[60:63], off nt
	global_store_dwordx4 v[142:143], v[56:59], off offset:16 nt
	v_cvt_pk_bf16_f32 v126, v60, v61
	v_cvt_pk_bf16_f32 v127, v62, v63
	v_mul_f32_e32 v61, v61, v61
	v_mul_f32_e32 v63, v63, v63
	v_mul_f32_e32 v130, v53, v53
	v_mul_f32_e32 v131, v55, v55
	v_pk_add_f32 v[50:51], v[50:51], v[140:141]
	v_cvt_pk_bf16_f32 v128, v56, v57
	v_cvt_pk_bf16_f32 v129, v58, v59
	v_mul_f32_e32 v57, v57, v57
	v_mul_f32_e32 v59, v59, v59
	v_mul_f32_e32 v132, v49, v49
	v_fmac_f32_e32 v61, v60, v60
	v_fmac_f32_e32 v63, v62, v62
	v_fmac_f32_e32 v130, v52, v52
	v_fmac_f32_e32 v131, v54, v54
	v_mul_f32_e32 v133, v51, v51
	v_fmac_f32_e32 v57, v56, v56
	v_fmac_f32_e32 v59, v58, v58
	v_fmac_f32_e32 v132, v48, v48
	v_add_f32_e32 v56, v61, v63
	v_add_f32_e32 v58, v130, v131
	v_fmac_f32_e32 v133, v50, v50
	v_add_f32_e32 v56, v57, v56
	v_add_f32_e32 v57, v132, v58
	v_add_f32_e32 v56, v59, v56
	v_add_f32_e32 v57, v133, v57
	v_add_f32_e32 v56, v56, v57
	ds_bpermute_b32 v57, v218, v56
	global_store_dwordx4 v[146:147], v[126:129], off
	global_store_dwordx4 v[142:143], v[52:55], off offset:512 nt
	global_store_dwordx4 v[142:143], v[48:51], off offset:528 nt
	s_nop 0
	v_cvt_pk_bf16_f32 v52, v52, v53
	v_cvt_pk_bf16_f32 v53, v54, v55
	v_cvt_pk_bf16_f32 v54, v48, v49
	s_waitcnt lgkmcnt(0)
	v_add_f32_e32 v48, v56, v57
	ds_bpermute_b32 v49, v217, v48
	v_cvt_pk_bf16_f32 v55, v50, v51
	v_lshl_add_u64 v[50:51], s[80:81], 0, v[144:145]
	global_store_dwordx4 v[50:51], v[52:55], off
	s_and_saveexec_b64 s[22:23], s[0:1]
	s_cbranch_execz .LBB0_1006
	v_lshl_add_u64 v[50:51], v[124:125], 2, s[8:9]
	s_waitcnt lgkmcnt(0)
	v_add_f32_e32 v48, v48, v49
	global_atomic_add_f32 v[50:51], v48, off

; __device__ __forceinline__ unsigned cvtpk(float lo, float hi) { f32x2_t v = {lo, hi}; bf16x2_t b = __builtin_convertvector(v, bf16x2_t); return __builtin_bit_cast(unsigned, b); }
;     __device__ __forceinline__ void operator()(const pg8::f32x4 (&acc)[2][2][4][2], const pg8::Unit& u, int wr, int wc, int fr, int fq) const {
;     ...
;             for (int m = 0; m < 4; ++m) {
;                 const int row = u.pm * 256 + ai * 128 + wr * 64 + m * 16 + fr;
;                 float sq = 0.f;
; #pragma unroll
;                 for (int bj = 0; bj < 2; ++bj) {
;                     const size_t off = (size_t)row * DM + u.pn * 256 + bj * 128 + wc * 32 + 8 * fq;
;                     const pg8::f32x4 v0 = acc[ai][bj][m][0], v1 = acc[ai][bj][m][1];
;                     u32x4 w; w[0] = cvtpk(v0[0], v0[1]); w[1] = cvtpk(v0[2], v0[3]); w[2] = cvtpk(v1[0], v1[1]); w[3] = cvtpk(v1[2], v1[3]);
;                     *(u32x4*)(O + off) = w;
;                     sq += (v0[0] * v0[0] + v0[1] * v0[1]) + (v0[2] * v0[2] + v0[3] * v0[3]) + (v1[0] * v1[0] + v1[1] * v1[1]) + (v1[2] * v1[2] + v1[3] * v1[3]);
;                 }
;                 sq += __shfl_xor(sq, 16); sq += __shfl_xor(sq, 32);
;                 if (fq == 0) atomicAdd(ssout + row, sq);
;             }
.LBB0_1110:
	v_cvt_pk_bf16_f32 v156, v124, v125
	v_mul_f32_e32 v125, v125, v125
	v_fmac_f32_e32 v125, v124, v124
	v_mul_f32_e32 v124, v127, v127
	v_cvt_pk_bf16_f32 v158, v120, v121
	v_fmac_f32_e32 v124, v126, v126
	v_mul_f32_e32 v121, v121, v121
	v_add_f32_e32 v124, v125, v124
	v_fmac_f32_e32 v121, v120, v120
	v_add_f32_e32 v120, v121, v124
	v_mul_f32_e32 v121, v123, v123
	v_fmac_f32_e32 v121, v122, v122
	v_cvt_pk_bf16_f32 v159, v122, v123
	v_add_f32_e32 v120, v121, v120
	v_mul_f32_e32 v121, v117, v117
	v_mul_f32_e32 v122, v119, v119
	v_and_b32_e32 v153, 64, v152
	v_fmac_f32_e32 v121, v116, v116
	v_fmac_f32_e32 v122, v118, v118
	v_xor_b32_e32 v147, 16, v152
	v_add_u32_e32 v153, 64, v153
	v_add_f32_e32 v121, v121, v122
	v_mul_f32_e32 v122, v113, v113
	v_cmp_lt_i32_e32 vcc, v147, v153
	v_fmac_f32_e32 v122, v112, v112
	v_add_f32_e32 v121, v122, v121
	v_cndmask_b32_e32 v147, v152, v147, vcc
	v_mul_f32_e32 v122, v115, v115
	v_lshlrev_b32_e32 v155, 2, v147
	v_xor_b32_e32 v147, 32, v152
	v_fmac_f32_e32 v122, v114, v114
	v_cmp_lt_i32_e32 vcc, v147, v153
	v_add_f32_e32 v121, v122, v121
	v_lshl_add_u32 v146, s52, 8, v154
	v_cndmask_b32_e32 v147, v152, v147, vcc
	v_add_f32_e32 v122, v121, v120
	v_lshlrev_b32_e32 v153, 2, v147
	v_ashrrev_i32_e32 v147, 31, v146
	ds_bpermute_b32 v123, v155, v122
	s_lshl_b32 s28, s53, 8
	v_lshlrev_b64 v[160:161], 12, v[146:147]
	s_ashr_i32 s29, s28, 31
	v_lshl_add_u64 v[160:161], s[6:7], 0, v[160:161]
	v_lshl_add_u64 v[160:161], s[28:29], 1, v[160:161]
	v_lshl_add_u64 v[120:121], v[160:161], 0, s[14:15]
	v_lshl_add_u64 v[124:125], v[120:121], 0, v[136:137]
	v_cvt_pk_bf16_f32 v120, v116, v117
	s_waitcnt lgkmcnt(0)
	v_add_f32_e32 v116, v122, v123
	ds_bpermute_b32 v117, v153, v116
	v_cvt_pk_bf16_f32 v157, v126, v127
	v_cvt_pk_bf16_f32 v121, v118, v119
	v_cvt_pk_bf16_f32 v122, v112, v113
	v_cvt_pk_bf16_f32 v123, v114, v115
	global_store_dwordx4 v[124:125], v[156:159], off nt
	global_store_dwordx4 v[124:125], v[120:123], off offset:256 nt
	s_and_saveexec_b64 s[30:31], s[0:1]
	s_cbranch_execz .LBB0_1112
	s_waitcnt lgkmcnt(0)
	v_add_f32_e32 v114, v116, v117
	v_lshl_add_u64 v[112:113], v[146:147], 2, s[18:19]
	global_atomic_add_f32 v[112:113], v114, off
.LBB0_1112:
	s_or_b64 exec, exec, s[30:31]
	v_cvt_pk_bf16_f32 v114, v108, v109
	v_mul_f32_e32 v109, v109, v109
	v_fmac_f32_e32 v109, v108, v108
	v_mul_f32_e32 v108, v111, v111
	v_cvt_pk_bf16_f32 v116, v104, v105
	v_fmac_f32_e32 v108, v110, v110
	v_mul_f32_e32 v105, v105, v105
	v_add_f32_e32 v108, v109, v108
	v_fmac_f32_e32 v105, v104, v104
	v_add_f32_e32 v104, v105, v108
	v_mul_f32_e32 v105, v107, v107
	v_fmac_f32_e32 v105, v106, v106
	s_waitcnt lgkmcnt(0)
	v_cvt_pk_bf16_f32 v117, v106, v107
	v_add_f32_e32 v104, v105, v104
	v_mul_f32_e32 v105, v101, v101
	v_mul_f32_e32 v106, v103, v103
	v_fmac_f32_e32 v105, v100, v100
	v_fmac_f32_e32 v106, v102, v102
	v_add_f32_e32 v105, v105, v106
	v_mul_f32_e32 v106, v97, v97
	v_fmac_f32_e32 v106, v96, v96
	v_add_f32_e32 v105, v106, v105
	v_mul_f32_e32 v106, v99, v99
	v_fmac_f32_e32 v106, v98, v98
	v_add_f32_e32 v105, v106, v105
	v_or_b32_e32 v112, 16, v146
	v_add_f32_e32 v106, v105, v104
	v_ashrrev_i32_e32 v113, 31, v112
	ds_bpermute_b32 v107, v155, v106
	v_lshlrev_b64 v[118:119], 12, v[112:113]
	v_lshl_add_u64 v[118:119], s[6:7], 0, v[118:119]
	v_lshl_add_u64 v[118:119], s[28:29], 1, v[118:119]
	v_lshl_add_u64 v[104:105], v[118:119], 0, s[14:15]
	v_lshl_add_u64 v[108:109], v[104:105], 0, v[136:137]
	v_cvt_pk_bf16_f32 v104, v100, v101
	s_waitcnt lgkmcnt(0)
	v_add_f32_e32 v100, v106, v107
	ds_bpermute_b32 v101, v153, v100
	v_cvt_pk_bf16_f32 v115, v110, v111
	v_cvt_pk_bf16_f32 v105, v102, v103
	v_cvt_pk_bf16_f32 v106, v96, v97
	v_cvt_pk_bf16_f32 v107, v98, v99
	global_store_dwordx4 v[108:109], v[114:117], off nt
	global_store_dwordx4 v[108:109], v[104:107], off offset:256 nt
	s_and_saveexec_b64 s[30:31], s[0:1]
	s_cbranch_execz .LBB0_1114
	s_waitcnt lgkmcnt(0)
	v_add_f32_e32 v98, v100, v101
	v_lshl_add_u64 v[96:97], v[112:113], 2, s[18:19]
	global_atomic_add_f32 v[96:97], v98, off
.LBB0_1114:
	s_or_b64 exec, exec, s[30:31]
	v_cvt_pk_bf16_f32 v98, v92, v93
	v_mul_f32_e32 v93, v93, v93
	v_fmac_f32_e32 v93, v92, v92
	v_mul_f32_e32 v92, v95, v95
	v_cvt_pk_bf16_f32 v100, v88, v89
	v_fmac_f32_e32 v92, v94, v94
	v_mul_f32_e32 v89, v89, v89
	v_add_f32_e32 v92, v93, v92
	v_fmac_f32_e32 v89, v88, v88
	v_add_f32_e32 v88, v89, v92
	v_mul_f32_e32 v89, v91, v91
	v_fmac_f32_e32 v89, v90, v90
	s_waitcnt lgkmcnt(0)
	v_cvt_pk_bf16_f32 v101, v90, v91
	v_add_f32_e32 v88, v89, v88
	v_mul_f32_e32 v89, v85, v85
	v_mul_f32_e32 v90, v87, v87
	v_fmac_f32_e32 v89, v84, v84
	v_fmac_f32_e32 v90, v86, v86
	v_add_f32_e32 v89, v89, v90
	v_mul_f32_e32 v90, v81, v81
	v_fmac_f32_e32 v90, v80, v80
	v_add_f32_e32 v89, v90, v89
	v_mul_f32_e32 v90, v83, v83
	v_fmac_f32_e32 v90, v82, v82
	v_add_f32_e32 v89, v90, v89
	v_or_b32_e32 v96, 32, v146
	v_add_f32_e32 v90, v89, v88
	v_ashrrev_i32_e32 v97, 31, v96
	ds_bpermute_b32 v91, v155, v90
	v_lshlrev_b64 v[102:103], 12, v[96:97]
	v_lshl_add_u64 v[102:103], s[6:7], 0, v[102:103]
	v_lshl_add_u64 v[102:103], s[28:29], 1, v[102:103]
	v_lshl_add_u64 v[88:89], v[102:103], 0, s[14:15]
	v_lshl_add_u64 v[92:93], v[88:89], 0, v[136:137]
	v_cvt_pk_bf16_f32 v88, v84, v85
	s_waitcnt lgkmcnt(0)
	v_add_f32_e32 v84, v90, v91
	ds_bpermute_b32 v85, v153, v84
	v_cvt_pk_bf16_f32 v99, v94, v95
	v_cvt_pk_bf16_f32 v89, v86, v87
	v_cvt_pk_bf16_f32 v90, v80, v81
	v_cvt_pk_bf16_f32 v91, v82, v83
	global_store_dwordx4 v[92:93], v[98:101], off nt
	global_store_dwordx4 v[92:93], v[88:91], off offset:256 nt
	s_and_saveexec_b64 s[30:31], s[0:1]
	s_cbranch_execz .LBB0_1116
	s_waitcnt lgkmcnt(0)
	v_add_f32_e32 v82, v84, v85
	v_lshl_add_u64 v[80:81], v[96:97], 2, s[18:19]
	global_atomic_add_f32 v[80:81], v82, off
; __device__ __forceinline__ unsigned cvtpk(float lo, float hi) { f32x2_t v = {lo, hi}; bf16x2_t b = __builtin_convertvector(v, bf16x2_t); return __builtin_bit_cast(unsigned, b); }
;     __device__ __forceinline__ void operator()(const pg8::f32x4 (&acc)[2][2][4][2], const pg8::Unit& u, int wr, int wc, int fr, int fq) const {
;     ...
;             for (int m = 0; m < 4; ++m) {
;                 const int row = u.pm * 256 + ai * 128 + wr * 64 + m * 16 + fr;
;                 float sq = 0.f;
; #pragma unroll
;                 for (int bj = 0; bj < 2; ++bj) {
;                     const size_t off = (size_t)row * DM + u.pn * 256 + bj * 128 + wc * 32 + 8 * fq;
;                     const pg8::f32x4 v0 = acc[ai][bj][m][0], v1 = acc[ai][bj][m][1];
;                     u32x4 w; w[0] = cvtpk(v0[0], v0[1]); w[1] = cvtpk(v0[2], v0[3]); w[2] = cvtpk(v1[0], v1[1]); w[3] = cvtpk(v1[2], v1[3]);
;                     *(u32x4*)(O + off) = w;
;                     sq += (v0[0] * v0[0] + v0[1] * v0[1]) + (v0[2] * v0[2] + v0[3] * v0[3]) + (v1[0] * v1[0] + v1[1] * v1[1]) + (v1[2] * v1[2] + v1[3] * v1[3]);
;                 }
;                 sq += __shfl_xor(sq, 16); sq += __shfl_xor(sq, 32);
;                 if (fq == 0) atomicAdd(ssout + row, sq);
;             }
.LBB0_1116:
	s_or_b64 exec, exec, s[30:31]
	v_cvt_pk_bf16_f32 v82, v76, v77
	v_mul_f32_e32 v77, v77, v77
	v_fmac_f32_e32 v77, v76, v76
	v_mul_f32_e32 v76, v79, v79
	v_cvt_pk_bf16_f32 v84, v72, v73
	v_fmac_f32_e32 v76, v78, v78
	v_mul_f32_e32 v73, v73, v73
	v_add_f32_e32 v76, v77, v76
	v_fmac_f32_e32 v73, v72, v72
	v_add_f32_e32 v72, v73, v76
	v_mul_f32_e32 v73, v75, v75
	v_fmac_f32_e32 v73, v74, v74
	s_waitcnt lgkmcnt(0)
	v_cvt_pk_bf16_f32 v85, v74, v75
	v_add_f32_e32 v72, v73, v72
	v_mul_f32_e32 v73, v69, v69
	v_mul_f32_e32 v74, v71, v71
	v_fmac_f32_e32 v73, v68, v68
	v_fmac_f32_e32 v74, v70, v70
	v_add_f32_e32 v73, v73, v74
	v_mul_f32_e32 v74, v65, v65
	v_fmac_f32_e32 v74, v64, v64
	v_add_f32_e32 v73, v74, v73
	v_mul_f32_e32 v74, v67, v67
	v_fmac_f32_e32 v74, v66, v66
	v_add_f32_e32 v73, v74, v73
	v_or_b32_e32 v80, 48, v146
	v_add_f32_e32 v74, v73, v72
	v_ashrrev_i32_e32 v81, 31, v80
	ds_bpermute_b32 v75, v155, v74
	v_lshlrev_b64 v[86:87], 12, v[80:81]
	v_lshl_add_u64 v[86:87], s[6:7], 0, v[86:87]
	v_lshl_add_u64 v[86:87], s[28:29], 1, v[86:87]
	v_lshl_add_u64 v[72:73], v[86:87], 0, s[14:15]
	v_lshl_add_u64 v[76:77], v[72:73], 0, v[136:137]
	v_cvt_pk_bf16_f32 v72, v68, v69
	s_waitcnt lgkmcnt(0)
	v_add_f32_e32 v68, v74, v75
	ds_bpermute_b32 v69, v153, v68
	v_cvt_pk_bf16_f32 v83, v78, v79
	v_cvt_pk_bf16_f32 v73, v70, v71
	v_cvt_pk_bf16_f32 v74, v64, v65
	v_cvt_pk_bf16_f32 v75, v66, v67
	global_store_dwordx4 v[76:77], v[82:85], off nt
	global_store_dwordx4 v[76:77], v[72:75], off offset:256 nt
	s_and_saveexec_b64 s[30:31], s[0:1]
	s_cbranch_execz .LBB0_1118
	s_waitcnt lgkmcnt(0)
	v_add_f32_e32 v66, v68, v69
	v_lshl_add_u64 v[64:65], v[80:81], 2, s[18:19]
	global_atomic_add_f32 v[64:65], v66, off
.LBB0_1118:
	s_or_b64 exec, exec, s[30:31]
	v_cvt_pk_bf16_f32 v66, v60, v61
	v_mul_f32_e32 v61, v61, v61
	v_fmac_f32_e32 v61, v60, v60
	v_mul_f32_e32 v60, v63, v63
	v_cvt_pk_bf16_f32 v68, v56, v57
	v_fmac_f32_e32 v60, v62, v62
	v_mul_f32_e32 v57, v57, v57
	v_add_f32_e32 v60, v61, v60
	v_fmac_f32_e32 v57, v56, v56
	v_add_f32_e32 v56, v57, v60
	v_mul_f32_e32 v57, v59, v59
	v_fmac_f32_e32 v57, v58, v58
	s_waitcnt lgkmcnt(0)
	v_cvt_pk_bf16_f32 v69, v58, v59
	v_add_f32_e32 v56, v57, v56
	v_mul_f32_e32 v57, v53, v53
	v_mul_f32_e32 v58, v55, v55
	v_fmac_f32_e32 v57, v52, v52
	v_fmac_f32_e32 v58, v54, v54
	v_add_f32_e32 v57, v57, v58
	v_mul_f32_e32 v58, v49, v49
	v_fmac_f32_e32 v58, v48, v48
	v_add_f32_e32 v57, v58, v57
	v_mul_f32_e32 v58, v51, v51
	v_fmac_f32_e32 v58, v50, v50
	v_add_f32_e32 v57, v58, v57
	v_add_u32_e32 v64, 0x80, v146
	v_add_f32_e32 v58, v57, v56
	v_ashrrev_i32_e32 v65, 31, v64
	ds_bpermute_b32 v59, v155, v58
	v_lshlrev_b64 v[70:71], 12, v[64:65]
	v_lshl_add_u64 v[70:71], s[6:7], 0, v[70:71]
	v_lshl_add_u64 v[70:71], s[28:29], 1, v[70:71]
	v_lshl_add_u64 v[56:57], v[70:71], 0, s[14:15]
	v_lshl_add_u64 v[60:61], v[56:57], 0, v[136:137]
	v_cvt_pk_bf16_f32 v56, v52, v53
	s_waitcnt lgkmcnt(0)
	v_add_f32_e32 v52, v58, v59
	ds_bpermute_b32 v53, v153, v52
	v_cvt_pk_bf16_f32 v67, v62, v63
	v_cvt_pk_bf16_f32 v57, v54, v55
	v_cvt_pk_bf16_f32 v58, v48, v49
	v_cvt_pk_bf16_f32 v59, v50, v51
	global_store_dwordx4 v[60:61], v[66:69], off nt
	global_store_dwordx4 v[60:61], v[56:59], off offset:256 nt
	s_and_saveexec_b64 s[30:31], s[0:1]
	s_cbranch_execz .LBB0_1120
	s_waitcnt lgkmcnt(0)
	v_add_f32_e32 v50, v52, v53
	v_lshl_add_u64 v[48:49], v[64:65], 2, s[18:19]
	global_atomic_add_f32 v[48:49], v50, off
; __device__ __forceinline__ unsigned cvtpk(float lo, float hi) { f32x2_t v = {lo, hi}; bf16x2_t b = __builtin_convertvector(v, bf16x2_t); return __builtin_bit_cast(unsigned, b); }
;     __device__ __forceinline__ void operator()(const pg8::f32x4 (&acc)[2][2][4][2], const pg8::Unit& u, int wr, int wc, int fr, int fq) const {
;     ...
;             for (int m = 0; m < 4; ++m) {
;                 const int row = u.pm * 256 + ai * 128 + wr * 64 + m * 16 + fr;
;                 float sq = 0.f;
; #pragma unroll
;                 for (int bj = 0; bj < 2; ++bj) {
;                     const size_t off = (size_t)row * DM + u.pn * 256 + bj * 128 + wc * 32 + 8 * fq;
;                     const pg8::f32x4 v0 = acc[ai][bj][m][0], v1 = acc[ai][bj][m][1];
;                     u32x4 w; w[0] = cvtpk(v0[0], v0[1]); w[1] = cvtpk(v0[2], v0[3]); w[2] = cvtpk(v1[0], v1[1]); w[3] = cvtpk(v1[2], v1[3]);
;                     *(u32x4*)(O + off) = w;
;                     sq += (v0[0] * v0[0] + v0[1] * v0[1]) + (v0[2] * v0[2] + v0[3] * v0[3]) + (v1[0] * v1[0] + v1[1] * v1[1]) + (v1[2] * v1[2] + v1[3] * v1[3]);
;                 }
;                 sq += __shfl_xor(sq, 16); sq += __shfl_xor(sq, 32);
;                 if (fq == 0) atomicAdd(ssout + row, sq);
;             }
.LBB0_1120:
	s_or_b64 exec, exec, s[30:31]
	v_cvt_pk_bf16_f32 v50, v44, v45
	v_mul_f32_e32 v45, v45, v45
	v_fmac_f32_e32 v45, v44, v44
	v_mul_f32_e32 v44, v47, v47
	v_cvt_pk_bf16_f32 v52, v40, v41
	v_fmac_f32_e32 v44, v46, v46
	v_mul_f32_e32 v41, v41, v41
	v_add_f32_e32 v44, v45, v44
	v_fmac_f32_e32 v41, v40, v40
	v_add_f32_e32 v40, v41, v44
	v_mul_f32_e32 v41, v43, v43
	v_fmac_f32_e32 v41, v42, v42
	s_waitcnt lgkmcnt(0)
	v_cvt_pk_bf16_f32 v53, v42, v43
	v_add_f32_e32 v40, v41, v40
	v_mul_f32_e32 v41, v37, v37
	v_mul_f32_e32 v42, v39, v39
	v_fmac_f32_e32 v41, v36, v36
	v_fmac_f32_e32 v42, v38, v38
	v_add_f32_e32 v41, v41, v42
	v_mul_f32_e32 v42, v33, v33
	v_fmac_f32_e32 v42, v32, v32
	v_add_f32_e32 v41, v42, v41
	v_mul_f32_e32 v42, v35, v35
	v_fmac_f32_e32 v42, v34, v34
	v_add_f32_e32 v41, v42, v41
	v_add_u32_e32 v48, 0x90, v146
	v_add_f32_e32 v42, v41, v40
	v_ashrrev_i32_e32 v49, 31, v48
	ds_bpermute_b32 v43, v155, v42
	v_lshlrev_b64 v[54:55], 12, v[48:49]
	v_lshl_add_u64 v[54:55], s[6:7], 0, v[54:55]
	v_lshl_add_u64 v[54:55], s[28:29], 1, v[54:55]
	v_lshl_add_u64 v[40:41], v[54:55], 0, s[14:15]
	v_lshl_add_u64 v[44:45], v[40:41], 0, v[136:137]
	v_cvt_pk_bf16_f32 v40, v36, v37
	s_waitcnt lgkmcnt(0)
	v_add_f32_e32 v36, v42, v43
	ds_bpermute_b32 v37, v153, v36
	v_cvt_pk_bf16_f32 v51, v46, v47
	v_cvt_pk_bf16_f32 v41, v38, v39
	v_cvt_pk_bf16_f32 v42, v32, v33
	v_cvt_pk_bf16_f32 v43, v34, v35
	global_store_dwordx4 v[44:45], v[50:53], off nt
	global_store_dwordx4 v[44:45], v[40:43], off offset:256 nt
	s_and_saveexec_b64 s[30:31], s[0:1]
	s_cbranch_execz .LBB0_1122
	s_waitcnt lgkmcnt(0)
	v_add_f32_e32 v34, v36, v37
	v_lshl_add_u64 v[32:33], v[48:49], 2, s[18:19]
	global_atomic_add_f32 v[32:33], v34, off
.LBB0_1122:
	s_or_b64 exec, exec, s[30:31]
	v_cvt_pk_bf16_f32 v34, v28, v29
	v_mul_f32_e32 v29, v29, v29
	v_fmac_f32_e32 v29, v28, v28
	v_mul_f32_e32 v28, v31, v31
	v_cvt_pk_bf16_f32 v36, v24, v25
	v_fmac_f32_e32 v28, v30, v30
	v_mul_f32_e32 v25, v25, v25
	v_add_f32_e32 v28, v29, v28
	v_fmac_f32_e32 v25, v24, v24
	v_add_f32_e32 v24, v25, v28
	v_mul_f32_e32 v25, v27, v27
	v_fmac_f32_e32 v25, v26, v26
	s_waitcnt lgkmcnt(0)
	v_cvt_pk_bf16_f32 v37, v26, v27
	v_add_f32_e32 v24, v25, v24
	v_mul_f32_e32 v25, v21, v21
	v_mul_f32_e32 v26, v23, v23
	v_fmac_f32_e32 v25, v20, v20
	v_fmac_f32_e32 v26, v22, v22
	v_add_f32_e32 v25, v25, v26
	v_mul_f32_e32 v26, v17, v17
	v_fmac_f32_e32 v26, v16, v16
	v_add_f32_e32 v25, v26, v25
	v_mul_f32_e32 v26, v19, v19
	v_fmac_f32_e32 v26, v18, v18
	v_add_f32_e32 v25, v26, v25
	v_add_u32_e32 v32, 0xa0, v146
	v_add_f32_e32 v26, v25, v24
	v_ashrrev_i32_e32 v33, 31, v32
	ds_bpermute_b32 v27, v155, v26
	v_lshlrev_b64 v[38:39], 12, v[32:33]
	v_lshl_add_u64 v[38:39], s[6:7], 0, v[38:39]
	v_lshl_add_u64 v[38:39], s[28:29], 1, v[38:39]
	v_lshl_add_u64 v[24:25], v[38:39], 0, s[14:15]
	v_lshl_add_u64 v[28:29], v[24:25], 0, v[136:137]
	v_cvt_pk_bf16_f32 v24, v20, v21
	s_waitcnt lgkmcnt(0)
	v_add_f32_e32 v20, v26, v27
	ds_bpermute_b32 v21, v153, v20
	v_cvt_pk_bf16_f32 v35, v30, v31
	v_cvt_pk_bf16_f32 v25, v22, v23
	v_cvt_pk_bf16_f32 v26, v16, v17
	v_cvt_pk_bf16_f32 v27, v18, v19
	global_store_dwordx4 v[28:29], v[34:37], off nt
	global_store_dwordx4 v[28:29], v[24:27], off offset:256 nt
	s_and_saveexec_b64 s[30:31], s[0:1]
	s_cbranch_execz .LBB0_1124
	s_waitcnt lgkmcnt(0)
	v_add_f32_e32 v18, v20, v21
	v_lshl_add_u64 v[16:17], v[32:33], 2, s[18:19]
	global_atomic_add_f32 v[16:17], v18, off
.LBB0_1124:
	s_or_b64 exec, exec, s[30:31]
	v_cvt_pk_bf16_f32 v18, v12, v13
	v_mul_f32_e32 v13, v13, v13
	v_fmac_f32_e32 v13, v12, v12
	v_mul_f32_e32 v12, v15, v15
	v_cvt_pk_bf16_f32 v20, v8, v9
	v_fmac_f32_e32 v12, v14, v14
	v_mul_f32_e32 v9, v9, v9
	v_add_f32_e32 v12, v13, v12
	v_fmac_f32_e32 v9, v8, v8
	v_add_f32_e32 v8, v9, v12
	v_mul_f32_e32 v9, v11, v11
	v_fmac_f32_e32 v9, v10, v10
	s_waitcnt lgkmcnt(0)
	v_cvt_pk_bf16_f32 v21, v10, v11
	v_add_f32_e32 v8, v9, v8
	v_mul_f32_e32 v9, v5, v5
	v_mul_f32_e32 v10, v7, v7
	v_fmac_f32_e32 v9, v4, v4
	v_fmac_f32_e32 v10, v6, v6
	v_add_f32_e32 v9, v9, v10
	v_mul_f32_e32 v10, v1, v1
	v_fmac_f32_e32 v10, v0, v0
	v_add_f32_e32 v9, v10, v9
	v_mul_f32_e32 v10, v3, v3
	v_fmac_f32_e32 v10, v2, v2
	v_add_f32_e32 v9, v10, v9
	v_add_u32_e32 v16, 0xb0, v146
	v_add_f32_e32 v10, v9, v8
	v_ashrrev_i32_e32 v17, 31, v16
	ds_bpermute_b32 v11, v155, v10
	v_lshlrev_b64 v[22:23], 12, v[16:17]
	v_lshl_add_u64 v[22:23], s[6:7], 0, v[22:23]
	v_lshl_add_u64 v[22:23], s[28:29], 1, v[22:23]
	v_lshl_add_u64 v[8:9], v[22:23], 0, s[14:15]
	v_lshl_add_u64 v[12:13], v[8:9], 0, v[136:137]
	v_cvt_pk_bf16_f32 v8, v4, v5
	s_waitcnt lgkmcnt(0)
	v_add_f32_e32 v4, v10, v11
	ds_bpermute_b32 v5, v153, v4
	v_cvt_pk_bf16_f32 v19, v14, v15
	v_cvt_pk_bf16_f32 v9, v6, v7
	v_cvt_pk_bf16_f32 v10, v0, v1
	v_cvt_pk_bf16_f32 v11, v2, v3
	global_store_dwordx4 v[12:13], v[18:21], off nt
	global_store_dwordx4 v[12:13], v[8:11], off offset:256 nt
	s_and_saveexec_b64 s[28:29], s[0:1]
	s_cbranch_execz .LBB0_1126
	s_waitcnt lgkmcnt(0)
	v_add_f32_e32 v2, v4, v5
	v_lshl_add_u64 v[0:1], v[16:17], 2, s[18:19]
	global_atomic_add_f32 v[0:1], v2, off

; __device__ __forceinline__ unsigned cvtpk(float lo, float hi) { f32x2_t v = {lo, hi}; bf16x2_t b = __builtin_convertvector(v, bf16x2_t); return __builtin_bit_cast(unsigned, b); }
;     __device__ __forceinline__ void operator()(const pg8::f32x4 (&acc)[2][2][4][2], const pg8::Unit& u, int wr, int wc, int fr, int fq) const {
;         const int row0 = u.pm * 256 + wr * 64 + fr, colb = u.pn * 256 + wc * 32 + 8 * fq;
; #pragma unroll
;         for (int ai = 0; ai < 2; ++ai) {
;             pg8::f32x4 rv[4][2][2];
; #pragma unroll
;             for (int m = 0; m < 4; ++m)
; #pragma unroll
;                 for (int bj = 0; bj < 2; ++bj) { const size_t off = (size_t)(row0 + ai * 128 + m * 16) * DM + colb + bj * 128;
;                     rv[m][bj][0] = *(const pg8::f32x4*)(R + off); rv[m][bj][1] = *(const pg8::f32x4*)(R + off + 4); }
; #pragma unroll
;             for (int m = 0; m < 4; ++m) {
;                 const int row = row0 + ai * 128 + m * 16;
;                 float sq = 0.f;
; #pragma unroll
;                 for (int bj = 0; bj < 2; ++bj) {
;                     const size_t off = (size_t)row * DM + colb + bj * 128;
;                     const pg8::f32x4 v0 = rv[m][bj][0] + acc[ai][bj][m][0] * alpha, v1 = rv[m][bj][1] + acc[ai][bj][m][1] * alpha;
;                     *(pg8::f32x4*)(X + off) = v0; *(pg8::f32x4*)(X + off + 4) = v1;
;                     u32x4 w; w[0] = cvtpk(v0[0], v0[1]); w[1] = cvtpk(v0[2], v0[3]); w[2] = cvtpk(v1[0], v1[1]); w[3] = cvtpk(v1[2], v1[3]);
;                     *(u32x4*)(XB + off) = w;
;                     sq += (v0[0] * v0[0] + v0[1] * v0[1]) + (v0[2] * v0[2] + v0[3] * v0[3]) + (v1[0] * v1[0] + v1[1] * v1[1]) + (v1[2] * v1[2] + v1[3] * v1[3]);
;                 }
;                 sq += __shfl_xor(sq, 16); sq += __shfl_xor(sq, 32);
;                 if (fq == 0) atomicAdd(ssout + row, sq);
.LBB0_1207:
	v_lshl_add_u32 v194, s42, 8, v210
	v_lshl_or_b32 v192, s43, 8, v212
	v_ashrrev_i32_e32 v193, 31, v192
	v_ashrrev_i32_e32 v195, 31, v194
	v_lshl_add_u64 v[196:197], v[192:193], 2, s[62:63]
	v_lshlrev_b64 v[128:129], 13, v[194:195]
	v_lshl_add_u64 v[238:239], v[196:197], 0, v[128:129]
	global_load_dwordx4 v[222:225], v[238:239], off nt
	global_load_dwordx4 v[226:229], v[238:239], off offset:16 nt
	global_load_dwordx4 v[230:233], v[238:239], off offset:512 nt
	global_load_dwordx4 v[234:237], v[238:239], off offset:528 nt
	v_or_b32_e32 v206, 16, v194
	v_or_b32_e32 v202, 32, v194
	v_or_b32_e32 v198, 48, v194
	v_ashrrev_i32_e32 v207, 31, v206
	v_ashrrev_i32_e32 v203, 31, v202
	v_ashrrev_i32_e32 v199, 31, v198
	v_lshlrev_b64 v[128:129], 13, v[206:207]
	v_lshlrev_b64 v[130:131], 13, v[202:203]
	v_lshlrev_b64 v[132:133], 13, v[198:199]
	v_lshl_add_u64 v[208:209], v[196:197], 0, v[128:129]
	v_lshl_add_u64 v[204:205], v[196:197], 0, v[130:131]
	v_lshl_add_u64 v[200:201], v[196:197], 0, v[132:133]
	global_load_dwordx4 v[168:171], v[208:209], off offset:16 nt
	global_load_dwordx4 v[172:175], v[208:209], off nt
	global_load_dwordx4 v[160:163], v[208:209], off offset:528 nt
	global_load_dwordx4 v[164:167], v[208:209], off offset:512 nt
	global_load_dwordx4 v[152:155], v[204:205], off offset:16 nt
	global_load_dwordx4 v[156:159], v[204:205], off nt
	global_load_dwordx4 v[144:147], v[204:205], off offset:528 nt
	global_load_dwordx4 v[148:151], v[204:205], off offset:512 nt
	global_load_dwordx4 v[136:139], v[200:201], off offset:16 nt
	global_load_dwordx4 v[140:143], v[200:201], off nt
	global_load_dwordx4 v[128:131], v[200:201], off offset:528 nt
	global_load_dwordx4 v[132:135], v[200:201], off offset:512 nt
	v_and_b32_e32 v218, 64, v216
	v_xor_b32_e32 v217, 16, v216
	v_add_u32_e32 v218, 64, v218
	v_xor_b32_e32 v219, 32, v216
	v_cmp_lt_i32_e32 vcc, v217, v218
	v_lshlrev_b64 v[240:241], 11, v[194:195]
	v_lshl_add_u64 v[240:241], v[240:241], 0, v[192:193]
	v_cndmask_b32_e32 v217, v216, v217, vcc
	v_cmp_lt_i32_e32 vcc, v219, v218
	v_lshlrev_b32_e32 v218, 2, v217
	v_lshlrev_b64 v[240:241], 1, v[240:241]
	v_cndmask_b32_e32 v219, v216, v219, vcc
	v_lshlrev_b32_e32 v217, 2, v219
	v_lshl_add_u64 v[242:243], s[80:81], 0, v[240:241]
	v_or_b32_e32 v240, 0x100, v240
	s_waitcnt vmcnt(0)
	v_pk_fma_f32 v[126:127], v[126:127], 0.5, v[224:225] op_sel_hi:[1,0,1]
	v_pk_fma_f32 v[124:125], v[124:125], 0.5, v[222:223] op_sel_hi:[1,0,1]
	v_pk_fma_f32 v[118:119], v[118:119], 0.5, v[232:233] op_sel_hi:[1,0,1]
	v_pk_fma_f32 v[116:117], v[116:117], 0.5, v[230:231] op_sel_hi:[1,0,1]
	v_pk_fma_f32 v[122:123], v[122:123], 0.5, v[228:229] op_sel_hi:[1,0,1]
	v_pk_fma_f32 v[120:121], v[120:121], 0.5, v[226:227] op_sel_hi:[1,0,1]
	v_pk_fma_f32 v[112:113], v[112:113], 0.5, v[234:235] op_sel_hi:[1,0,1]
	global_store_dwordx4 v[238:239], v[124:127], off nt
	global_store_dwordx4 v[238:239], v[120:123], off offset:16 nt
	v_cvt_pk_bf16_f32 v222, v124, v125
	v_cvt_pk_bf16_f32 v223, v126, v127
	v_mul_f32_e32 v125, v125, v125
	v_mul_f32_e32 v127, v127, v127
	v_mul_f32_e32 v219, v117, v117
	v_mul_f32_e32 v221, v119, v119
	v_pk_fma_f32 v[114:115], v[114:115], 0.5, v[236:237] op_sel_hi:[1,0,1]
	v_cvt_pk_bf16_f32 v224, v120, v121
	v_cvt_pk_bf16_f32 v225, v122, v123
	v_mul_f32_e32 v121, v121, v121
	v_mul_f32_e32 v123, v123, v123
	v_mul_f32_e32 v226, v113, v113
	v_fmac_f32_e32 v125, v124, v124
	v_fmac_f32_e32 v127, v126, v126
	v_fmac_f32_e32 v219, v116, v116
	v_fmac_f32_e32 v221, v118, v118
	v_mul_f32_e32 v227, v115, v115
	v_fmac_f32_e32 v121, v120, v120
	v_fmac_f32_e32 v123, v122, v122
	v_fmac_f32_e32 v226, v112, v112
	v_add_f32_e32 v120, v125, v127
	v_add_f32_e32 v122, v219, v221
	v_fmac_f32_e32 v227, v114, v114
	v_add_f32_e32 v120, v121, v120
	v_add_f32_e32 v121, v226, v122
	v_add_f32_e32 v120, v123, v120
	v_add_f32_e32 v121, v227, v121
	v_add_f32_e32 v120, v120, v121
	ds_bpermute_b32 v121, v218, v120
	global_store_dwordx4 v[242:243], v[222:225], off
	global_store_dwordx4 v[238:239], v[116:119], off offset:512 nt
	global_store_dwordx4 v[238:239], v[112:115], off offset:528 nt
	s_nop 0
	v_cvt_pk_bf16_f32 v116, v116, v117
	v_cvt_pk_bf16_f32 v117, v118, v119
	v_cvt_pk_bf16_f32 v118, v112, v113
	s_waitcnt lgkmcnt(0)
	v_add_f32_e32 v112, v120, v121
	ds_bpermute_b32 v113, v217, v112
	v_cvt_pk_bf16_f32 v119, v114, v115
	v_lshl_add_u64 v[114:115], s[80:81], 0, v[240:241]
	global_store_dwordx4 v[114:115], v[116:119], off
	s_and_saveexec_b64 s[20:21], s[0:1]
	s_cbranch_execz .LBB0_1209
	v_lshl_add_u64 v[114:115], v[194:195], 2, s[12:13]
	s_waitcnt lgkmcnt(0)
	v_add_f32_e32 v112, v112, v113
	global_atomic_add_f32 v[114:115], v112, off

; __device__ __forceinline__ unsigned cvtpk(float lo, float hi) { f32x2_t v = {lo, hi}; bf16x2_t b = __builtin_convertvector(v, bf16x2_t); return __builtin_bit_cast(unsigned, b); }
;     __device__ __forceinline__ void operator()(const pg8::f32x4 (&acc)[2][2][4][2], const pg8::Unit& u, int wr, int wc, int fr, int fq) const {
;     ...
;         for (int ai = 0; ai < 2; ++ai) {
;             pg8::f32x4 rv[4][2][2];
; #pragma unroll
;             for (int m = 0; m < 4; ++m)
; #pragma unroll
;                 for (int bj = 0; bj < 2; ++bj) { const size_t off = (size_t)(row0 + ai * 128 + m * 16) * DM + colb + bj * 128;
;                     rv[m][bj][0] = *(const pg8::f32x4*)(R + off); rv[m][bj][1] = *(const pg8::f32x4*)(R + off + 4); }
; #pragma unroll
;             for (int m = 0; m < 4; ++m) {
;                 const int row = row0 + ai * 128 + m * 16;
;                 float sq = 0.f;
; #pragma unroll
;                 for (int bj = 0; bj < 2; ++bj) {
;                     const size_t off = (size_t)row * DM + colb + bj * 128;
;                     const pg8::f32x4 v0 = rv[m][bj][0] + acc[ai][bj][m][0] * alpha, v1 = rv[m][bj][1] + acc[ai][bj][m][1] * alpha;
;                     *(pg8::f32x4*)(X + off) = v0; *(pg8::f32x4*)(X + off + 4) = v1;
;                     u32x4 w; w[0] = cvtpk(v0[0], v0[1]); w[1] = cvtpk(v0[2], v0[3]); w[2] = cvtpk(v1[0], v1[1]); w[3] = cvtpk(v1[2], v1[3]);
;                     *(u32x4*)(XB + off) = w;
;                     sq += (v0[0] * v0[0] + v0[1] * v0[1]) + (v0[2] * v0[2] + v0[3] * v0[3]) + (v1[0] * v1[0] + v1[1] * v1[1]) + (v1[2] * v1[2] + v1[3] * v1[3]);
;                 }
;                 sq += __shfl_xor(sq, 16); sq += __shfl_xor(sq, 32);
;                 if (fq == 0) atomicAdd(ssout + row, sq);
.LBB0_1215:
	s_or_b64 exec, exec, s[20:21]
	v_add_u32_e32 v124, 0x80, v194
	v_ashrrev_i32_e32 v125, 31, v124
	s_waitcnt lgkmcnt(0)
	v_lshlrev_b64 v[64:65], 13, v[124:125]
	v_lshl_add_u64 v[142:143], v[196:197], 0, v[64:65]
	global_load_dwordx4 v[126:129], v[142:143], off nt
	global_load_dwordx4 v[130:133], v[142:143], off offset:16 nt
	global_load_dwordx4 v[134:137], v[142:143], off offset:512 nt
	global_load_dwordx4 v[138:141], v[142:143], off offset:528 nt
	v_add_u32_e32 v120, 0x90, v194
	v_add_u32_e32 v116, 0xa0, v194
	v_add_u32_e32 v112, 0xb0, v194
	v_ashrrev_i32_e32 v121, 31, v120
	v_ashrrev_i32_e32 v117, 31, v116
	v_ashrrev_i32_e32 v113, 31, v112
	v_lshlrev_b64 v[64:65], 13, v[120:121]
	v_lshlrev_b64 v[66:67], 13, v[116:117]
	v_lshlrev_b64 v[68:69], 13, v[112:113]
	v_lshl_add_u64 v[122:123], v[196:197], 0, v[64:65]
	v_lshl_add_u64 v[118:119], v[196:197], 0, v[66:67]
	v_lshl_add_u64 v[114:115], v[196:197], 0, v[68:69]
	global_load_dwordx4 v[104:107], v[122:123], off offset:16 nt
	global_load_dwordx4 v[108:111], v[122:123], off nt
	global_load_dwordx4 v[96:99], v[122:123], off offset:528 nt
	global_load_dwordx4 v[100:103], v[122:123], off offset:512 nt
	global_load_dwordx4 v[88:91], v[118:119], off offset:16 nt
	global_load_dwordx4 v[92:95], v[118:119], off nt
	global_load_dwordx4 v[80:83], v[118:119], off offset:528 nt
	global_load_dwordx4 v[84:87], v[118:119], off offset:512 nt
	global_load_dwordx4 v[72:75], v[114:115], off offset:16 nt
	global_load_dwordx4 v[76:79], v[114:115], off nt
	global_load_dwordx4 v[64:67], v[114:115], off offset:528 nt
	global_load_dwordx4 v[68:71], v[114:115], off offset:512 nt
	v_lshlrev_b64 v[144:145], 11, v[124:125]
	v_lshl_add_u64 v[144:145], v[144:145], 0, v[192:193]
	v_lshlrev_b64 v[144:145], 1, v[144:145]
	v_lshl_add_u64 v[146:147], s[80:81], 0, v[144:145]
	v_or_b32_e32 v144, 0x100, v144
	s_waitcnt vmcnt(15)
	v_pk_fma_f32 v[62:63], v[62:63], 0.5, v[128:129] op_sel_hi:[1,0,1]
	v_pk_fma_f32 v[60:61], v[60:61], 0.5, v[126:127] op_sel_hi:[1,0,1]
	s_waitcnt vmcnt(13)
	v_pk_fma_f32 v[54:55], v[54:55], 0.5, v[136:137] op_sel_hi:[1,0,1]
	v_pk_fma_f32 v[52:53], v[52:53], 0.5, v[134:135] op_sel_hi:[1,0,1]
	v_pk_fma_f32 v[58:59], v[58:59], 0.5, v[132:133] op_sel_hi:[1,0,1]
	v_pk_fma_f32 v[56:57], v[56:57], 0.5, v[130:131] op_sel_hi:[1,0,1]
	s_waitcnt vmcnt(12)
	v_pk_fma_f32 v[48:49], v[48:49], 0.5, v[138:139] op_sel_hi:[1,0,1]
	global_store_dwordx4 v[142:143], v[60:63], off nt
	global_store_dwordx4 v[142:143], v[56:59], off offset:16 nt
	v_cvt_pk_bf16_f32 v126, v60, v61
	v_cvt_pk_bf16_f32 v127, v62, v63
	v_mul_f32_e32 v61, v61, v61
	v_mul_f32_e32 v63, v63, v63
	v_mul_f32_e32 v130, v53, v53
	v_mul_f32_e32 v131, v55, v55
	v_pk_fma_f32 v[50:51], v[50:51], 0.5, v[140:141] op_sel_hi:[1,0,1]
	v_cvt_pk_bf16_f32 v128, v56, v57
	v_cvt_pk_bf16_f32 v129, v58, v59
	v_mul_f32_e32 v57, v57, v57
	v_mul_f32_e32 v59, v59, v59
	v_mul_f32_e32 v132, v49, v49
	v_fmac_f32_e32 v61, v60, v60
	v_fmac_f32_e32 v63, v62, v62
	v_fmac_f32_e32 v130, v52, v52
	v_fmac_f32_e32 v131, v54, v54
	v_mul_f32_e32 v133, v51, v51
	v_fmac_f32_e32 v57, v56, v56
	v_fmac_f32_e32 v59, v58, v58
	v_fmac_f32_e32 v132, v48, v48
	v_add_f32_e32 v56, v61, v63
	v_add_f32_e32 v58, v130, v131
	v_fmac_f32_e32 v133, v50, v50
	v_add_f32_e32 v56, v57, v56
	v_add_f32_e32 v57, v132, v58
	v_add_f32_e32 v56, v59, v56
	v_add_f32_e32 v57, v133, v57
	v_add_f32_e32 v56, v56, v57
	ds_bpermute_b32 v57, v218, v56
	global_store_dwordx4 v[146:147], v[126:129], off
	global_store_dwordx4 v[142:143], v[52:55], off offset:512 nt
	global_store_dwordx4 v[142:143], v[48:51], off offset:528 nt
	s_nop 0
	v_cvt_pk_bf16_f32 v52, v52, v53
	v_cvt_pk_bf16_f32 v53, v54, v55
	v_cvt_pk_bf16_f32 v54, v48, v49
	s_waitcnt lgkmcnt(0)
	v_add_f32_e32 v48, v56, v57
	ds_bpermute_b32 v49, v217, v48
	v_cvt_pk_bf16_f32 v55, v50, v51
	v_lshl_add_u64 v[50:51], s[80:81], 0, v[144:145]
	global_store_dwordx4 v[50:51], v[52:55], off
	s_and_saveexec_b64 s[20:21], s[0:1]
	s_cbranch_execz .LBB0_1217
	v_lshl_add_u64 v[50:51], v[124:125], 2, s[12:13]
	s_waitcnt lgkmcnt(0)
	v_add_f32_e32 v48, v48, v49
	global_atomic_add_f32 v[50:51], v48, off

;     __device__ __forceinline__ void operator()(const pg8::f32x4 (&acc)[2][2][4][2], const pg8::Unit& u, int wr, int wc, int fr, int fq) const {
;     ...
;         for (int ai = 0; ai < 2; ++ai)
; #pragma unroll
;             for (int m = 0; m < 4; ++m) { s4[ai][m] = ss4[row0 + ai * 128 + m * 16]; sp[ai][m] = ssp[row0 + ai * 128 + m * 16]; }
; #pragma unroll
;         for (int bj = 0; bj < 2; ++bj) { gp[bj][0] = *(const pg8::f32x4*)(gpost + colb + bj * 128); gp[bj][1] = *(const pg8::f32x4*)(gpost + colb + bj * 128 + 4); }
; #pragma unroll
;         for (int ai = 0; ai < 2; ++ai)
; #pragma unroll
;             for (int mp = 0; mp < 2; ++mp) {
;                 pg8::f32x4 xv[2][2][2]; u32x4 pl[2][2];
; #pragma unroll
;                 for (int mm = 0; mm < 2; ++mm)
; #pragma unroll
;                     for (int bj = 0; bj < 2; ++bj) { const size_t off = (size_t)(row0 + ai * 128 + (2 * mp + mm) * 16) * DM + colb + bj * 128;
;                         xv[mm][bj][0] = *(const pg8::f32x4*)(X + off); xv[mm][bj][1] = *(const pg8::f32x4*)(X + off + 4); pl[mm][bj] = *(const u32x4*)(PLE + off); }
; #pragma unroll
;                 for (int mm = 0; mm < 2; ++mm) {
;                     const int m = 2 * mp + mm;
;                     const float rs = rsqrtf(s4[ai][m] * (1.f / DM) + EPS), rp = rsqrtf(sp[ai][m] * (1.f / DM) + EPS);
; #pragma unroll
;                     for (int bj = 0; bj < 2; ++bj) {
;                         const size_t off = (size_t)(row0 + ai * 128 + m * 16) * DM + colb + bj * 128;
;                         const u32x4 pw = pl[mm][bj];
;                         const pg8::f32x4 g0 = gp[bj][0], g1 = gp[bj][1];
;                         pg8::f32x4 x0 = xv[mm][bj][0], x1 = xv[mm][bj][1];
;                         const pg8::f32x4 a0 = acc[ai][bj][m][0] * rs, a1 = acc[ai][bj][m][1] * rs;
;                         x0[0] += sigm(a0[0]) * (bflo(pw[0]) * rp * g0[0]); x0[1] += sigm(a0[1]) * (bfhi(pw[0]) * rp * g0[1]);
;                         x0[2] += sigm(a0[2]) * (bflo(pw[1]) * rp * g0[2]); x0[3] += sigm(a0[3]) * (bfhi(pw[1]) * rp * g0[3]);
;                         x1[0] += sigm(a1[0]) * (bflo(pw[2]) * rp * g1[0]); x1[1] += sigm(a1[1]) * (bfhi(pw[2]) * rp * g1[1]);
;                         x1[2] += sigm(a1[2]) * (bflo(pw[3]) * rp * g1[2]); x1[3] += sigm(a1[3]) * (bfhi(pw[3]) * rp * g1[3]);
.LBB0_1298:
	v_lshl_add_u32 v56, s2, 8, v200
	v_ashrrev_i32_e32 v57, 31, v56
	v_lshlrev_b64 v[58:59], 2, v[56:57]
	v_lshl_add_u64 v[144:145], s[8:9], 0, v[58:59]
	v_lshl_add_u64 v[146:147], s[10:11], 0, v[58:59]
	global_load_dword v219, v[144:145], off
	global_load_dword v240, v[146:147], off
	v_lshl_or_b32 v190, s3, 8, v202
	v_ashrrev_i32_e32 v191, 31, v190
	v_lshlrev_b64 v[58:59], 11, v[56:57]
	v_lshl_add_u64 v[188:189], v[58:59], 0, v[190:191]
	v_lshlrev_b64 v[148:149], 1, v[188:189]
	v_lshl_add_u64 v[58:59], s[6:7], 0, v[148:149]
	global_load_dwordx4 v[220:223], v[58:59], off nt
	v_lshl_add_u64 v[64:65], v[190:191], 2, s[60:61]
	v_lshl_add_u64 v[198:199], v[188:189], 2, s[62:63]
	global_load_dwordx4 v[76:79], v[64:65], off nt
	global_load_dwordx4 v[72:75], v[64:65], off offset:16 nt
	global_load_dwordx4 v[224:227], v[198:199], off offset:16 nt
	global_load_dwordx4 v[228:231], v[198:199], off nt
	v_or_b32_e32 v150, 16, v56
	v_or_b32_e32 v194, 32, v56
	v_or_b32_e32 v192, 48, v56
	v_ashrrev_i32_e32 v151, 31, v150
	v_ashrrev_i32_e32 v195, 31, v194
	v_ashrrev_i32_e32 v193, 31, v192
	v_lshlrev_b64 v[152:153], 2, v[150:151]
	v_lshlrev_b64 v[154:155], 2, v[194:195]
	v_lshlrev_b64 v[156:157], 2, v[192:193]
	global_load_dwordx4 v[56:59], v[64:65], off offset:528 nt
	s_nop 0
	global_load_dwordx4 v[64:67], v[64:65], off offset:512 nt
	v_lshl_add_u64 v[158:159], s[8:9], 0, v[152:153]
	v_lshl_add_u64 v[152:153], s[10:11], 0, v[152:153]
	v_lshl_add_u64 v[160:161], s[8:9], 0, v[154:155]
	v_lshl_add_u64 v[154:155], s[10:11], 0, v[154:155]
	v_lshl_add_u64 v[162:163], s[8:9], 0, v[156:157]
	v_lshl_add_u64 v[156:157], s[10:11], 0, v[156:157]
	global_load_dword v214, v[144:145], off offset:512
	global_load_dword v213, v[146:147], off offset:512
	global_load_dword v212, v[144:145], off offset:576
	global_load_dword v211, v[146:147], off offset:576
	global_load_dword v210, v[144:145], off offset:640
	global_load_dword v207, v[144:145], off offset:704
	global_load_dword v209, v[146:147], off offset:640
	global_load_dword v243, v[158:159], off
	global_load_dword v246, v[152:153], off
	global_load_dword v218, v[160:161], off
	global_load_dword v217, v[154:155], off
	global_load_dword v216, v[162:163], off
	global_load_dword v215, v[156:157], off
	global_load_dword v208, v[146:147], off offset:704
	global_load_dwordx4 v[168:171], v[198:199], off offset:528 nt
	global_load_dwordx4 v[232:235], v[198:199], off offset:512 nt
	v_lshlrev_b64 v[150:151], 11, v[150:151]
	v_lshl_add_u64 v[144:145], v[150:151], 0, v[190:191]
	v_or_b32_e32 v148, 0x100, v148
	v_lshl_add_u64 v[196:197], v[144:145], 2, s[62:63]
	v_lshl_add_u64 v[148:149], s[6:7], 0, v[148:149]
	v_lshlrev_b64 v[150:151], 1, v[144:145]
	global_load_dwordx4 v[156:159], v[196:197], off offset:16 nt
	global_load_dwordx4 v[164:167], v[196:197], off nt
	global_load_dwordx4 v[144:147], v[196:197], off offset:528 nt
	global_load_dwordx4 v[152:155], v[196:197], off offset:512 nt
	global_load_dwordx4 v[236:239], v[148:149], off nt
	v_lshl_add_u64 v[160:161], s[6:7], 0, v[150:151]
	v_or_b32_e32 v150, 0x100, v150
	v_lshl_add_u64 v[148:149], s[6:7], 0, v[150:151]
	global_load_dwordx4 v[160:163], v[160:161], off nt
	s_nop 0
	global_load_dwordx4 v[148:151], v[148:149], off nt
	s_waitcnt vmcnt(0)
	v_fmamk_f32 v219, v219, 0x3a000000, v206
	v_mul_f32_e32 v241, 0x4b800000, v219
	v_cmp_gt_f32_e32 vcc, s51, v219
	v_fmamk_f32 v240, v240, 0x3a000000, v206
	v_mul_f32_e32 v242, 0x4b800000, v240
	v_cndmask_b32_e32 v219, v219, v241, vcc
	v_rsq_f32_e32 v219, v219
	v_cmp_gt_f32_e64 s[2:3], s51, v240
	v_and_b32_e32 v241, 0xffff0000, v220
	s_nop 0
	v_cndmask_b32_e64 v240, v240, v242, s[2:3]
	v_rsq_f32_e32 v242, v240
	v_lshlrev_b32_e32 v240, 16, v220
	v_mul_f32_e32 v220, 0x45800000, v219
	v_cndmask_b32_e32 v220, v219, v220, vcc
	v_pk_mul_f32 v[140:141], v[140:141], v[220:221] op_sel_hi:[1,0]
	v_pk_mul_f32 v[142:143], v[142:143], v[220:221] op_sel_hi:[1,0]
	v_mul_f32_e32 v140, 0xbfb8aa3b, v140
	v_mul_f32_e32 v141, 0xbfb8aa3b, v141
	v_exp_f32_e32 v140, v140
	v_exp_f32_e32 v141, v141
	v_mul_f32_e32 v142, 0xbfb8aa3b, v142
	v_mul_f32_e32 v143, 0xbfb8aa3b, v143
	v_add_f32_e32 v140, 1.0, v140
	v_add_f32_e32 v141, 1.0, v141
	v_mul_f32_e32 v244, 0x45800000, v242
	v_exp_f32_e32 v142, v142
	v_rcp_f32_e32 v140, v140
	v_rcp_f32_e32 v141, v141
	v_exp_f32_e32 v143, v143
	v_cndmask_b32_e64 v242, v242, v244, s[2:3]
	v_pk_mul_f32 v[244:245], v[138:139], v[220:221] op_sel_hi:[1,0]
	v_pk_mul_f32 v[138:139], v[136:137], v[220:221] op_sel_hi:[1,0]
	v_pk_mul_f32 v[136:137], v[242:243], v[240:241] op_sel_hi:[0,1]
	v_pk_mul_f32 v[136:137], v[76:77], v[136:137]
	v_mul_f32_e32 v138, 0xbfb8aa3b, v138
	v_add_f32_e32 v142, 1.0, v142
	v_pk_fma_f32 v[136:137], v[140:141], v[136:137], v[228:229]
	v_add_f32_e32 v141, 1.0, v143
	v_exp_f32_e32 v219, v138
	v_mul_f32_e32 v138, 0xbfb8aa3b, v139
	v_rcp_f32_e32 v140, v142
	v_rcp_f32_e32 v141, v141
	v_lshlrev_b32_e32 v142, 16, v221
	v_and_b32_e32 v143, 0xffff0000, v221
	v_exp_f32_e32 v221, v138
	v_pk_mul_f32 v[142:143], v[242:243], v[142:143] op_sel_hi:[0,1]
	v_pk_mul_f32 v[142:143], v[78:79], v[142:143]
	s_nop 0
	v_pk_fma_f32 v[138:139], v[140:141], v[142:143], v[230:231]
	v_add_f32_e32 v140, 1.0, v219
	v_add_f32_e32 v141, 1.0, v221
	v_mul_f32_e32 v219, 0xbfb8aa3b, v244
	v_mul_f32_e32 v221, 0xbfb8aa3b, v245
	v_rcp_f32_e32 v140, v140
	v_rcp_f32_e32 v141, v141
	v_exp_f32_e32 v219, v219
	v_exp_f32_e32 v221, v221
	v_lshlrev_b32_e32 v142, 16, v222
	v_and_b32_e32 v143, 0xffff0000, v222
	v_pk_mul_f32 v[142:143], v[242:243], v[142:143] op_sel_hi:[0,1]
	v_pk_mul_f32 v[142:143], v[72:73], v[142:143]
	v_lshlrev_b32_e32 v222, 16, v223
; __device__ __forceinline__ float bflo(unsigned w) { return __uint_as_float(w << 16); }
; __device__ __forceinline__ float bfhi(unsigned w) { return __uint_as_float(w & 0xffff0000u); }
; __device__ __forceinline__ float sigm(float x) { return __builtin_amdgcn_rcpf(1.f + __builtin_amdgcn_exp2f(-x * LOG2E)); }
;     __device__ __forceinline__ void operator()(const pg8::f32x4 (&acc)[2][2][4][2], const pg8::Unit& u, int wr, int wc, int fr, int fq) const {
;     ...
;                     for (int bj = 0; bj < 2; ++bj) {
;                         const size_t off = (size_t)(row0 + ai * 128 + m * 16) * DM + colb + bj * 128;
;                         const u32x4 pw = pl[mm][bj];
;                         const pg8::f32x4 g0 = gp[bj][0], g1 = gp[bj][1];
;                         pg8::f32x4 x0 = xv[mm][bj][0], x1 = xv[mm][bj][1];
;                         const pg8::f32x4 a0 = acc[ai][bj][m][0] * rs, a1 = acc[ai][bj][m][1] * rs;
;                         x0[0] += sigm(a0[0]) * (bflo(pw[0]) * rp * g0[0]); x0[1] += sigm(a0[1]) * (bfhi(pw[0]) * rp * g0[1]);
;                         x0[2] += sigm(a0[2]) * (bflo(pw[1]) * rp * g0[2]); x0[3] += sigm(a0[3]) * (bfhi(pw[1]) * rp * g0[3]);
;                         x1[0] += sigm(a1[0]) * (bflo(pw[2]) * rp * g1[0]); x1[1] += sigm(a1[1]) * (bfhi(pw[2]) * rp * g1[1]);
;                         x1[2] += sigm(a1[2]) * (bflo(pw[3]) * rp * g1[2]); x1[3] += sigm(a1[3]) * (bfhi(pw[3]) * rp * g1[3]);
;                         *(pg8::f32x4*)(X + off) = x0; *(pg8::f32x4*)(X + off + 4) = x1;
	v_pk_fma_f32 v[140:141], v[140:141], v[142:143], v[224:225]
	v_add_f32_e32 v142, 1.0, v219
	v_add_f32_e32 v143, 1.0, v221
	v_rcp_f32_e32 v142, v142
	v_rcp_f32_e32 v143, v143
	v_and_b32_e32 v223, 0xffff0000, v223
	v_pk_mul_f32 v[222:223], v[242:243], v[222:223] op_sel_hi:[0,1]
	v_pk_mul_f32 v[222:223], v[74:75], v[222:223]
	v_pk_mul_f32 v[132:133], v[132:133], v[220:221] op_sel_hi:[1,0]
	v_pk_fma_f32 v[142:143], v[142:143], v[222:223], v[226:227]
	global_store_dwordx4 v[198:199], v[136:139], off nt
	global_store_dwordx4 v[198:199], v[140:143], off offset:16 nt
	v_pk_mul_f32 v[134:135], v[134:135], v[220:221] op_sel_hi:[1,0]
	v_pk_mul_f32 v[136:137], v[130:131], v[220:221] op_sel_hi:[1,0]
	v_mul_f32_e32 v130, 0xbfb8aa3b, v132
	v_exp_f32_e32 v132, v130
	v_mul_f32_e32 v130, 0xbfb8aa3b, v133
	v_exp_f32_e32 v133, v130
	v_pk_mul_f32 v[130:131], v[128:129], v[220:221] op_sel_hi:[1,0]
	v_add_f32_e32 v128, 1.0, v132
	v_mul_f32_e32 v134, 0xbfb8aa3b, v134
	v_add_f32_e32 v129, 1.0, v133
	v_mul_f32_e32 v135, 0xbfb8aa3b, v135
	v_rcp_f32_e32 v128, v128
	v_rcp_f32_e32 v129, v129
	v_exp_f32_e32 v134, v134
	v_exp_f32_e32 v135, v135
	v_lshlrev_b32_e32 v132, 16, v236
	v_and_b32_e32 v133, 0xffff0000, v236
	v_pk_mul_f32 v[132:133], v[242:243], v[132:133] op_sel_hi:[0,1]
	v_pk_mul_f32 v[132:133], v[64:65], v[132:133]
	v_mul_f32_e32 v130, 0xbfb8aa3b, v130
	v_pk_fma_f32 v[128:129], v[128:129], v[132:133], v[232:233]
	v_add_f32_e32 v132, 1.0, v134
	v_add_f32_e32 v133, 1.0, v135
	v_exp_f32_e32 v138, v130
	v_mul_f32_e32 v130, 0xbfb8aa3b, v131
	v_rcp_f32_e32 v132, v132
	v_rcp_f32_e32 v133, v133
	v_exp_f32_e32 v139, v130
	v_lshlrev_b32_e32 v134, 16, v237
	v_and_b32_e32 v135, 0xffff0000, v237
	v_pk_mul_f32 v[134:135], v[242:243], v[134:135] op_sel_hi:[0,1]
	v_pk_mul_f32 v[134:135], v[66:67], v[134:135]
	v_mul_f32_e32 v136, 0xbfb8aa3b, v136
	v_pk_fma_f32 v[130:131], v[132:133], v[134:135], v[234:235]
	v_add_f32_e32 v132, 1.0, v138
	v_add_f32_e32 v133, 1.0, v139
	v_mul_f32_e32 v137, 0xbfb8aa3b, v137
	v_rcp_f32_e32 v132, v132
	v_rcp_f32_e32 v133, v133
	v_exp_f32_e32 v136, v136
	v_exp_f32_e32 v137, v137
	global_store_dwordx4 v[198:199], v[128:131], off offset:512 nt
	v_lshlrev_b32_e32 v134, 16, v238
	v_and_b32_e32 v135, 0xffff0000, v238
	v_fmamk_f32 v128, v243, 0x3a000000, v206
	v_mul_f32_e32 v129, 0x4b800000, v128
	v_cmp_gt_f32_e32 vcc, s51, v128
	v_pk_mul_f32 v[134:135], v[242:243], v[134:135] op_sel_hi:[0,1]
	v_pk_mul_f32 v[134:135], v[56:57], v[134:135]
	v_cndmask_b32_e32 v128, v128, v129, vcc
	v_fmamk_f32 v129, v246, 0x3a000000, v206
	v_rsq_f32_e32 v128, v128
	v_mul_f32_e32 v130, 0x4b800000, v129
	v_cmp_gt_f32_e64 s[2:3], s51, v129
	v_pk_fma_f32 v[132:133], v[132:133], v[134:135], v[168:169]
	v_add_f32_e32 v134, 1.0, v136
	v_add_f32_e32 v135, 1.0, v137
	v_cndmask_b32_e64 v129, v129, v130, s[2:3]
	v_rcp_f32_e32 v134, v134
	v_rcp_f32_e32 v135, v135
	v_rsq_f32_e32 v129, v129
	v_lshlrev_b32_e32 v136, 16, v239
	v_and_b32_e32 v137, 0xffff0000, v239
	v_pk_mul_f32 v[136:137], v[242:243], v[136:137] op_sel_hi:[0,1]
	v_mul_f32_e32 v130, 0x45800000, v128
	v_pk_mul_f32 v[136:137], v[58:59], v[136:137]
	v_cndmask_b32_e32 v128, v128, v130, vcc
	v_pk_fma_f32 v[134:135], v[134:135], v[136:137], v[170:171]
	v_pk_mul_f32 v[124:125], v[124:125], v[128:129] op_sel_hi:[1,0]
	global_store_dwordx4 v[198:199], v[132:135], off offset:528 nt
	v_pk_mul_f32 v[126:127], v[126:127], v[128:129] op_sel_hi:[1,0]
	v_mul_f32_e32 v130, 0x45800000, v129
	v_pk_mul_f32 v[132:133], v[122:123], v[128:129] op_sel_hi:[1,0]
	v_mul_f32_e32 v122, 0xbfb8aa3b, v124
	v_exp_f32_e32 v124, v122
	v_mul_f32_e32 v122, 0xbfb8aa3b, v125
	v_exp_f32_e32 v125, v122
	v_pk_mul_f32 v[122:123], v[120:121], v[128:129] op_sel_hi:[1,0]
	v_add_f32_e32 v120, 1.0, v124
	v_mul_f32_e32 v126, 0xbfb8aa3b, v126
	v_add_f32_e32 v121, 1.0, v125
	v_mul_f32_e32 v127, 0xbfb8aa3b, v127
	v_rcp_f32_e32 v120, v120
	v_rcp_f32_e32 v121, v121
	v_exp_f32_e32 v126, v126
	v_exp_f32_e32 v127, v127
	v_cndmask_b32_e64 v130, v129, v130, s[2:3]
	v_lshlrev_b32_e32 v124, 16, v160
	v_and_b32_e32 v125, 0xffff0000, v160
	v_pk_mul_f32 v[124:125], v[130:131], v[124:125] op_sel_hi:[0,1]
	v_pk_mul_f32 v[124:125], v[76:77], v[124:125]
	v_mul_f32_e32 v122, 0xbfb8aa3b, v122
	v_pk_fma_f32 v[120:121], v[120:121], v[124:125], v[164:165]
	v_add_f32_e32 v124, 1.0, v126
	v_add_f32_e32 v125, 1.0, v127
	v_rcp_f32_e32 v124, v124
	v_rcp_f32_e32 v125, v125
	v_lshlrev_b32_e32 v126, 16, v161
	v_and_b32_e32 v127, 0xffff0000, v161
	v_exp_f32_e32 v129, v122
	v_mul_f32_e32 v122, 0xbfb8aa3b, v123
	v_pk_mul_f32 v[126:127], v[130:131], v[126:127] op_sel_hi:[0,1]
	v_exp_f32_e32 v131, v122
	v_pk_mul_f32 v[126:127], v[78:79], v[126:127]
	s_nop 0
	v_pk_fma_f32 v[122:123], v[124:125], v[126:127], v[166:167]
	v_lshlrev_b32_e32 v126, 16, v162
	v_and_b32_e32 v127, 0xffff0000, v162
	v_add_f32_e32 v124, 1.0, v129
	v_add_f32_e32 v125, 1.0, v131
	v_pk_mul_f32 v[126:127], v[130:131], v[126:127] op_sel_hi:[0,1]
	v_mul_f32_e32 v129, 0xbfb8aa3b, v132
	v_mul_f32_e32 v131, 0xbfb8aa3b, v133
	v_rcp_f32_e32 v124, v124
	v_rcp_f32_e32 v125, v125
	v_exp_f32_e32 v129, v129
	v_exp_f32_e32 v131, v131
	v_pk_mul_f32 v[126:127], v[72:73], v[126:127]
	v_lshlrev_b32_e32 v132, 16, v163
	v_pk_fma_f32 v[124:125], v[124:125], v[126:127], v[156:157]
	v_add_f32_e32 v126, 1.0, v129
	v_add_f32_e32 v127, 1.0, v131
	v_rcp_f32_e32 v126, v126
	v_rcp_f32_e32 v127, v127
	v_and_b32_e32 v133, 0xffff0000, v163
	v_pk_mul_f32 v[132:133], v[130:131], v[132:133] op_sel_hi:[0,1]
	v_pk_mul_f32 v[132:133], v[74:75], v[132:133]
	v_pk_mul_f32 v[116:117], v[116:117], v[128:129] op_sel_hi:[1,0]
	v_pk_fma_f32 v[126:127], v[126:127], v[132:133], v[158:159]
; __device__ __forceinline__ float bflo(unsigned w) { return __uint_as_float(w << 16); }
; __device__ __forceinline__ float bfhi(unsigned w) { return __uint_as_float(w & 0xffff0000u); }
; __device__ __forceinline__ float sigm(float x) { return __builtin_amdgcn_rcpf(1.f + __builtin_amdgcn_exp2f(-x * LOG2E)); }
;     __device__ __forceinline__ void operator()(const pg8::f32x4 (&acc)[2][2][4][2], const pg8::Unit& u, int wr, int wc, int fr, int fq) const {
;     ...
;                     for (int bj = 0; bj < 2; ++bj) { const size_t off = (size_t)(row0 + ai * 128 + (2 * mp + mm) * 16) * DM + colb + bj * 128;
;                         xv[mm][bj][0] = *(const pg8::f32x4*)(X + off); xv[mm][bj][1] = *(const pg8::f32x4*)(X + off + 4); pl[mm][bj] = *(const u32x4*)(PLE + off); }
; #pragma unroll
;                 for (int mm = 0; mm < 2; ++mm) {
;                     const int m = 2 * mp + mm;
;                     const float rs = rsqrtf(s4[ai][m] * (1.f / DM) + EPS), rp = rsqrtf(sp[ai][m] * (1.f / DM) + EPS);
; #pragma unroll
;                     for (int bj = 0; bj < 2; ++bj) {
;                         const size_t off = (size_t)(row0 + ai * 128 + m * 16) * DM + colb + bj * 128;
;                         const u32x4 pw = pl[mm][bj];
;                         const pg8::f32x4 g0 = gp[bj][0], g1 = gp[bj][1];
;                         pg8::f32x4 x0 = xv[mm][bj][0], x1 = xv[mm][bj][1];
;                         const pg8::f32x4 a0 = acc[ai][bj][m][0] * rs, a1 = acc[ai][bj][m][1] * rs;
;                         x0[0] += sigm(a0[0]) * (bflo(pw[0]) * rp * g0[0]); x0[1] += sigm(a0[1]) * (bfhi(pw[0]) * rp * g0[1]);
;                         x0[2] += sigm(a0[2]) * (bflo(pw[1]) * rp * g0[2]); x0[3] += sigm(a0[3]) * (bfhi(pw[1]) * rp * g0[3]);
;                         x1[0] += sigm(a1[0]) * (bflo(pw[2]) * rp * g1[0]); x1[1] += sigm(a1[1]) * (bfhi(pw[2]) * rp * g1[1]);
;                         x1[2] += sigm(a1[2]) * (bflo(pw[3]) * rp * g1[2]); x1[3] += sigm(a1[3]) * (bfhi(pw[3]) * rp * g1[3]);
;                         *(pg8::f32x4*)(X + off) = x0; *(pg8::f32x4*)(X + off + 4) = x1;
	global_store_dwordx4 v[196:197], v[120:123], off nt
	global_store_dwordx4 v[196:197], v[124:127], off offset:16 nt
	v_pk_mul_f32 v[118:119], v[118:119], v[128:129] op_sel_hi:[1,0]
	v_pk_mul_f32 v[120:121], v[114:115], v[128:129] op_sel_hi:[1,0]
	v_mul_f32_e32 v114, 0xbfb8aa3b, v116
	v_exp_f32_e32 v116, v114
	v_mul_f32_e32 v114, 0xbfb8aa3b, v117
	v_exp_f32_e32 v117, v114
	v_pk_mul_f32 v[114:115], v[112:113], v[128:129] op_sel_hi:[1,0]
	v_add_f32_e32 v112, 1.0, v116
	v_mul_f32_e32 v118, 0xbfb8aa3b, v118
	v_add_f32_e32 v113, 1.0, v117
	v_mul_f32_e32 v119, 0xbfb8aa3b, v119
	v_rcp_f32_e32 v112, v112
	v_rcp_f32_e32 v113, v113
	v_exp_f32_e32 v118, v118
	v_exp_f32_e32 v119, v119
	v_lshlrev_b32_e32 v116, 16, v148
	v_and_b32_e32 v117, 0xffff0000, v148
	v_pk_mul_f32 v[116:117], v[130:131], v[116:117] op_sel_hi:[0,1]
	v_pk_mul_f32 v[116:117], v[64:65], v[116:117]
	v_mul_f32_e32 v114, 0xbfb8aa3b, v114
	v_pk_fma_f32 v[112:113], v[112:113], v[116:117], v[152:153]
	v_add_f32_e32 v116, 1.0, v118
	v_add_f32_e32 v117, 1.0, v119
	v_exp_f32_e32 v122, v114
	v_mul_f32_e32 v114, 0xbfb8aa3b, v115
	v_rcp_f32_e32 v116, v116
	v_rcp_f32_e32 v117, v117
	v_exp_f32_e32 v123, v114
	v_lshlrev_b32_e32 v118, 16, v149
	v_and_b32_e32 v119, 0xffff0000, v149
	v_pk_mul_f32 v[118:119], v[130:131], v[118:119] op_sel_hi:[0,1]
	v_pk_mul_f32 v[118:119], v[66:67], v[118:119]
	v_mul_f32_e32 v120, 0xbfb8aa3b, v120
	v_pk_fma_f32 v[114:115], v[116:117], v[118:119], v[154:155]
	v_add_f32_e32 v116, 1.0, v122
	v_add_f32_e32 v117, 1.0, v123
	v_mul_f32_e32 v121, 0xbfb8aa3b, v121
	v_rcp_f32_e32 v116, v116
	v_rcp_f32_e32 v117, v117
	v_exp_f32_e32 v120, v120
	v_exp_f32_e32 v121, v121
	v_lshlrev_b32_e32 v118, 16, v150
	v_and_b32_e32 v119, 0xffff0000, v150
	v_pk_mul_f32 v[118:119], v[130:131], v[118:119] op_sel_hi:[0,1]
	v_pk_mul_f32 v[118:119], v[56:57], v[118:119]
	v_fmamk_f32 v128, v218, 0x3a000000, v206
	v_pk_fma_f32 v[116:117], v[116:117], v[118:119], v[144:145]
	v_add_f32_e32 v118, 1.0, v120
	v_add_f32_e32 v119, 1.0, v121
	v_rcp_f32_e32 v118, v118
	v_rcp_f32_e32 v119, v119
	v_lshlrev_b32_e32 v120, 16, v151
	v_and_b32_e32 v121, 0xffff0000, v151
	v_pk_mul_f32 v[120:121], v[130:131], v[120:121] op_sel_hi:[0,1]
	v_pk_mul_f32 v[120:121], v[58:59], v[120:121]
	v_mul_f32_e32 v129, 0x4b800000, v128
	v_pk_fma_f32 v[118:119], v[118:119], v[120:121], v[146:147]
	global_store_dwordx4 v[196:197], v[112:115], off offset:512 nt
	global_store_dwordx4 v[196:197], v[116:119], off offset:528 nt
	v_cmp_gt_f32_e32 vcc, s51, v128
	v_lshlrev_b64 v[112:113], 11, v[194:195]
	v_lshl_add_u64 v[112:113], v[112:113], 0, v[190:191]
	v_lshlrev_b64 v[114:115], 1, v[112:113]
	v_lshl_add_u64 v[116:117], s[6:7], 0, v[114:115]
	global_load_dwordx4 v[140:143], v[116:117], off nt
	v_lshl_add_u64 v[138:139], v[112:113], 2, s[62:63]
	global_load_dwordx4 v[144:147], v[138:139], off nt
	global_load_dwordx4 v[148:151], v[138:139], off offset:16 nt
	global_load_dwordx4 v[152:155], v[138:139], off offset:528 nt
	global_load_dwordx4 v[156:159], v[138:139], off offset:512 nt
	v_or_b32_e32 v114, 0x100, v114
	v_lshl_add_u64 v[112:113], s[6:7], 0, v[114:115]
	global_load_dwordx4 v[160:163], v[112:113], off nt
	v_lshlrev_b64 v[112:113], 11, v[192:193]
	v_lshl_add_u64 v[112:113], v[112:113], 0, v[190:191]
	v_cndmask_b32_e32 v128, v128, v129, vcc
	v_lshlrev_b64 v[116:117], 1, v[112:113]
	v_rsq_f32_e32 v164, v128
	v_fmamk_f32 v128, v217, 0x3a000000, v206
	v_lshl_add_u64 v[118:119], s[6:7], 0, v[116:117]
	v_or_b32_e32 v116, 0x100, v116
	v_mul_f32_e32 v129, 0x4b800000, v128
	v_cmp_gt_f32_e64 s[2:3], s51, v128
	v_lshl_add_u64 v[136:137], v[112:113], 2, s[62:63]
	v_lshl_add_u64 v[116:117], s[6:7], 0, v[116:117]
	v_cndmask_b32_e64 v128, v128, v129, s[2:3]
	global_load_dwordx4 v[124:127], v[136:137], off offset:16 nt
	global_load_dwordx4 v[132:135], v[136:137], off nt
	global_load_dwordx4 v[112:115], v[136:137], off offset:528 nt
	global_load_dwordx4 v[120:123], v[136:137], off offset:512 nt
	v_rsq_f32_e32 v165, v128
	global_load_dwordx4 v[128:131], v[118:119], off nt
	s_nop 0
	global_load_dwordx4 v[116:119], v[116:117], off nt
	v_mul_f32_e32 v166, 0x45800000, v164
	v_cndmask_b32_e32 v164, v164, v166, vcc
	v_pk_mul_f32 v[108:109], v[108:109], v[164:165] op_sel_hi:[1,0]
	v_pk_mul_f32 v[168:169], v[106:107], v[164:165] op_sel_hi:[1,0]
	v_mul_f32_e32 v106, 0xbfb8aa3b, v108
	v_exp_f32_e32 v108, v106
	v_mul_f32_e32 v106, 0xbfb8aa3b, v109
	v_exp_f32_e32 v109, v106
	v_pk_mul_f32 v[110:111], v[110:111], v[164:165] op_sel_hi:[1,0]
	v_pk_mul_f32 v[106:107], v[104:105], v[164:165] op_sel_hi:[1,0]
	v_add_f32_e32 v104, 1.0, v108
	v_add_f32_e32 v105, 1.0, v109
	v_mul_f32_e32 v110, 0xbfb8aa3b, v110
	v_mul_f32_e32 v111, 0xbfb8aa3b, v111
	v_mul_f32_e32 v166, 0x45800000, v165
	v_rcp_f32_e32 v104, v104
	v_rcp_f32_e32 v105, v105
	v_exp_f32_e32 v110, v110
	v_exp_f32_e32 v111, v111
	v_cndmask_b32_e64 v166, v165, v166, s[2:3]
	v_mul_f32_e32 v106, 0xbfb8aa3b, v106
	v_pk_mul_f32 v[100:101], v[100:101], v[164:165] op_sel_hi:[1,0]
	v_pk_mul_f32 v[102:103], v[102:103], v[164:165] op_sel_hi:[1,0]
	s_waitcnt vmcnt(11)
	v_lshlrev_b32_e32 v108, 16, v140
	v_and_b32_e32 v109, 0xffff0000, v140
	v_pk_mul_f32 v[108:109], v[166:167], v[108:109] op_sel_hi:[0,1]
	v_pk_mul_f32 v[108:109], v[76:77], v[108:109]
	v_exp_f32_e32 v140, v106
	s_waitcnt vmcnt(10)
; __device__ __forceinline__ float bflo(unsigned w) { return __uint_as_float(w << 16); }
; __device__ __forceinline__ float bfhi(unsigned w) { return __uint_as_float(w & 0xffff0000u); }
; __device__ __forceinline__ float sigm(float x) { return __builtin_amdgcn_rcpf(1.f + __builtin_amdgcn_exp2f(-x * LOG2E)); }
;     __device__ __forceinline__ void operator()(const pg8::f32x4 (&acc)[2][2][4][2], const pg8::Unit& u, int wr, int wc, int fr, int fq) const {
;     ...
;                     for (int bj = 0; bj < 2; ++bj) {
;                         const size_t off = (size_t)(row0 + ai * 128 + m * 16) * DM + colb + bj * 128;
;                         const u32x4 pw = pl[mm][bj];
;                         const pg8::f32x4 g0 = gp[bj][0], g1 = gp[bj][1];
;                         pg8::f32x4 x0 = xv[mm][bj][0], x1 = xv[mm][bj][1];
;                         const pg8::f32x4 a0 = acc[ai][bj][m][0] * rs, a1 = acc[ai][bj][m][1] * rs;
;                         x0[0] += sigm(a0[0]) * (bflo(pw[0]) * rp * g0[0]); x0[1] += sigm(a0[1]) * (bfhi(pw[0]) * rp * g0[1]);
;                         x0[2] += sigm(a0[2]) * (bflo(pw[1]) * rp * g0[2]); x0[3] += sigm(a0[3]) * (bfhi(pw[1]) * rp * g0[3]);
;                         x1[0] += sigm(a1[0]) * (bflo(pw[2]) * rp * g1[0]); x1[1] += sigm(a1[1]) * (bfhi(pw[2]) * rp * g1[1]);
;                         x1[2] += sigm(a1[2]) * (bflo(pw[3]) * rp * g1[2]); x1[3] += sigm(a1[3]) * (bfhi(pw[3]) * rp * g1[3]);
;                         *(pg8::f32x4*)(X + off) = x0; *(pg8::f32x4*)(X + off + 4) = x1;
	v_pk_fma_f32 v[104:105], v[104:105], v[108:109], v[144:145]
	v_add_f32_e32 v108, 1.0, v110
	v_add_f32_e32 v109, 1.0, v111
	v_mul_f32_e32 v106, 0xbfb8aa3b, v107
	v_rcp_f32_e32 v108, v108
	v_rcp_f32_e32 v109, v109
	v_lshlrev_b32_e32 v110, 16, v141
	v_and_b32_e32 v111, 0xffff0000, v141
	v_exp_f32_e32 v141, v106
	v_pk_mul_f32 v[110:111], v[166:167], v[110:111] op_sel_hi:[0,1]
	v_pk_mul_f32 v[110:111], v[78:79], v[110:111]
	v_mul_f32_e32 v102, 0xbfb8aa3b, v102
	v_pk_fma_f32 v[106:107], v[108:109], v[110:111], v[146:147]
	v_add_f32_e32 v108, 1.0, v140
	v_add_f32_e32 v109, 1.0, v141
	v_mul_f32_e32 v140, 0xbfb8aa3b, v168
	v_mul_f32_e32 v141, 0xbfb8aa3b, v169
	v_rcp_f32_e32 v108, v108
	v_rcp_f32_e32 v109, v109
	v_exp_f32_e32 v140, v140
	v_exp_f32_e32 v141, v141
	v_lshlrev_b32_e32 v110, 16, v142
	v_and_b32_e32 v111, 0xffff0000, v142
	v_pk_mul_f32 v[110:111], v[166:167], v[110:111] op_sel_hi:[0,1]
	v_pk_mul_f32 v[110:111], v[72:73], v[110:111]
	v_mul_f32_e32 v103, 0xbfb8aa3b, v103
	s_waitcnt vmcnt(9)
	v_pk_fma_f32 v[108:109], v[108:109], v[110:111], v[148:149]
	v_add_f32_e32 v110, 1.0, v140
	v_add_f32_e32 v111, 1.0, v141
	v_rcp_f32_e32 v110, v110
	v_rcp_f32_e32 v111, v111
	v_lshlrev_b32_e32 v140, 16, v143
	v_and_b32_e32 v141, 0xffff0000, v143
	v_pk_mul_f32 v[140:141], v[166:167], v[140:141] op_sel_hi:[0,1]
	v_pk_mul_f32 v[140:141], v[74:75], v[140:141]
	v_exp_f32_e32 v102, v102
	v_pk_fma_f32 v[110:111], v[110:111], v[140:141], v[150:151]
	global_store_dwordx4 v[138:139], v[104:107], off nt
	global_store_dwordx4 v[138:139], v[108:111], off offset:16 nt
	v_exp_f32_e32 v103, v103
	v_pk_mul_f32 v[104:105], v[98:99], v[164:165] op_sel_hi:[1,0]
	v_mul_f32_e32 v98, 0xbfb8aa3b, v100
	v_exp_f32_e32 v100, v98
	v_mul_f32_e32 v98, 0xbfb8aa3b, v101
	v_exp_f32_e32 v101, v98
	v_pk_mul_f32 v[98:99], v[96:97], v[164:165] op_sel_hi:[1,0]
	v_add_f32_e32 v96, 1.0, v100
	v_rcp_f32_e32 v96, v96
	v_add_f32_e32 v97, 1.0, v101
	v_rcp_f32_e32 v97, v97
	s_waitcnt vmcnt(8)
	v_lshlrev_b32_e32 v100, 16, v160
	v_and_b32_e32 v101, 0xffff0000, v160
	v_pk_mul_f32 v[100:101], v[166:167], v[100:101] op_sel_hi:[0,1]
	v_pk_mul_f32 v[100:101], v[64:65], v[100:101]
	v_mul_f32_e32 v98, 0xbfb8aa3b, v98
	v_pk_fma_f32 v[96:97], v[96:97], v[100:101], v[156:157]
	v_add_f32_e32 v100, 1.0, v102
	v_add_f32_e32 v101, 1.0, v103
	v_exp_f32_e32 v106, v98
	v_mul_f32_e32 v98, 0xbfb8aa3b, v99
	v_rcp_f32_e32 v100, v100
	v_rcp_f32_e32 v101, v101
	v_exp_f32_e32 v107, v98
	v_lshlrev_b32_e32 v102, 16, v161
	v_and_b32_e32 v103, 0xffff0000, v161
	v_pk_mul_f32 v[102:103], v[166:167], v[102:103] op_sel_hi:[0,1]
	v_pk_mul_f32 v[102:103], v[66:67], v[102:103]
	v_mul_f32_e32 v104, 0xbfb8aa3b, v104
	v_pk_fma_f32 v[98:99], v[100:101], v[102:103], v[158:159]
	v_add_f32_e32 v100, 1.0, v106
	v_add_f32_e32 v101, 1.0, v107
	v_mul_f32_e32 v105, 0xbfb8aa3b, v105
	v_rcp_f32_e32 v100, v100
	v_rcp_f32_e32 v101, v101
	v_exp_f32_e32 v104, v104
	v_exp_f32_e32 v105, v105
	global_store_dwordx4 v[138:139], v[96:99], off offset:512 nt
	v_lshlrev_b32_e32 v102, 16, v162
	v_and_b32_e32 v103, 0xffff0000, v162
	v_fmamk_f32 v96, v216, 0x3a000000, v206
	v_mul_f32_e32 v97, 0x4b800000, v96
	v_cmp_gt_f32_e32 vcc, s51, v96
	v_pk_mul_f32 v[102:103], v[166:167], v[102:103] op_sel_hi:[0,1]
	v_pk_mul_f32 v[102:103], v[56:57], v[102:103]
	v_cndmask_b32_e32 v96, v96, v97, vcc
	v_fmamk_f32 v97, v215, 0x3a000000, v206
	v_rsq_f32_e32 v96, v96
	v_mul_f32_e32 v98, 0x4b800000, v97
	v_cmp_gt_f32_e64 s[2:3], s51, v97
	v_pk_fma_f32 v[100:101], v[100:101], v[102:103], v[152:153]
	v_add_f32_e32 v102, 1.0, v104
	v_add_f32_e32 v103, 1.0, v105
	v_cndmask_b32_e64 v97, v97, v98, s[2:3]
	v_rcp_f32_e32 v102, v102
	v_rcp_f32_e32 v103, v103
	v_rsq_f32_e32 v97, v97
	v_lshlrev_b32_e32 v104, 16, v163
	v_and_b32_e32 v105, 0xffff0000, v163
	v_pk_mul_f32 v[104:105], v[166:167], v[104:105] op_sel_hi:[0,1]
	v_mul_f32_e32 v98, 0x45800000, v96
	v_pk_mul_f32 v[104:105], v[58:59], v[104:105]
	v_cndmask_b32_e32 v96, v96, v98, vcc
	v_pk_fma_f32 v[102:103], v[102:103], v[104:105], v[154:155]
	v_pk_mul_f32 v[92:93], v[92:93], v[96:97] op_sel_hi:[1,0]
	global_store_dwordx4 v[138:139], v[100:103], off offset:528 nt
	v_pk_mul_f32 v[94:95], v[94:95], v[96:97] op_sel_hi:[1,0]
	v_mul_f32_e32 v98, 0x45800000, v97
	v_pk_mul_f32 v[100:101], v[90:91], v[96:97] op_sel_hi:[1,0]
	v_mul_f32_e32 v90, 0xbfb8aa3b, v92
	v_exp_f32_e32 v92, v90
	v_mul_f32_e32 v90, 0xbfb8aa3b, v93
	v_exp_f32_e32 v93, v90
	v_pk_mul_f32 v[90:91], v[88:89], v[96:97] op_sel_hi:[1,0]
	v_add_f32_e32 v88, 1.0, v92
	v_mul_f32_e32 v94, 0xbfb8aa3b, v94
	v_add_f32_e32 v89, 1.0, v93
	v_mul_f32_e32 v95, 0xbfb8aa3b, v95
	v_rcp_f32_e32 v88, v88
	v_rcp_f32_e32 v89, v89
	v_exp_f32_e32 v94, v94
	v_exp_f32_e32 v95, v95
	v_cndmask_b32_e64 v98, v97, v98, s[2:3]
	s_waitcnt vmcnt(5)
; __device__ __forceinline__ float bflo(unsigned w) { return __uint_as_float(w << 16); }
; __device__ __forceinline__ float bfhi(unsigned w) { return __uint_as_float(w & 0xffff0000u); }
; __device__ __forceinline__ float sigm(float x) { return __builtin_amdgcn_rcpf(1.f + __builtin_amdgcn_exp2f(-x * LOG2E)); }
;     __device__ __forceinline__ void operator()(const pg8::f32x4 (&acc)[2][2][4][2], const pg8::Unit& u, int wr, int wc, int fr, int fq) const {
;     ...
;                     for (int bj = 0; bj < 2; ++bj) { const size_t off = (size_t)(row0 + ai * 128 + (2 * mp + mm) * 16) * DM + colb + bj * 128;
;                         xv[mm][bj][0] = *(const pg8::f32x4*)(X + off); xv[mm][bj][1] = *(const pg8::f32x4*)(X + off + 4); pl[mm][bj] = *(const u32x4*)(PLE + off); }
; #pragma unroll
;                 for (int mm = 0; mm < 2; ++mm) {
;                     const int m = 2 * mp + mm;
;                     const float rs = rsqrtf(s4[ai][m] * (1.f / DM) + EPS), rp = rsqrtf(sp[ai][m] * (1.f / DM) + EPS);
; #pragma unroll
;                     for (int bj = 0; bj < 2; ++bj) {
;                         const size_t off = (size_t)(row0 + ai * 128 + m * 16) * DM + colb + bj * 128;
;                         const u32x4 pw = pl[mm][bj];
;                         const pg8::f32x4 g0 = gp[bj][0], g1 = gp[bj][1];
;                         pg8::f32x4 x0 = xv[mm][bj][0], x1 = xv[mm][bj][1];
;                         const pg8::f32x4 a0 = acc[ai][bj][m][0] * rs, a1 = acc[ai][bj][m][1] * rs;
;                         x0[0] += sigm(a0[0]) * (bflo(pw[0]) * rp * g0[0]); x0[1] += sigm(a0[1]) * (bfhi(pw[0]) * rp * g0[1]);
;                         x0[2] += sigm(a0[2]) * (bflo(pw[1]) * rp * g0[2]); x0[3] += sigm(a0[3]) * (bfhi(pw[1]) * rp * g0[3]);
;                         x1[0] += sigm(a1[0]) * (bflo(pw[2]) * rp * g1[0]); x1[1] += sigm(a1[1]) * (bfhi(pw[2]) * rp * g1[1]);
;                         x1[2] += sigm(a1[2]) * (bflo(pw[3]) * rp * g1[2]); x1[3] += sigm(a1[3]) * (bfhi(pw[3]) * rp * g1[3]);
;                         *(pg8::f32x4*)(X + off) = x0; *(pg8::f32x4*)(X + off + 4) = x1;
	v_lshlrev_b32_e32 v92, 16, v128
	v_and_b32_e32 v93, 0xffff0000, v128
	v_pk_mul_f32 v[92:93], v[98:99], v[92:93] op_sel_hi:[0,1]
	v_pk_mul_f32 v[92:93], v[76:77], v[92:93]
	v_mul_f32_e32 v90, 0xbfb8aa3b, v90
	v_pk_fma_f32 v[88:89], v[88:89], v[92:93], v[132:133]
	v_add_f32_e32 v92, 1.0, v94
	v_add_f32_e32 v93, 1.0, v95
	v_rcp_f32_e32 v92, v92
	v_rcp_f32_e32 v93, v93
	v_lshlrev_b32_e32 v94, 16, v129
	v_and_b32_e32 v95, 0xffff0000, v129
	v_exp_f32_e32 v97, v90
	v_mul_f32_e32 v90, 0xbfb8aa3b, v91
	v_pk_mul_f32 v[94:95], v[98:99], v[94:95] op_sel_hi:[0,1]
	v_exp_f32_e32 v99, v90
	v_pk_mul_f32 v[94:95], v[78:79], v[94:95]
	s_nop 0
	v_pk_fma_f32 v[90:91], v[92:93], v[94:95], v[134:135]
	v_lshlrev_b32_e32 v94, 16, v130
	v_and_b32_e32 v95, 0xffff0000, v130
	v_add_f32_e32 v92, 1.0, v97
	v_add_f32_e32 v93, 1.0, v99
	v_pk_mul_f32 v[94:95], v[98:99], v[94:95] op_sel_hi:[0,1]
	v_mul_f32_e32 v97, 0xbfb8aa3b, v100
	v_mul_f32_e32 v99, 0xbfb8aa3b, v101
	v_rcp_f32_e32 v92, v92
	v_rcp_f32_e32 v93, v93
	v_exp_f32_e32 v97, v97
	v_exp_f32_e32 v99, v99
	v_pk_mul_f32 v[94:95], v[72:73], v[94:95]
	v_lshlrev_b32_e32 v100, 16, v131
	v_pk_fma_f32 v[92:93], v[92:93], v[94:95], v[124:125]
	v_add_f32_e32 v94, 1.0, v97
	v_add_f32_e32 v95, 1.0, v99
	v_rcp_f32_e32 v94, v94
	v_rcp_f32_e32 v95, v95
	v_and_b32_e32 v101, 0xffff0000, v131
	v_pk_mul_f32 v[100:101], v[98:99], v[100:101] op_sel_hi:[0,1]
	v_pk_mul_f32 v[100:101], v[74:75], v[100:101]
	v_pk_mul_f32 v[84:85], v[84:85], v[96:97] op_sel_hi:[1,0]
	v_pk_fma_f32 v[94:95], v[94:95], v[100:101], v[126:127]
	global_store_dwordx4 v[136:137], v[88:91], off nt
	global_store_dwordx4 v[136:137], v[92:95], off offset:16 nt
	v_pk_mul_f32 v[86:87], v[86:87], v[96:97] op_sel_hi:[1,0]
	v_pk_mul_f32 v[88:89], v[82:83], v[96:97] op_sel_hi:[1,0]
	v_mul_f32_e32 v82, 0xbfb8aa3b, v84
	v_exp_f32_e32 v84, v82
	v_mul_f32_e32 v82, 0xbfb8aa3b, v85
	v_exp_f32_e32 v85, v82
	v_pk_mul_f32 v[82:83], v[80:81], v[96:97] op_sel_hi:[1,0]
	v_add_f32_e32 v80, 1.0, v84
	v_mul_f32_e32 v86, 0xbfb8aa3b, v86
	v_add_f32_e32 v81, 1.0, v85
	v_mul_f32_e32 v87, 0xbfb8aa3b, v87
	v_rcp_f32_e32 v80, v80
	v_rcp_f32_e32 v81, v81
	v_exp_f32_e32 v86, v86
	v_exp_f32_e32 v87, v87
	s_waitcnt vmcnt(6)
	v_lshlrev_b32_e32 v84, 16, v116
	v_and_b32_e32 v85, 0xffff0000, v116
	v_pk_mul_f32 v[84:85], v[98:99], v[84:85] op_sel_hi:[0,1]
	v_pk_mul_f32 v[84:85], v[64:65], v[84:85]
	v_mul_f32_e32 v82, 0xbfb8aa3b, v82
	v_pk_fma_f32 v[80:81], v[80:81], v[84:85], v[120:121]
	v_add_f32_e32 v84, 1.0, v86
	v_add_f32_e32 v85, 1.0, v87
	v_exp_f32_e32 v90, v82
	v_mul_f32_e32 v82, 0xbfb8aa3b, v83
	v_rcp_f32_e32 v84, v84
	v_rcp_f32_e32 v85, v85
	v_exp_f32_e32 v91, v82
	v_lshlrev_b32_e32 v86, 16, v117
	v_and_b32_e32 v87, 0xffff0000, v117
	v_pk_mul_f32 v[86:87], v[98:99], v[86:87] op_sel_hi:[0,1]
	v_pk_mul_f32 v[86:87], v[66:67], v[86:87]
	v_mul_f32_e32 v88, 0xbfb8aa3b, v88
	v_pk_fma_f32 v[82:83], v[84:85], v[86:87], v[122:123]
	v_add_f32_e32 v84, 1.0, v90
	v_add_f32_e32 v85, 1.0, v91
	v_mul_f32_e32 v89, 0xbfb8aa3b, v89
	v_rcp_f32_e32 v84, v84
	v_rcp_f32_e32 v85, v85
	v_exp_f32_e32 v88, v88
	v_exp_f32_e32 v89, v89
	v_lshlrev_b32_e32 v86, 16, v118
	v_and_b32_e32 v87, 0xffff0000, v118
	v_pk_mul_f32 v[86:87], v[98:99], v[86:87] op_sel_hi:[0,1]
	v_pk_mul_f32 v[86:87], v[56:57], v[86:87]
	v_fmamk_f32 v96, v214, 0x3a000000, v206
	v_pk_fma_f32 v[84:85], v[84:85], v[86:87], v[112:113]
	v_add_f32_e32 v86, 1.0, v88
	v_add_f32_e32 v87, 1.0, v89
	v_rcp_f32_e32 v86, v86
	v_rcp_f32_e32 v87, v87
	v_lshlrev_b32_e32 v88, 16, v119
	v_and_b32_e32 v89, 0xffff0000, v119
	v_pk_mul_f32 v[88:89], v[98:99], v[88:89] op_sel_hi:[0,1]
	v_pk_mul_f32 v[88:89], v[58:59], v[88:89]
	v_mul_f32_e32 v97, 0x4b800000, v96
	v_pk_fma_f32 v[86:87], v[86:87], v[88:89], v[114:115]
	global_store_dwordx4 v[136:137], v[80:83], off offset:512 nt
	global_store_dwordx4 v[136:137], v[84:87], off offset:528 nt
	v_cmp_gt_f32_e32 vcc, s51, v96
	v_lshl_add_u64 v[80:81], v[188:189], 0, s[14:15]
	v_lshlrev_b64 v[82:83], 1, v[80:81]
	v_lshl_add_u64 v[84:85], s[6:7], 0, v[82:83]
	global_load_dwordx4 v[108:111], v[84:85], off nt
	v_lshl_add_u64 v[106:107], v[80:81], 2, s[62:63]
	global_load_dwordx4 v[112:115], v[106:107], off nt
	global_load_dwordx4 v[116:119], v[106:107], off offset:16 nt
	global_load_dwordx4 v[120:123], v[106:107], off offset:528 nt
	global_load_dwordx4 v[124:127], v[106:107], off offset:512 nt
	v_or_b32_e32 v82, 0x100, v82
	v_lshl_add_u64 v[80:81], s[6:7], 0, v[82:83]
	global_load_dwordx4 v[128:131], v[80:81], off nt
	v_lshl_add_u64 v[80:81], v[188:189], 0, s[18:19]
	v_cndmask_b32_e32 v96, v96, v97, vcc
	v_lshlrev_b64 v[84:85], 1, v[80:81]
	v_rsq_f32_e32 v132, v96
	v_fmamk_f32 v96, v213, 0x3a000000, v206
	v_lshl_add_u64 v[86:87], s[6:7], 0, v[84:85]
	v_or_b32_e32 v84, 0x100, v84
	v_mul_f32_e32 v97, 0x4b800000, v96
	v_cmp_gt_f32_e64 s[2:3], s51, v96
	v_lshl_add_u64 v[104:105], v[80:81], 2, s[62:63]
	v_lshl_add_u64 v[84:85], s[6:7], 0, v[84:85]
	v_cndmask_b32_e64 v96, v96, v97, s[2:3]
	global_load_dwordx4 v[92:95], v[104:105], off offset:16 nt
	global_load_dwordx4 v[100:103], v[104:105], off nt
	global_load_dwordx4 v[80:83], v[104:105], off offset:528 nt
	global_load_dwordx4 v[88:91], v[104:105], off offset:512 nt
	v_rsq_f32_e32 v133, v96
	global_load_dwordx4 v[96:99], v[86:87], off nt
	s_nop 0
	global_load_dwordx4 v[84:87], v[84:85], off nt
	v_mul_f32_e32 v134, 0x45800000, v132
	v_cndmask_b32_e32 v132, v132, v134, vcc
	v_pk_mul_f32 v[68:69], v[68:69], v[132:133] op_sel_hi:[1,0]
	v_pk_mul_f32 v[136:137], v[62:63], v[132:133] op_sel_hi:[1,0]
	v_mul_f32_e32 v62, 0xbfb8aa3b, v68
	v_exp_f32_e32 v68, v62
	v_mul_f32_e32 v62, 0xbfb8aa3b, v69
	v_exp_f32_e32 v69, v62
	v_pk_mul_f32 v[70:71], v[70:71], v[132:133] op_sel_hi:[1,0]
	v_pk_mul_f32 v[62:63], v[60:61], v[132:133] op_sel_hi:[1,0]
	v_add_f32_e32 v60, 1.0, v68
	v_add_f32_e32 v61, 1.0, v69
	v_mul_f32_e32 v70, 0xbfb8aa3b, v70
	v_mul_f32_e32 v71, 0xbfb8aa3b, v71
	v_mul_f32_e32 v134, 0x45800000, v133
	v_rcp_f32_e32 v60, v60
	v_rcp_f32_e32 v61, v61
	v_exp_f32_e32 v70, v70
	v_exp_f32_e32 v71, v71
	v_cndmask_b32_e64 v134, v133, v134, s[2:3]
	v_mul_f32_e32 v62, 0xbfb8aa3b, v62
	v_pk_mul_f32 v[52:53], v[52:53], v[132:133] op_sel_hi:[1,0]
	v_pk_mul_f32 v[54:55], v[54:55], v[132:133] op_sel_hi:[1,0]
	s_waitcnt vmcnt(11)
; __device__ __forceinline__ float bflo(unsigned w) { return __uint_as_float(w << 16); }
; __device__ __forceinline__ float bfhi(unsigned w) { return __uint_as_float(w & 0xffff0000u); }
; __device__ __forceinline__ float sigm(float x) { return __builtin_amdgcn_rcpf(1.f + __builtin_amdgcn_exp2f(-x * LOG2E)); }
;     __device__ __forceinline__ void operator()(const pg8::f32x4 (&acc)[2][2][4][2], const pg8::Unit& u, int wr, int wc, int fr, int fq) const {
;     ...
;                     const float rs = rsqrtf(s4[ai][m] * (1.f / DM) + EPS), rp = rsqrtf(sp[ai][m] * (1.f / DM) + EPS);
; #pragma unroll
;                     for (int bj = 0; bj < 2; ++bj) {
;                         const size_t off = (size_t)(row0 + ai * 128 + m * 16) * DM + colb + bj * 128;
;                         const u32x4 pw = pl[mm][bj];
;                         const pg8::f32x4 g0 = gp[bj][0], g1 = gp[bj][1];
;                         pg8::f32x4 x0 = xv[mm][bj][0], x1 = xv[mm][bj][1];
;                         const pg8::f32x4 a0 = acc[ai][bj][m][0] * rs, a1 = acc[ai][bj][m][1] * rs;
;                         x0[0] += sigm(a0[0]) * (bflo(pw[0]) * rp * g0[0]); x0[1] += sigm(a0[1]) * (bfhi(pw[0]) * rp * g0[1]);
;                         x0[2] += sigm(a0[2]) * (bflo(pw[1]) * rp * g0[2]); x0[3] += sigm(a0[3]) * (bfhi(pw[1]) * rp * g0[3]);
;                         x1[0] += sigm(a1[0]) * (bflo(pw[2]) * rp * g1[0]); x1[1] += sigm(a1[1]) * (bfhi(pw[2]) * rp * g1[1]);
;                         x1[2] += sigm(a1[2]) * (bflo(pw[3]) * rp * g1[2]); x1[3] += sigm(a1[3]) * (bfhi(pw[3]) * rp * g1[3]);
;                         *(pg8::f32x4*)(X + off) = x0; *(pg8::f32x4*)(X + off + 4) = x1;
	v_lshlrev_b32_e32 v68, 16, v108
	v_and_b32_e32 v69, 0xffff0000, v108
	v_pk_mul_f32 v[68:69], v[134:135], v[68:69] op_sel_hi:[0,1]
	v_pk_mul_f32 v[68:69], v[76:77], v[68:69]
	v_exp_f32_e32 v108, v62
	s_waitcnt vmcnt(10)
	v_pk_fma_f32 v[60:61], v[60:61], v[68:69], v[112:113]
	v_add_f32_e32 v68, 1.0, v70
	v_add_f32_e32 v69, 1.0, v71
	v_mul_f32_e32 v62, 0xbfb8aa3b, v63
	v_rcp_f32_e32 v68, v68
	v_rcp_f32_e32 v69, v69
	v_lshlrev_b32_e32 v70, 16, v109
	v_and_b32_e32 v71, 0xffff0000, v109
	v_exp_f32_e32 v109, v62
	v_pk_mul_f32 v[70:71], v[134:135], v[70:71] op_sel_hi:[0,1]
	v_pk_mul_f32 v[70:71], v[78:79], v[70:71]
	v_mul_f32_e32 v54, 0xbfb8aa3b, v54
	v_pk_fma_f32 v[62:63], v[68:69], v[70:71], v[114:115]
	v_add_f32_e32 v68, 1.0, v108
	v_add_f32_e32 v69, 1.0, v109
	v_mul_f32_e32 v108, 0xbfb8aa3b, v136
	v_mul_f32_e32 v109, 0xbfb8aa3b, v137
	v_rcp_f32_e32 v68, v68
	v_rcp_f32_e32 v69, v69
	v_exp_f32_e32 v108, v108
	v_exp_f32_e32 v109, v109
	v_lshlrev_b32_e32 v70, 16, v110
	v_and_b32_e32 v71, 0xffff0000, v110
	v_pk_mul_f32 v[70:71], v[134:135], v[70:71] op_sel_hi:[0,1]
	v_pk_mul_f32 v[70:71], v[72:73], v[70:71]
	v_mul_f32_e32 v55, 0xbfb8aa3b, v55
	s_waitcnt vmcnt(9)
	v_pk_fma_f32 v[68:69], v[68:69], v[70:71], v[116:117]
	v_add_f32_e32 v70, 1.0, v108
	v_add_f32_e32 v71, 1.0, v109
	v_rcp_f32_e32 v70, v70
	v_rcp_f32_e32 v71, v71
	v_lshlrev_b32_e32 v108, 16, v111
	v_and_b32_e32 v109, 0xffff0000, v111
	v_pk_mul_f32 v[108:109], v[134:135], v[108:109] op_sel_hi:[0,1]
	v_pk_mul_f32 v[108:109], v[74:75], v[108:109]
	v_exp_f32_e32 v54, v54
	v_pk_fma_f32 v[70:71], v[70:71], v[108:109], v[118:119]
	global_store_dwordx4 v[106:107], v[60:63], off nt
	global_store_dwordx4 v[106:107], v[68:71], off offset:16 nt
	v_exp_f32_e32 v55, v55
	v_pk_mul_f32 v[60:61], v[50:51], v[132:133] op_sel_hi:[1,0]
	v_mul_f32_e32 v50, 0xbfb8aa3b, v52
	v_exp_f32_e32 v52, v50
	v_mul_f32_e32 v50, 0xbfb8aa3b, v53
	v_exp_f32_e32 v53, v50
	v_pk_mul_f32 v[50:51], v[48:49], v[132:133] op_sel_hi:[1,0]
	v_add_f32_e32 v48, 1.0, v52
	v_rcp_f32_e32 v48, v48
	v_add_f32_e32 v49, 1.0, v53
	v_rcp_f32_e32 v49, v49
	s_waitcnt vmcnt(8)
	v_lshlrev_b32_e32 v52, 16, v128
	v_and_b32_e32 v53, 0xffff0000, v128
	v_pk_mul_f32 v[52:53], v[134:135], v[52:53] op_sel_hi:[0,1]
	v_pk_mul_f32 v[52:53], v[64:65], v[52:53]
	v_mul_f32_e32 v50, 0xbfb8aa3b, v50
	v_pk_fma_f32 v[48:49], v[48:49], v[52:53], v[124:125]
	v_add_f32_e32 v52, 1.0, v54
	v_add_f32_e32 v53, 1.0, v55
	v_exp_f32_e32 v62, v50
	v_mul_f32_e32 v50, 0xbfb8aa3b, v51
	v_rcp_f32_e32 v52, v52
	v_rcp_f32_e32 v53, v53
	v_exp_f32_e32 v63, v50
	v_lshlrev_b32_e32 v54, 16, v129
	v_and_b32_e32 v55, 0xffff0000, v129
	v_pk_mul_f32 v[54:55], v[134:135], v[54:55] op_sel_hi:[0,1]
	v_pk_mul_f32 v[54:55], v[66:67], v[54:55]
	v_mul_f32_e32 v60, 0xbfb8aa3b, v60
	v_pk_fma_f32 v[50:51], v[52:53], v[54:55], v[126:127]
	v_add_f32_e32 v52, 1.0, v62
	v_add_f32_e32 v53, 1.0, v63
	v_mul_f32_e32 v61, 0xbfb8aa3b, v61
	v_rcp_f32_e32 v52, v52
	v_rcp_f32_e32 v53, v53
	v_exp_f32_e32 v60, v60
	v_exp_f32_e32 v61, v61
	global_store_dwordx4 v[106:107], v[48:51], off offset:512 nt
	v_lshlrev_b32_e32 v54, 16, v130
	v_and_b32_e32 v55, 0xffff0000, v130
	v_fmamk_f32 v48, v212, 0x3a000000, v206
	v_mul_f32_e32 v49, 0x4b800000, v48
	v_cmp_gt_f32_e32 vcc, s51, v48
	v_pk_mul_f32 v[54:55], v[134:135], v[54:55] op_sel_hi:[0,1]
	v_pk_mul_f32 v[54:55], v[56:57], v[54:55]
	v_cndmask_b32_e32 v48, v48, v49, vcc
	v_fmamk_f32 v49, v211, 0x3a000000, v206
	v_rsq_f32_e32 v48, v48
	v_mul_f32_e32 v50, 0x4b800000, v49
	v_cmp_gt_f32_e64 s[2:3], s51, v49
	v_pk_fma_f32 v[52:53], v[52:53], v[54:55], v[120:121]
	v_add_f32_e32 v54, 1.0, v60
	v_add_f32_e32 v55, 1.0, v61
	v_cndmask_b32_e64 v49, v49, v50, s[2:3]
	v_rcp_f32_e32 v54, v54
	v_rcp_f32_e32 v55, v55
	v_rsq_f32_e32 v49, v49
	v_lshlrev_b32_e32 v60, 16, v131
	v_and_b32_e32 v61, 0xffff0000, v131
	v_pk_mul_f32 v[60:61], v[134:135], v[60:61] op_sel_hi:[0,1]
	v_mul_f32_e32 v50, 0x45800000, v48
	v_pk_mul_f32 v[60:61], v[58:59], v[60:61]
	v_cndmask_b32_e32 v48, v48, v50, vcc
	v_pk_fma_f32 v[54:55], v[54:55], v[60:61], v[122:123]
	v_pk_mul_f32 v[44:45], v[44:45], v[48:49] op_sel_hi:[1,0]
	global_store_dwordx4 v[106:107], v[52:55], off offset:528 nt
	v_pk_mul_f32 v[46:47], v[46:47], v[48:49] op_sel_hi:[1,0]
	v_mul_f32_e32 v50, 0x45800000, v49
	v_pk_mul_f32 v[52:53], v[42:43], v[48:49] op_sel_hi:[1,0]
	v_mul_f32_e32 v42, 0xbfb8aa3b, v44
	v_exp_f32_e32 v44, v42
	v_mul_f32_e32 v42, 0xbfb8aa3b, v45
	v_exp_f32_e32 v45, v42
	v_pk_mul_f32 v[42:43], v[40:41], v[48:49] op_sel_hi:[1,0]
	v_add_f32_e32 v40, 1.0, v44
	v_mul_f32_e32 v46, 0xbfb8aa3b, v46
	v_add_f32_e32 v41, 1.0, v45
	v_mul_f32_e32 v47, 0xbfb8aa3b, v47
	v_rcp_f32_e32 v40, v40
	v_rcp_f32_e32 v41, v41
	v_exp_f32_e32 v46, v46
	v_exp_f32_e32 v47, v47
	v_cndmask_b32_e64 v50, v49, v50, s[2:3]
	s_waitcnt vmcnt(5)
; __device__ __forceinline__ float bflo(unsigned w) { return __uint_as_float(w << 16); }
; __device__ __forceinline__ float bfhi(unsigned w) { return __uint_as_float(w & 0xffff0000u); }
; __device__ __forceinline__ float sigm(float x) { return __builtin_amdgcn_rcpf(1.f + __builtin_amdgcn_exp2f(-x * LOG2E)); }
;     __device__ __forceinline__ void operator()(const pg8::f32x4 (&acc)[2][2][4][2], const pg8::Unit& u, int wr, int wc, int fr, int fq) const {
;     ...
;                     for (int bj = 0; bj < 2; ++bj) { const size_t off = (size_t)(row0 + ai * 128 + (2 * mp + mm) * 16) * DM + colb + bj * 128;
;                         xv[mm][bj][0] = *(const pg8::f32x4*)(X + off); xv[mm][bj][1] = *(const pg8::f32x4*)(X + off + 4); pl[mm][bj] = *(const u32x4*)(PLE + off); }
; #pragma unroll
;                 for (int mm = 0; mm < 2; ++mm) {
;                     const int m = 2 * mp + mm;
;                     const float rs = rsqrtf(s4[ai][m] * (1.f / DM) + EPS), rp = rsqrtf(sp[ai][m] * (1.f / DM) + EPS);
; #pragma unroll
;                     for (int bj = 0; bj < 2; ++bj) {
;                         const size_t off = (size_t)(row0 + ai * 128 + m * 16) * DM + colb + bj * 128;
;                         const u32x4 pw = pl[mm][bj];
;                         const pg8::f32x4 g0 = gp[bj][0], g1 = gp[bj][1];
;                         pg8::f32x4 x0 = xv[mm][bj][0], x1 = xv[mm][bj][1];
;                         const pg8::f32x4 a0 = acc[ai][bj][m][0] * rs, a1 = acc[ai][bj][m][1] * rs;
;                         x0[0] += sigm(a0[0]) * (bflo(pw[0]) * rp * g0[0]); x0[1] += sigm(a0[1]) * (bfhi(pw[0]) * rp * g0[1]);
;                         x0[2] += sigm(a0[2]) * (bflo(pw[1]) * rp * g0[2]); x0[3] += sigm(a0[3]) * (bfhi(pw[1]) * rp * g0[3]);
;                         x1[0] += sigm(a1[0]) * (bflo(pw[2]) * rp * g1[0]); x1[1] += sigm(a1[1]) * (bfhi(pw[2]) * rp * g1[1]);
;                         x1[2] += sigm(a1[2]) * (bflo(pw[3]) * rp * g1[2]); x1[3] += sigm(a1[3]) * (bfhi(pw[3]) * rp * g1[3]);
;                         *(pg8::f32x4*)(X + off) = x0; *(pg8::f32x4*)(X + off + 4) = x1;
	v_lshlrev_b32_e32 v44, 16, v96
	v_and_b32_e32 v45, 0xffff0000, v96
	v_pk_mul_f32 v[44:45], v[50:51], v[44:45] op_sel_hi:[0,1]
	v_pk_mul_f32 v[44:45], v[76:77], v[44:45]
	v_mul_f32_e32 v42, 0xbfb8aa3b, v42
	v_pk_fma_f32 v[40:41], v[40:41], v[44:45], v[100:101]
	v_add_f32_e32 v44, 1.0, v46
	v_add_f32_e32 v45, 1.0, v47
	v_rcp_f32_e32 v44, v44
	v_rcp_f32_e32 v45, v45
	v_lshlrev_b32_e32 v46, 16, v97
	v_and_b32_e32 v47, 0xffff0000, v97
	v_exp_f32_e32 v49, v42
	v_mul_f32_e32 v42, 0xbfb8aa3b, v43
	v_pk_mul_f32 v[46:47], v[50:51], v[46:47] op_sel_hi:[0,1]
	v_exp_f32_e32 v51, v42
	v_pk_mul_f32 v[46:47], v[78:79], v[46:47]
	s_nop 0
	v_pk_fma_f32 v[42:43], v[44:45], v[46:47], v[102:103]
	v_lshlrev_b32_e32 v46, 16, v98
	v_and_b32_e32 v47, 0xffff0000, v98
	v_add_f32_e32 v44, 1.0, v49
	v_add_f32_e32 v45, 1.0, v51
	v_pk_mul_f32 v[46:47], v[50:51], v[46:47] op_sel_hi:[0,1]
	v_mul_f32_e32 v49, 0xbfb8aa3b, v52
	v_mul_f32_e32 v51, 0xbfb8aa3b, v53
	v_rcp_f32_e32 v44, v44
	v_rcp_f32_e32 v45, v45
	v_exp_f32_e32 v49, v49
	v_exp_f32_e32 v51, v51
	v_pk_mul_f32 v[46:47], v[72:73], v[46:47]
	v_lshlrev_b32_e32 v52, 16, v99
	v_pk_fma_f32 v[44:45], v[44:45], v[46:47], v[92:93]
	v_add_f32_e32 v46, 1.0, v49
	v_add_f32_e32 v47, 1.0, v51
	v_rcp_f32_e32 v46, v46
	v_rcp_f32_e32 v47, v47
	v_and_b32_e32 v53, 0xffff0000, v99
	v_pk_mul_f32 v[52:53], v[50:51], v[52:53] op_sel_hi:[0,1]
	v_pk_mul_f32 v[52:53], v[74:75], v[52:53]
	v_pk_mul_f32 v[36:37], v[36:37], v[48:49] op_sel_hi:[1,0]
	v_pk_fma_f32 v[46:47], v[46:47], v[52:53], v[94:95]
	global_store_dwordx4 v[104:105], v[40:43], off nt
	global_store_dwordx4 v[104:105], v[44:47], off offset:16 nt
	v_pk_mul_f32 v[38:39], v[38:39], v[48:49] op_sel_hi:[1,0]
	v_pk_mul_f32 v[40:41], v[34:35], v[48:49] op_sel_hi:[1,0]
	v_mul_f32_e32 v34, 0xbfb8aa3b, v36
	v_exp_f32_e32 v36, v34
	v_mul_f32_e32 v34, 0xbfb8aa3b, v37
	v_exp_f32_e32 v37, v34
	v_pk_mul_f32 v[34:35], v[32:33], v[48:49] op_sel_hi:[1,0]
	v_add_f32_e32 v32, 1.0, v36
	v_mul_f32_e32 v38, 0xbfb8aa3b, v38
	v_add_f32_e32 v33, 1.0, v37
	v_mul_f32_e32 v39, 0xbfb8aa3b, v39
	v_rcp_f32_e32 v32, v32
	v_rcp_f32_e32 v33, v33
	v_exp_f32_e32 v38, v38
	v_exp_f32_e32 v39, v39
	s_waitcnt vmcnt(6)
	v_lshlrev_b32_e32 v36, 16, v84
	v_and_b32_e32 v37, 0xffff0000, v84
	v_pk_mul_f32 v[36:37], v[50:51], v[36:37] op_sel_hi:[0,1]
	v_pk_mul_f32 v[36:37], v[64:65], v[36:37]
	v_mul_f32_e32 v34, 0xbfb8aa3b, v34
	v_pk_fma_f32 v[32:33], v[32:33], v[36:37], v[88:89]
	v_add_f32_e32 v36, 1.0, v38
	v_add_f32_e32 v37, 1.0, v39
	v_exp_f32_e32 v42, v34
	v_mul_f32_e32 v34, 0xbfb8aa3b, v35
	v_rcp_f32_e32 v36, v36
	v_rcp_f32_e32 v37, v37
	v_exp_f32_e32 v43, v34
	v_lshlrev_b32_e32 v38, 16, v85
	v_and_b32_e32 v39, 0xffff0000, v85
	v_pk_mul_f32 v[38:39], v[50:51], v[38:39] op_sel_hi:[0,1]
	v_pk_mul_f32 v[38:39], v[66:67], v[38:39]
	v_mul_f32_e32 v40, 0xbfb8aa3b, v40
	v_pk_fma_f32 v[34:35], v[36:37], v[38:39], v[90:91]
	v_add_f32_e32 v36, 1.0, v42
	v_add_f32_e32 v37, 1.0, v43
	v_mul_f32_e32 v41, 0xbfb8aa3b, v41
	v_rcp_f32_e32 v36, v36
	v_rcp_f32_e32 v37, v37
	v_exp_f32_e32 v40, v40
	v_exp_f32_e32 v41, v41
	v_lshlrev_b32_e32 v38, 16, v86
	v_and_b32_e32 v39, 0xffff0000, v86
	v_pk_mul_f32 v[38:39], v[50:51], v[38:39] op_sel_hi:[0,1]
	v_pk_mul_f32 v[38:39], v[56:57], v[38:39]
	v_fmamk_f32 v48, v210, 0x3a000000, v206
	v_pk_fma_f32 v[36:37], v[36:37], v[38:39], v[80:81]
	v_add_f32_e32 v38, 1.0, v40
	v_add_f32_e32 v39, 1.0, v41
	v_rcp_f32_e32 v38, v38
	v_rcp_f32_e32 v39, v39
	v_lshlrev_b32_e32 v40, 16, v87
	v_and_b32_e32 v41, 0xffff0000, v87
	v_pk_mul_f32 v[40:41], v[50:51], v[40:41] op_sel_hi:[0,1]
	v_pk_mul_f32 v[40:41], v[58:59], v[40:41]
	v_mul_f32_e32 v49, 0x4b800000, v48
	v_pk_fma_f32 v[38:39], v[38:39], v[40:41], v[82:83]
	global_store_dwordx4 v[104:105], v[32:35], off offset:512 nt
	global_store_dwordx4 v[104:105], v[36:39], off offset:528 nt
	v_cmp_gt_f32_e32 vcc, s51, v48
	v_lshl_add_u64 v[32:33], v[188:189], 0, s[20:21]
	v_lshlrev_b64 v[34:35], 1, v[32:33]
	v_lshl_add_u64 v[36:37], s[6:7], 0, v[34:35]
	global_load_dwordx4 v[68:71], v[36:37], off nt
	v_lshl_add_u64 v[62:63], v[32:33], 2, s[62:63]
	global_load_dwordx4 v[80:83], v[62:63], off nt
	global_load_dwordx4 v[84:87], v[62:63], off offset:16 nt
	global_load_dwordx4 v[88:91], v[62:63], off offset:528 nt
	global_load_dwordx4 v[92:95], v[62:63], off offset:512 nt
	v_or_b32_e32 v34, 0x100, v34
	v_lshl_add_u64 v[32:33], s[6:7], 0, v[34:35]
	global_load_dwordx4 v[96:99], v[32:33], off nt
	v_lshl_add_u64 v[32:33], v[188:189], 0, s[22:23]
	v_cndmask_b32_e32 v48, v48, v49, vcc
	v_lshlrev_b64 v[36:37], 1, v[32:33]
	v_rsq_f32_e32 v100, v48
	v_fmamk_f32 v48, v209, 0x3a000000, v206
	v_lshl_add_u64 v[38:39], s[6:7], 0, v[36:37]
	v_or_b32_e32 v36, 0x100, v36
	v_mul_f32_e32 v49, 0x4b800000, v48
	v_cmp_gt_f32_e64 s[2:3], s51, v48
	v_lshl_add_u64 v[60:61], v[32:33], 2, s[62:63]
	v_lshl_add_u64 v[36:37], s[6:7], 0, v[36:37]
	v_cndmask_b32_e64 v48, v48, v49, s[2:3]
	global_load_dwordx4 v[44:47], v[60:61], off offset:16 nt
	global_load_dwordx4 v[52:55], v[60:61], off nt
	global_load_dwordx4 v[32:35], v[60:61], off offset:528 nt
	global_load_dwordx4 v[40:43], v[60:61], off offset:512 nt
	v_rsq_f32_e32 v101, v48
	global_load_dwordx4 v[48:51], v[38:39], off nt
	s_nop 0
	global_load_dwordx4 v[36:39], v[36:37], off nt
	v_mul_f32_e32 v102, 0x45800000, v100
	v_cndmask_b32_e32 v100, v100, v102, vcc
	v_pk_mul_f32 v[28:29], v[28:29], v[100:101] op_sel_hi:[1,0]
	v_pk_mul_f32 v[104:105], v[26:27], v[100:101] op_sel_hi:[1,0]
	v_mul_f32_e32 v26, 0xbfb8aa3b, v28
	v_exp_f32_e32 v28, v26
	v_mul_f32_e32 v26, 0xbfb8aa3b, v29
	v_exp_f32_e32 v29, v26
	v_pk_mul_f32 v[30:31], v[30:31], v[100:101] op_sel_hi:[1,0]
	v_pk_mul_f32 v[26:27], v[24:25], v[100:101] op_sel_hi:[1,0]
	v_add_f32_e32 v24, 1.0, v28
	v_add_f32_e32 v25, 1.0, v29
	v_mul_f32_e32 v30, 0xbfb8aa3b, v30
	v_mul_f32_e32 v31, 0xbfb8aa3b, v31
	v_mul_f32_e32 v102, 0x45800000, v101
	v_rcp_f32_e32 v24, v24
	v_rcp_f32_e32 v25, v25
	v_exp_f32_e32 v30, v30
	v_exp_f32_e32 v31, v31
	v_cndmask_b32_e64 v102, v101, v102, s[2:3]
	v_mul_f32_e32 v26, 0xbfb8aa3b, v26
	v_pk_mul_f32 v[20:21], v[20:21], v[100:101] op_sel_hi:[1,0]
	v_pk_mul_f32 v[22:23], v[22:23], v[100:101] op_sel_hi:[1,0]
	s_waitcnt vmcnt(11)
; __device__ __forceinline__ float bflo(unsigned w) { return __uint_as_float(w << 16); }
; __device__ __forceinline__ float bfhi(unsigned w) { return __uint_as_float(w & 0xffff0000u); }
; __device__ __forceinline__ float sigm(float x) { return __builtin_amdgcn_rcpf(1.f + __builtin_amdgcn_exp2f(-x * LOG2E)); }
;     __device__ __forceinline__ void operator()(const pg8::f32x4 (&acc)[2][2][4][2], const pg8::Unit& u, int wr, int wc, int fr, int fq) const {
;     ...
;                     const float rs = rsqrtf(s4[ai][m] * (1.f / DM) + EPS), rp = rsqrtf(sp[ai][m] * (1.f / DM) + EPS);
; #pragma unroll
;                     for (int bj = 0; bj < 2; ++bj) {
;                         const size_t off = (size_t)(row0 + ai * 128 + m * 16) * DM + colb + bj * 128;
;                         const u32x4 pw = pl[mm][bj];
;                         const pg8::f32x4 g0 = gp[bj][0], g1 = gp[bj][1];
;                         pg8::f32x4 x0 = xv[mm][bj][0], x1 = xv[mm][bj][1];
;                         const pg8::f32x4 a0 = acc[ai][bj][m][0] * rs, a1 = acc[ai][bj][m][1] * rs;
;                         x0[0] += sigm(a0[0]) * (bflo(pw[0]) * rp * g0[0]); x0[1] += sigm(a0[1]) * (bfhi(pw[0]) * rp * g0[1]);
;                         x0[2] += sigm(a0[2]) * (bflo(pw[1]) * rp * g0[2]); x0[3] += sigm(a0[3]) * (bfhi(pw[1]) * rp * g0[3]);
;                         x1[0] += sigm(a1[0]) * (bflo(pw[2]) * rp * g1[0]); x1[1] += sigm(a1[1]) * (bfhi(pw[2]) * rp * g1[1]);
;                         x1[2] += sigm(a1[2]) * (bflo(pw[3]) * rp * g1[2]); x1[3] += sigm(a1[3]) * (bfhi(pw[3]) * rp * g1[3]);
;                         *(pg8::f32x4*)(X + off) = x0; *(pg8::f32x4*)(X + off + 4) = x1;
	v_lshlrev_b32_e32 v28, 16, v68
	v_and_b32_e32 v29, 0xffff0000, v68
	v_pk_mul_f32 v[28:29], v[102:103], v[28:29] op_sel_hi:[0,1]
	v_pk_mul_f32 v[28:29], v[76:77], v[28:29]
	v_exp_f32_e32 v68, v26
	s_waitcnt vmcnt(10)
	v_pk_fma_f32 v[24:25], v[24:25], v[28:29], v[80:81]
	v_add_f32_e32 v28, 1.0, v30
	v_add_f32_e32 v29, 1.0, v31
	v_mul_f32_e32 v26, 0xbfb8aa3b, v27
	v_rcp_f32_e32 v28, v28
	v_rcp_f32_e32 v29, v29
	v_lshlrev_b32_e32 v30, 16, v69
	v_and_b32_e32 v31, 0xffff0000, v69
	v_exp_f32_e32 v69, v26
	v_pk_mul_f32 v[30:31], v[102:103], v[30:31] op_sel_hi:[0,1]
	v_pk_mul_f32 v[30:31], v[78:79], v[30:31]
	v_mul_f32_e32 v22, 0xbfb8aa3b, v22
	v_pk_fma_f32 v[26:27], v[28:29], v[30:31], v[82:83]
	v_add_f32_e32 v28, 1.0, v68
	v_add_f32_e32 v29, 1.0, v69
	v_mul_f32_e32 v68, 0xbfb8aa3b, v104
	v_mul_f32_e32 v69, 0xbfb8aa3b, v105
	v_rcp_f32_e32 v28, v28
	v_rcp_f32_e32 v29, v29
	v_exp_f32_e32 v68, v68
	v_exp_f32_e32 v69, v69
	v_lshlrev_b32_e32 v30, 16, v70
	v_and_b32_e32 v31, 0xffff0000, v70
	v_pk_mul_f32 v[30:31], v[102:103], v[30:31] op_sel_hi:[0,1]
	v_pk_mul_f32 v[30:31], v[72:73], v[30:31]
	v_mul_f32_e32 v23, 0xbfb8aa3b, v23
	s_waitcnt vmcnt(9)
	v_pk_fma_f32 v[28:29], v[28:29], v[30:31], v[84:85]
	v_add_f32_e32 v30, 1.0, v68
	v_add_f32_e32 v31, 1.0, v69
	v_rcp_f32_e32 v30, v30
	v_rcp_f32_e32 v31, v31
	v_lshlrev_b32_e32 v68, 16, v71
	v_and_b32_e32 v69, 0xffff0000, v71
	v_pk_mul_f32 v[68:69], v[102:103], v[68:69] op_sel_hi:[0,1]
	v_pk_mul_f32 v[68:69], v[74:75], v[68:69]
	v_exp_f32_e32 v22, v22
	v_pk_fma_f32 v[30:31], v[30:31], v[68:69], v[86:87]
	global_store_dwordx4 v[62:63], v[24:27], off nt
	global_store_dwordx4 v[62:63], v[28:31], off offset:16 nt
	v_exp_f32_e32 v23, v23
	v_pk_mul_f32 v[24:25], v[18:19], v[100:101] op_sel_hi:[1,0]
	v_mul_f32_e32 v18, 0xbfb8aa3b, v20
	v_exp_f32_e32 v20, v18
	v_mul_f32_e32 v18, 0xbfb8aa3b, v21
	v_exp_f32_e32 v21, v18
	v_pk_mul_f32 v[18:19], v[16:17], v[100:101] op_sel_hi:[1,0]
	v_add_f32_e32 v16, 1.0, v20
	v_rcp_f32_e32 v16, v16
	v_add_f32_e32 v17, 1.0, v21
	v_rcp_f32_e32 v17, v17
	s_waitcnt vmcnt(8)
	v_lshlrev_b32_e32 v20, 16, v96
	v_and_b32_e32 v21, 0xffff0000, v96
	v_pk_mul_f32 v[20:21], v[102:103], v[20:21] op_sel_hi:[0,1]
	v_pk_mul_f32 v[20:21], v[64:65], v[20:21]
	v_mul_f32_e32 v18, 0xbfb8aa3b, v18
	v_pk_fma_f32 v[16:17], v[16:17], v[20:21], v[92:93]
	v_add_f32_e32 v20, 1.0, v22
	v_add_f32_e32 v21, 1.0, v23
	v_exp_f32_e32 v26, v18
	v_mul_f32_e32 v18, 0xbfb8aa3b, v19
	v_rcp_f32_e32 v20, v20
	v_rcp_f32_e32 v21, v21
	v_exp_f32_e32 v27, v18
	v_lshlrev_b32_e32 v22, 16, v97
	v_and_b32_e32 v23, 0xffff0000, v97
	v_pk_mul_f32 v[22:23], v[102:103], v[22:23] op_sel_hi:[0,1]
	v_pk_mul_f32 v[22:23], v[66:67], v[22:23]
	v_mul_f32_e32 v24, 0xbfb8aa3b, v24
	v_pk_fma_f32 v[18:19], v[20:21], v[22:23], v[94:95]
	v_add_f32_e32 v20, 1.0, v26
	v_add_f32_e32 v21, 1.0, v27
	v_mul_f32_e32 v25, 0xbfb8aa3b, v25
	v_rcp_f32_e32 v20, v20
	v_rcp_f32_e32 v21, v21
	v_exp_f32_e32 v24, v24
	v_exp_f32_e32 v25, v25
	global_store_dwordx4 v[62:63], v[16:19], off offset:512 nt
	v_lshlrev_b32_e32 v22, 16, v98
	v_and_b32_e32 v23, 0xffff0000, v98
	v_fmamk_f32 v16, v207, 0x3a000000, v206
	v_mul_f32_e32 v17, 0x4b800000, v16
	v_cmp_gt_f32_e32 vcc, s51, v16
	v_pk_mul_f32 v[22:23], v[102:103], v[22:23] op_sel_hi:[0,1]
	v_pk_mul_f32 v[22:23], v[56:57], v[22:23]
	v_cndmask_b32_e32 v16, v16, v17, vcc
	v_fmamk_f32 v17, v208, 0x3a000000, v206
	v_rsq_f32_e32 v16, v16
	v_mul_f32_e32 v18, 0x4b800000, v17
	v_cmp_gt_f32_e64 s[2:3], s51, v17
	v_pk_fma_f32 v[20:21], v[20:21], v[22:23], v[88:89]
	v_add_f32_e32 v22, 1.0, v24
	v_add_f32_e32 v23, 1.0, v25
	v_cndmask_b32_e64 v17, v17, v18, s[2:3]
	v_rcp_f32_e32 v22, v22
	v_rcp_f32_e32 v23, v23
	v_rsq_f32_e32 v17, v17
	v_lshlrev_b32_e32 v24, 16, v99
	v_and_b32_e32 v25, 0xffff0000, v99
	v_pk_mul_f32 v[24:25], v[102:103], v[24:25] op_sel_hi:[0,1]
	v_mul_f32_e32 v18, 0x45800000, v16
	v_pk_mul_f32 v[24:25], v[58:59], v[24:25]
	v_cndmask_b32_e32 v16, v16, v18, vcc
	v_pk_fma_f32 v[22:23], v[22:23], v[24:25], v[90:91]
	v_pk_mul_f32 v[12:13], v[12:13], v[16:17] op_sel_hi:[1,0]
	global_store_dwordx4 v[62:63], v[20:23], off offset:528 nt
	v_pk_mul_f32 v[14:15], v[14:15], v[16:17] op_sel_hi:[1,0]
	v_mul_f32_e32 v18, 0x45800000, v17
	v_pk_mul_f32 v[20:21], v[10:11], v[16:17] op_sel_hi:[1,0]
	v_mul_f32_e32 v10, 0xbfb8aa3b, v12
	v_exp_f32_e32 v12, v10
	v_mul_f32_e32 v10, 0xbfb8aa3b, v13
	v_exp_f32_e32 v13, v10
	v_pk_mul_f32 v[10:11], v[8:9], v[16:17] op_sel_hi:[1,0]
	v_add_f32_e32 v8, 1.0, v12
	v_mul_f32_e32 v14, 0xbfb8aa3b, v14
	v_add_f32_e32 v9, 1.0, v13
	v_mul_f32_e32 v15, 0xbfb8aa3b, v15
	v_rcp_f32_e32 v8, v8
	v_rcp_f32_e32 v9, v9
	v_exp_f32_e32 v14, v14
	v_exp_f32_e32 v15, v15
	v_cndmask_b32_e64 v18, v17, v18, s[2:3]
	s_waitcnt vmcnt(5)
; __device__ __forceinline__ float bflo(unsigned w) { return __uint_as_float(w << 16); }
; __device__ __forceinline__ float bfhi(unsigned w) { return __uint_as_float(w & 0xffff0000u); }
; __device__ __forceinline__ float sigm(float x) { return __builtin_amdgcn_rcpf(1.f + __builtin_amdgcn_exp2f(-x * LOG2E)); }
;     __device__ __forceinline__ void operator()(const pg8::f32x4 (&acc)[2][2][4][2], const pg8::Unit& u, int wr, int wc, int fr, int fq) const {
;     ...
;                     const float rs = rsqrtf(s4[ai][m] * (1.f / DM) + EPS), rp = rsqrtf(sp[ai][m] * (1.f / DM) + EPS);
; #pragma unroll
;                     for (int bj = 0; bj < 2; ++bj) {
;                         const size_t off = (size_t)(row0 + ai * 128 + m * 16) * DM + colb + bj * 128;
;                         const u32x4 pw = pl[mm][bj];
;                         const pg8::f32x4 g0 = gp[bj][0], g1 = gp[bj][1];
;                         pg8::f32x4 x0 = xv[mm][bj][0], x1 = xv[mm][bj][1];
;                         const pg8::f32x4 a0 = acc[ai][bj][m][0] * rs, a1 = acc[ai][bj][m][1] * rs;
;                         x0[0] += sigm(a0[0]) * (bflo(pw[0]) * rp * g0[0]); x0[1] += sigm(a0[1]) * (bfhi(pw[0]) * rp * g0[1]);
;                         x0[2] += sigm(a0[2]) * (bflo(pw[1]) * rp * g0[2]); x0[3] += sigm(a0[3]) * (bfhi(pw[1]) * rp * g0[3]);
;                         x1[0] += sigm(a1[0]) * (bflo(pw[2]) * rp * g1[0]); x1[1] += sigm(a1[1]) * (bfhi(pw[2]) * rp * g1[1]);
;                         x1[2] += sigm(a1[2]) * (bflo(pw[3]) * rp * g1[2]); x1[3] += sigm(a1[3]) * (bfhi(pw[3]) * rp * g1[3]);
;                         *(pg8::f32x4*)(X + off) = x0; *(pg8::f32x4*)(X + off + 4) = x1;
;                     }
	v_lshlrev_b32_e32 v12, 16, v48
	v_and_b32_e32 v13, 0xffff0000, v48
	v_pk_mul_f32 v[12:13], v[18:19], v[12:13] op_sel_hi:[0,1]
	v_pk_mul_f32 v[12:13], v[76:77], v[12:13]
	v_mul_f32_e32 v10, 0xbfb8aa3b, v10
	v_pk_fma_f32 v[8:9], v[8:9], v[12:13], v[52:53]
	v_add_f32_e32 v12, 1.0, v14
	v_add_f32_e32 v13, 1.0, v15
	v_rcp_f32_e32 v12, v12
	v_rcp_f32_e32 v13, v13
	v_lshlrev_b32_e32 v14, 16, v49
	v_and_b32_e32 v15, 0xffff0000, v49
	v_exp_f32_e32 v17, v10
	v_mul_f32_e32 v10, 0xbfb8aa3b, v11
	v_pk_mul_f32 v[14:15], v[18:19], v[14:15] op_sel_hi:[0,1]
	v_exp_f32_e32 v19, v10
	v_pk_mul_f32 v[14:15], v[78:79], v[14:15]
	s_andn2_b64 vcc, exec, s[0:1]
	v_pk_fma_f32 v[10:11], v[12:13], v[14:15], v[54:55]
	v_lshlrev_b32_e32 v14, 16, v50
	v_and_b32_e32 v15, 0xffff0000, v50
	v_add_f32_e32 v12, 1.0, v17
	v_add_f32_e32 v13, 1.0, v19
	v_pk_mul_f32 v[14:15], v[18:19], v[14:15] op_sel_hi:[0,1]
	v_mul_f32_e32 v17, 0xbfb8aa3b, v20
	v_mul_f32_e32 v19, 0xbfb8aa3b, v21
	v_rcp_f32_e32 v12, v12
	v_rcp_f32_e32 v13, v13
	v_exp_f32_e32 v17, v17
	v_exp_f32_e32 v19, v19
	v_pk_mul_f32 v[14:15], v[72:73], v[14:15]
	v_lshlrev_b32_e32 v20, 16, v51
	v_pk_fma_f32 v[12:13], v[12:13], v[14:15], v[44:45]
	v_add_f32_e32 v14, 1.0, v17
	v_add_f32_e32 v15, 1.0, v19
	v_rcp_f32_e32 v14, v14
	v_rcp_f32_e32 v15, v15
	v_and_b32_e32 v21, 0xffff0000, v51
	v_pk_mul_f32 v[20:21], v[18:19], v[20:21] op_sel_hi:[0,1]
	v_pk_mul_f32 v[20:21], v[74:75], v[20:21]
	v_pk_mul_f32 v[4:5], v[4:5], v[16:17] op_sel_hi:[1,0]
	v_pk_fma_f32 v[14:15], v[14:15], v[20:21], v[46:47]
	global_store_dwordx4 v[60:61], v[8:11], off nt
	global_store_dwordx4 v[60:61], v[12:15], off offset:16 nt
	v_pk_mul_f32 v[6:7], v[6:7], v[16:17] op_sel_hi:[1,0]
	v_pk_mul_f32 v[8:9], v[2:3], v[16:17] op_sel_hi:[1,0]
	v_mul_f32_e32 v2, 0xbfb8aa3b, v4
	v_exp_f32_e32 v4, v2
	v_mul_f32_e32 v2, 0xbfb8aa3b, v5
	v_exp_f32_e32 v5, v2
	v_pk_mul_f32 v[2:3], v[0:1], v[16:17] op_sel_hi:[1,0]
	v_add_f32_e32 v0, 1.0, v4
	v_mul_f32_e32 v6, 0xbfb8aa3b, v6
	v_add_f32_e32 v1, 1.0, v5
	v_mul_f32_e32 v7, 0xbfb8aa3b, v7
	v_rcp_f32_e32 v0, v0
	v_rcp_f32_e32 v1, v1
	v_exp_f32_e32 v6, v6
	v_exp_f32_e32 v7, v7
	s_waitcnt vmcnt(6)
	v_lshlrev_b32_e32 v4, 16, v36
	v_and_b32_e32 v5, 0xffff0000, v36
	v_pk_mul_f32 v[4:5], v[18:19], v[4:5] op_sel_hi:[0,1]
	v_pk_mul_f32 v[4:5], v[64:65], v[4:5]
	v_mul_f32_e32 v2, 0xbfb8aa3b, v2
	v_pk_fma_f32 v[0:1], v[0:1], v[4:5], v[40:41]
	v_add_f32_e32 v4, 1.0, v6
	v_add_f32_e32 v5, 1.0, v7
	v_exp_f32_e32 v10, v2
	v_mul_f32_e32 v2, 0xbfb8aa3b, v3
	v_rcp_f32_e32 v4, v4
	v_rcp_f32_e32 v5, v5
	v_exp_f32_e32 v11, v2
	v_lshlrev_b32_e32 v6, 16, v37
	v_and_b32_e32 v7, 0xffff0000, v37
	v_pk_mul_f32 v[6:7], v[18:19], v[6:7] op_sel_hi:[0,1]
	v_pk_mul_f32 v[6:7], v[66:67], v[6:7]
	v_mul_f32_e32 v8, 0xbfb8aa3b, v8
	v_pk_fma_f32 v[2:3], v[4:5], v[6:7], v[42:43]
	v_add_f32_e32 v4, 1.0, v10
	v_add_f32_e32 v5, 1.0, v11
	v_mul_f32_e32 v9, 0xbfb8aa3b, v9
	v_rcp_f32_e32 v4, v4
	v_rcp_f32_e32 v5, v5
	v_exp_f32_e32 v8, v8
	v_exp_f32_e32 v9, v9
	v_lshlrev_b32_e32 v6, 16, v38
	v_and_b32_e32 v7, 0xffff0000, v38
	v_pk_mul_f32 v[6:7], v[18:19], v[6:7] op_sel_hi:[0,1]
	v_pk_mul_f32 v[6:7], v[56:57], v[6:7]
	s_mov_b64 s[0:1], -1
	v_pk_fma_f32 v[4:5], v[4:5], v[6:7], v[32:33]
	v_add_f32_e32 v6, 1.0, v8
	v_add_f32_e32 v7, 1.0, v9
	v_rcp_f32_e32 v6, v6
	v_rcp_f32_e32 v7, v7
	v_lshlrev_b32_e32 v8, 16, v39
	v_and_b32_e32 v9, 0xffff0000, v39
	v_pk_mul_f32 v[8:9], v[18:19], v[8:9] op_sel_hi:[0,1]
	v_pk_mul_f32 v[8:9], v[58:59], v[8:9]
	s_nop 0
	v_pk_fma_f32 v[6:7], v[6:7], v[8:9], v[34:35]
	global_store_dwordx4 v[60:61], v[0:3], off offset:512 nt
	global_store_dwordx4 v[60:61], v[4:7], off offset:528 nt
	s_cbranch_vccnz .LBB0_1287
	s_andn2_b64 vcc, exec, s[4:5]
	s_cbranch_vccnz .LBB0_1286
	s_barrier
	s_branch .LBB0_1286
